# v14: v10 + xor16/xor32 ds_bpermute butterflies in EpiRes/EpiSoftmaxP/diff pass-2 epilogues replaced by v_permlane16/32_swap
# speedup vs baseline: 1.0018x; 1.0018x over previous
.LBB0_29:
	v_readlane_b32 s4, v255, 32
	s_cmp_gt_i32 s4, 9
	s_mov_b64 s[28:29], -1
	v_readlane_b32 s5, v255, 33
	s_cbranch_scc0 .LBB0_96
	s_cmp_gt_i32 s4, 10
	s_mov_b64 s[10:11], -1
	s_cbranch_scc0 .LBB0_95
	v_readlane_b32 s4, v255, 34
	v_readlane_b32 s5, v255, 35
	s_load_dwordx8 s[44:51], s[4:5], 0x90
	v_lshlrev_b32_e32 v0, 2, v226
	v_cmp_lt_i32_e32 vcc, v250, v213
	v_readlane_b32 s4, v251, 5
	v_readlane_b32 s5, v251, 6
	s_waitcnt lgkmcnt(0)
	global_load_dword v2, v0, s[44:45]
	global_load_dword v3, v0, s[46:47]
	global_load_dword v4, v0, s[48:49]
	s_nop 0
	global_load_dword v0, v0, s[50:51]
	v_cndmask_b32_e32 v5, v211, v250, vcc
	v_lshlrev_b32_e32 v166, 2, v5
	v_cmp_lt_i32_e32 vcc, v221, v213
	s_waitcnt vmcnt(0)
	v_mul_f32_e32 v5, v2, v3
	ds_bpermute_b32 v5, v166, v5
	s_waitcnt vmcnt(0)
	v_mul_f32_e32 v6, v4, v0
	ds_bpermute_b32 v6, v166, v6
	v_cndmask_b32_e32 v7, v211, v221, vcc
	v_lshlrev_b32_e32 v167, 2, v7
	s_waitcnt lgkmcnt(1)
	v_fmac_f32_e32 v5, v2, v3
	v_cmp_lt_i32_e32 vcc, v212, v213
	s_waitcnt lgkmcnt(0)
	v_fmac_f32_e32 v6, v4, v0
	ds_bpermute_b32 v0, v167, v5
	ds_bpermute_b32 v2, v167, v6
	v_cndmask_b32_e32 v3, v211, v212, vcc
	v_lshlrev_b32_e32 v168, 2, v3
	v_cmp_lt_i32_e32 vcc, v210, v213
	s_waitcnt lgkmcnt(1)
	v_add_f32_e32 v0, v5, v0
	s_waitcnt lgkmcnt(0)
	v_add_f32_e32 v2, v6, v2
	ds_bpermute_b32 v3, v168, v0
	ds_bpermute_b32 v4, v168, v2
	v_cndmask_b32_e32 v5, v211, v210, vcc
	v_lshlrev_b32_e32 v169, 2, v5
	v_cmp_lt_i32_e32 vcc, v218, v213
	s_waitcnt lgkmcnt(1)
	v_add_f32_e32 v0, v0, v3
	s_waitcnt lgkmcnt(0)
	v_add_f32_e32 v2, v2, v4
	ds_bpermute_b32 v3, v169, v0
	ds_bpermute_b32 v4, v169, v2
	v_cndmask_b32_e32 v5, v211, v218, vcc
	v_lshlrev_b32_e32 v170, 2, v5
	v_cmp_lt_i32_e32 vcc, v219, v213
	s_waitcnt lgkmcnt(1)
	v_add_f32_e32 v0, v0, v3
	s_waitcnt lgkmcnt(0)
	v_add_f32_e32 v2, v2, v4
	v_mov_b32_e32 v3, v0
	s_nop 1
	v_permlane16_swap_b32_e32 v0, v3
	v_mov_b32_e32 v4, v2
	s_nop 1
	v_permlane16_swap_b32_e32 v2, v4
	v_cndmask_b32_e32 v5, v211, v219, vcc
	v_lshlrev_b32_e32 v171, 2, v5
	s_andn2_b64 vcc, exec, s[4:5]
	s_waitcnt lgkmcnt(0)
	v_add_f32_e32 v0, v0, v3
	s_waitcnt lgkmcnt(0)
	v_add_f32_e32 v2, v2, v4
	ds_bpermute_b32 v3, v171, v0
	ds_bpermute_b32 v4, v171, v2
	s_waitcnt lgkmcnt(1)
	v_add_f32_e32 v0, v0, v3
	s_waitcnt lgkmcnt(0)
	v_add_f32_e32 v2, v2, v4
	v_mul_f32_e32 v0, 0x3fb8aa3b, v0
	v_mul_f32_e32 v2, 0x3fb8aa3b, v2
	v_exp_f32_e32 v0, v0
	v_exp_f32_e32 v2, v2
	s_nop 0
	v_sub_f32_e32 v0, v0, v2
	s_nop 0
	v_readfirstlane_b32 s1, v0
	s_cbranch_vccnz .LBB0_94
	v_readlane_b32 s4, v255, 34
	v_readlane_b32 s5, v255, 35
	s_load_dwordx2 s[4:5], s[4:5], 0xf0
	v_mov_b32_e32 v0, 0x3eb60549
	v_add_f32_e32 v142, s1, v0
	v_mov_b32_e32 v143, v142
	v_readlane_b32 s67, v253, 62
	s_waitcnt lgkmcnt(0)
	s_add_u32 s9, s4, 0x6000000
	s_addc_u32 s40, s5, 0
	s_add_u32 s41, s4, 0xc000000
	s_addc_u32 s66, s5, 0
	s_add_u32 s16, s4, 0x6061000
	s_addc_u32 s17, s5, 0
	s_add_u32 s44, s4, 0x6060800
	s_addc_u32 s45, s5, 0
	s_add_u32 s46, s4, 0x6060880
	s_addc_u32 s47, s5, 0
	v_readlane_b32 s68, v253, 60
	v_readlane_b32 s69, v251, 2
	s_branch .LBB0_34
.LBB0_33:
	v_rcp_f32_e32 v98, v67
	v_lshlrev_b32_e32 v67, 2, v145
	v_rcp_f32_e32 v94, v69
	v_rcp_f32_e32 v90, v71
	v_rcp_f32_e32 v86, v73
	global_load_dword v69, v67, s[50:51]
	global_load_dword v71, v67, s[50:51] offset:128
	global_load_dword v73, v67, s[50:51] offset:256
	v_readlane_b32 s4, v251, 48
	global_load_dword v67, v67, s[50:51] offset:384
	v_rcp_f32_e32 v88, v72
	v_rcp_f32_e32 v72, v77
	v_rcp_f32_e32 v96, v68
	v_rcp_f32_e32 v68, v79
	v_rcp_f32_e32 v84, v74
	v_rcp_f32_e32 v82, v75
	v_rcp_f32_e32 v100, v66
	v_mov_b32_e32 v106, v34
	v_mov_b32_e32 v107, v18
	s_mov_b32 s10, 0x800000
	v_rcp_f32_e32 v66, v80
	v_ashrrev_i32_e32 v80, 3, v172
	v_rcp_f32_e32 v92, v70
	v_rcp_f32_e32 v70, v78
	v_rcp_f32_e32 v0, v81
	v_and_b32_e32 v81, 0xffffffc, v80
	v_rcp_f32_e32 v76, v76
	s_waitcnt vmcnt(3)
	v_mul_f32_e32 v69, 0x3f24fd5c, v69
	s_waitcnt vmcnt(2)
	v_mul_f32_e32 v71, 0x3f24fd5c, v71
	s_waitcnt vmcnt(1)
	v_mul_f32_e32 v73, 0x3f24fd5c, v73
	s_waitcnt vmcnt(0)
	v_mul_f32_e32 v77, 0x3f24fd5c, v67
	v_mov_b32_e32 v67, s4
	s_nop 0
	v_add_u32_e32 v79, 0, v160
	ds_read2st64_b32 v[74:75], v79 offset1:1
	v_add_u32_e32 v67, 0, v67
	v_lshl_add_u32 v78, v145, 1, v67
	s_waitcnt lgkmcnt(0)
	v_lshlrev_b32_e32 v102, 16, v74
	v_and_b32_e32 v103, 0xffff0000, v74
	v_lshlrev_b32_e32 v105, 16, v75
	v_and_b32_e32 v104, 0xffff0000, v75
	v_mov_b32_e32 v74, v2
	v_mov_b32_e32 v75, v50
	v_pk_mul_f32 v[74:75], v[74:75], v[100:101] op_sel_hi:[1,0]
	v_pk_mul_f32 v[100:101], v[106:107], v[100:101] op_sel_hi:[1,0]
	v_pk_fma_f32 v[102:103], v[142:143], v[74:75], v[102:103] neg_lo:[1,0,0] neg_hi:[1,0,0]
	v_pk_fma_f32 v[100:101], v[142:143], v[100:101], v[104:105] neg_lo:[1,0,0] neg_hi:[1,0,0]
	v_pk_mul_f32 v[74:75], v[102:103], v[102:103]
	v_pk_mul_f32 v[104:105], v[100:101], v[100:101]
	v_add_f32_e32 v2, v74, v75
	v_add_f32_e32 v2, v2, v105
	v_add_f32_e32 v2, v104, v2
	v_mad_u64_u32 v[74:75], s[4:5], v81, s77, v[78:79]
	s_waitcnt lgkmcnt(0)
	s_nop 1
	v_add_f32_dpp v2, v2, v2 quad_perm:[1,0,3,2] row_mask:0xf bank_mask:0xf
	s_waitcnt lgkmcnt(0)
	s_nop 1
	v_add_f32_dpp v2, v2, v2 quad_perm:[2,3,0,1] row_mask:0xf bank_mask:0xf
	s_waitcnt lgkmcnt(0)
	s_nop 1
	v_add_f32_dpp v2, v2, v2 row_half_mirror row_mask:0xf bank_mask:0xf
	s_waitcnt lgkmcnt(0)
	s_nop 1
	v_add_f32_dpp v2, v2, v2 row_mirror row_mask:0xf bank_mask:0xf
	v_mov_b32_e32 v18, v2
	s_nop 1
	v_permlane16_swap_b32_e32 v2, v18
	s_waitcnt lgkmcnt(0)
	v_add_f32_e32 v2, v2, v18
	v_fmamk_f32 v2, v2, 0x3c000000, v249
	v_cmp_gt_f32_e32 vcc, s10, v2
	v_mul_f32_e32 v18, 0x4b800000, v2
	s_nop 0
	v_cndmask_b32_e32 v2, v2, v18, vcc
	v_rsq_f32_e32 v2, v2
	s_nop 0
	v_mul_f32_e32 v18, 0x45800000, v2
	v_cndmask_b32_e32 v2, v2, v18, vcc
	v_mul_f32_e32 v18, v102, v2
	v_mul_f32_e32 v18, v69, v18
	v_cvt_pk_bf16_f32 v18, v18, s0
	ds_write_b16 v74, v18
	v_mul_f32_e32 v18, v103, v2
	v_mul_f32_e32 v18, v71, v18
	v_cvt_pk_bf16_f32 v18, v18, s0
	ds_write_b16 v74, v18 offset:64
	v_mul_f32_e32 v18, v101, v2
	v_mul_f32_e32 v2, v100, v2
	v_mul_f32_e32 v18, v73, v18
	v_mul_f32_e32 v2, v77, v2
	v_cvt_pk_bf16_f32 v18, v18, s0
	v_cvt_pk_bf16_f32 v2, v2, s0
	ds_write_b16 v74, v18 offset:128
	ds_write_b16 v74, v2 offset:192
	ds_read2st64_b32 v[100:101], v79 offset0:2 offset1:3
	v_mov_b32_e32 v50, v3
	v_pk_mul_f32 v[50:51], v[50:51], v[98:99] op_sel_hi:[1,0]
	v_mov_b32_e32 v18, v35
	v_pk_mul_f32 v[18:19], v[18:19], v[98:99] op_sel_hi:[1,0]
	s_waitcnt lgkmcnt(0)
	v_lshlrev_b32_e32 v2, 16, v100
	v_and_b32_e32 v3, 0xffff0000, v100
	v_lshlrev_b32_e32 v103, 16, v101
	v_and_b32_e32 v102, 0xffff0000, v101
	v_pk_fma_f32 v[2:3], v[142:143], v[50:51], v[2:3] neg_lo:[1,0,0] neg_hi:[1,0,0]
	v_pk_fma_f32 v[18:19], v[142:143], v[18:19], v[102:103] neg_lo:[1,0,0] neg_hi:[1,0,0]
	v_pk_mul_f32 v[50:51], v[2:3], v[2:3]
	v_pk_mul_f32 v[34:35], v[18:19], v[18:19]
	v_add_f32_e32 v50, v50, v51
	v_add_f32_e32 v35, v50, v35
	v_add_f32_e32 v34, v34, v35
	s_waitcnt lgkmcnt(0)
	s_nop 1
	v_add_f32_dpp v34, v34, v34 quad_perm:[1,0,3,2] row_mask:0xf bank_mask:0xf
	s_waitcnt lgkmcnt(0)
	s_nop 1
	v_add_f32_dpp v34, v34, v34 quad_perm:[2,3,0,1] row_mask:0xf bank_mask:0xf
	s_waitcnt lgkmcnt(0)
	s_nop 1
	v_add_f32_dpp v34, v34, v34 row_half_mirror row_mask:0xf bank_mask:0xf
	s_waitcnt lgkmcnt(0)
	s_nop 1
	v_add_f32_dpp v34, v34, v34 row_mirror row_mask:0xf bank_mask:0xf
	v_mov_b32_e32 v35, v34
	s_nop 1
	v_permlane16_swap_b32_e32 v34, v35
	s_waitcnt lgkmcnt(0)
	v_add_f32_e32 v34, v34, v35
	v_fmamk_f32 v34, v34, 0x3c000000, v249
	v_mul_f32_e32 v35, 0x4b800000, v34
	v_cmp_gt_f32_e32 vcc, s10, v34
	s_nop 1
	v_cndmask_b32_e32 v34, v34, v35, vcc
	v_rsq_f32_e32 v34, v34
	s_nop 0
	v_mul_f32_e32 v35, 0x45800000, v34
	v_cndmask_b32_e32 v34, v34, v35, vcc
	v_mul_f32_e32 v2, v2, v34
	v_mul_f32_e32 v3, v3, v34
	v_mul_f32_e32 v19, v19, v34
	v_mul_f32_e32 v18, v18, v34
	v_mul_f32_e32 v2, v69, v2
	v_mul_f32_e32 v3, v71, v3
	v_mul_f32_e32 v19, v73, v19
	v_mul_f32_e32 v18, v77, v18
	v_cvt_pk_bf16_f32 v2, v2, s0
	v_cvt_pk_bf16_f32 v3, v3, s0
	v_cvt_pk_bf16_f32 v19, v19, s0
	v_cvt_pk_bf16_f32 v18, v18, s0
	ds_write_b16 v74, v2 offset:272
	ds_write_b16 v74, v3 offset:336
	ds_write_b16 v74, v19 offset:400
	ds_write_b16 v74, v18 offset:464
	ds_read2st64_b32 v[2:3], v79 offset0:4 offset1:5
	v_mov_b32_e32 v18, v4
	v_mov_b32_e32 v19, v52
	s_waitcnt lgkmcnt(0)
	v_lshlrev_b32_e32 v34, 16, v2
	v_and_b32_e32 v35, 0xffff0000, v2
	v_lshlrev_b32_e32 v51, 16, v3
	v_and_b32_e32 v50, 0xffff0000, v3
	v_pk_mul_f32 v[2:3], v[18:19], v[96:97] op_sel_hi:[1,0]
	s_nop 0
	v_pk_fma_f32 v[2:3], v[142:143], v[2:3], v[34:35] neg_lo:[1,0,0] neg_hi:[1,0,0]
	v_mov_b32_e32 v34, v36
	v_mov_b32_e32 v35, v20
	v_pk_mul_f32 v[34:35], v[34:35], v[96:97] op_sel_hi:[1,0]
	v_pk_mul_f32 v[18:19], v[2:3], v[2:3]
	v_pk_fma_f32 v[34:35], v[142:143], v[34:35], v[50:51] neg_lo:[1,0,0] neg_hi:[1,0,0]
	v_add_f32_e32 v4, v18, v19
	v_pk_mul_f32 v[50:51], v[34:35], v[34:35]
	s_nop 0
	v_add_f32_e32 v4, v4, v51
	v_add_f32_e32 v4, v50, v4
	s_waitcnt lgkmcnt(0)
	s_nop 1
	v_add_f32_dpp v4, v4, v4 quad_perm:[1,0,3,2] row_mask:0xf bank_mask:0xf
	s_waitcnt lgkmcnt(0)
	s_nop 1
	v_add_f32_dpp v4, v4, v4 quad_perm:[2,3,0,1] row_mask:0xf bank_mask:0xf
	s_waitcnt lgkmcnt(0)
	s_nop 1
	v_add_f32_dpp v4, v4, v4 row_half_mirror row_mask:0xf bank_mask:0xf
	s_waitcnt lgkmcnt(0)
	s_nop 1
	v_add_f32_dpp v4, v4, v4 row_mirror row_mask:0xf bank_mask:0xf
	v_mov_b32_e32 v18, v4
	s_nop 1
	v_permlane16_swap_b32_e32 v4, v18
	s_waitcnt lgkmcnt(0)
	v_add_f32_e32 v4, v4, v18
	v_fmamk_f32 v4, v4, 0x3c000000, v249
	v_mul_f32_e32 v18, 0x4b800000, v4
	v_cmp_gt_f32_e32 vcc, s10, v4
	s_nop 1
	v_cndmask_b32_e32 v4, v4, v18, vcc
	v_rsq_f32_e32 v4, v4
	s_nop 0
	v_mul_f32_e32 v18, 0x45800000, v4
	v_cndmask_b32_e32 v4, v4, v18, vcc
	v_mul_f32_e32 v2, v2, v4
	v_mul_f32_e32 v3, v3, v4
	v_mul_f32_e32 v18, v35, v4
	v_mul_f32_e32 v4, v34, v4
	v_mul_f32_e32 v2, v69, v2
	v_mul_f32_e32 v3, v71, v3
	v_mul_f32_e32 v18, v73, v18
	v_mul_f32_e32 v4, v77, v4
	v_cvt_pk_bf16_f32 v2, v2, s0
	v_cvt_pk_bf16_f32 v3, v3, s0
	v_cvt_pk_bf16_f32 v18, v18, s0
	v_cvt_pk_bf16_f32 v4, v4, s0
	ds_write_b16 v74, v2 offset:544
	ds_write_b16 v74, v3 offset:608
	ds_write_b16 v74, v18 offset:672
	ds_write_b16 v74, v4 offset:736
	ds_read2st64_b32 v[2:3], v79 offset0:6 offset1:7
	v_mov_b32_e32 v52, v5
	v_mov_b32_e32 v20, v37
	s_waitcnt lgkmcnt(0)
	v_lshlrev_b32_e32 v18, 16, v2
	v_and_b32_e32 v19, 0xffff0000, v2
	v_lshlrev_b32_e32 v35, 16, v3
	v_and_b32_e32 v34, 0xffff0000, v3
	v_pk_mul_f32 v[2:3], v[52:53], v[94:95] op_sel_hi:[1,0]
	s_nop 0
	v_pk_fma_f32 v[4:5], v[142:143], v[2:3], v[18:19] neg_lo:[1,0,0] neg_hi:[1,0,0]
	v_pk_mul_f32 v[18:19], v[20:21], v[94:95] op_sel_hi:[1,0]
	v_pk_mul_f32 v[2:3], v[4:5], v[4:5]
	v_pk_fma_f32 v[18:19], v[142:143], v[18:19], v[34:35] neg_lo:[1,0,0] neg_hi:[1,0,0]
	v_add_f32_e32 v2, v2, v3
	v_pk_mul_f32 v[20:21], v[18:19], v[18:19]
	s_nop 0
	v_add_f32_e32 v2, v2, v21
	v_add_f32_e32 v2, v20, v2
	s_waitcnt lgkmcnt(0)
	s_nop 1
	v_add_f32_dpp v2, v2, v2 quad_perm:[1,0,3,2] row_mask:0xf bank_mask:0xf
	s_waitcnt lgkmcnt(0)
	s_nop 1
	v_add_f32_dpp v2, v2, v2 quad_perm:[2,3,0,1] row_mask:0xf bank_mask:0xf
	s_waitcnt lgkmcnt(0)
	s_nop 1
	v_add_f32_dpp v2, v2, v2 row_half_mirror row_mask:0xf bank_mask:0xf
	s_waitcnt lgkmcnt(0)
	s_nop 1
	v_add_f32_dpp v2, v2, v2 row_mirror row_mask:0xf bank_mask:0xf
	v_mov_b32_e32 v3, v2
	s_nop 1
	v_permlane16_swap_b32_e32 v2, v3
	s_waitcnt lgkmcnt(0)
	v_add_f32_e32 v2, v2, v3
	v_fmamk_f32 v2, v2, 0x3c000000, v249
	v_cmp_gt_f32_e32 vcc, s10, v2
	v_mul_f32_e32 v3, 0x4b800000, v2
	s_nop 0
	v_cndmask_b32_e32 v2, v2, v3, vcc
	v_rsq_f32_e32 v2, v2
	s_nop 0
	v_mul_f32_e32 v3, 0x45800000, v2
	v_cndmask_b32_e32 v20, v2, v3, vcc
	v_or_b32_e32 v2, 3, v80
	v_mad_u64_u32 v[2:3], s[4:5], v2, s77, v[78:79]
	v_mul_f32_e32 v3, v4, v20
	v_mul_f32_e32 v3, v69, v3
	v_cvt_pk_bf16_f32 v3, v3, s0
	ds_write_b16 v2, v3
	v_mul_f32_e32 v3, v5, v20
	v_mul_f32_e32 v3, v71, v3
	v_cvt_pk_bf16_f32 v3, v3, s0
	ds_write_b16 v2, v3 offset:64
	v_mul_f32_e32 v3, v19, v20
	v_mul_f32_e32 v3, v73, v3
	v_cvt_pk_bf16_f32 v3, v3, s0
	ds_write_b16 v2, v3 offset:128
	v_mul_f32_e32 v3, v18, v20
	v_mul_f32_e32 v3, v77, v3
	v_cvt_pk_bf16_f32 v3, v3, s0
	ds_write_b16 v2, v3 offset:192
	ds_read2st64_b32 v[4:5], v79 offset0:8 offset1:9
	v_mov_b32_e32 v18, v6
	v_mov_b32_e32 v19, v54
	s_waitcnt lgkmcnt(0)
	v_lshlrev_b32_e32 v20, 16, v4
	v_and_b32_e32 v21, 0xffff0000, v4
	v_lshlrev_b32_e32 v35, 16, v5
	v_and_b32_e32 v34, 0xffff0000, v5
	v_pk_mul_f32 v[4:5], v[18:19], v[92:93] op_sel_hi:[1,0]
	s_nop 0
	v_pk_fma_f32 v[4:5], v[142:143], v[4:5], v[20:21] neg_lo:[1,0,0] neg_hi:[1,0,0]
	v_mov_b32_e32 v20, v38
	v_mov_b32_e32 v21, v22
	v_pk_mul_f32 v[20:21], v[20:21], v[92:93] op_sel_hi:[1,0]
	v_pk_mul_f32 v[18:19], v[4:5], v[4:5]
	v_pk_fma_f32 v[20:21], v[142:143], v[20:21], v[34:35] neg_lo:[1,0,0] neg_hi:[1,0,0]
	v_add_f32_e32 v3, v18, v19
	v_pk_mul_f32 v[34:35], v[20:21], v[20:21]
	s_nop 0
	v_add_f32_e32 v3, v3, v35
	v_add_f32_e32 v3, v34, v3
	s_waitcnt lgkmcnt(0)
	s_nop 1
	v_add_f32_dpp v3, v3, v3 quad_perm:[1,0,3,2] row_mask:0xf bank_mask:0xf
	s_waitcnt lgkmcnt(0)
	s_nop 1
	v_add_f32_dpp v3, v3, v3 quad_perm:[2,3,0,1] row_mask:0xf bank_mask:0xf
	s_waitcnt lgkmcnt(0)
	s_nop 1
	v_add_f32_dpp v3, v3, v3 row_half_mirror row_mask:0xf bank_mask:0xf
	s_waitcnt lgkmcnt(0)
	s_nop 1
	v_add_f32_dpp v3, v3, v3 row_mirror row_mask:0xf bank_mask:0xf
	v_mov_b32_e32 v6, v3
	s_nop 1
	v_permlane16_swap_b32_e32 v3, v6
	s_waitcnt lgkmcnt(0)
	v_add_f32_e32 v3, v3, v6
	v_fmamk_f32 v3, v3, 0x3c000000, v249
	v_mul_f32_e32 v6, 0x4b800000, v3
	v_cmp_gt_f32_e32 vcc, s10, v3
	s_nop 1
	v_cndmask_b32_e32 v3, v3, v6, vcc
	v_rsq_f32_e32 v3, v3
	s_nop 0
	v_mul_f32_e32 v6, 0x45800000, v3
	v_cndmask_b32_e32 v3, v3, v6, vcc
	v_mul_f32_e32 v4, v4, v3
	v_mul_f32_e32 v5, v5, v3
	v_mul_f32_e32 v6, v21, v3
	v_mul_f32_e32 v3, v20, v3
	v_mul_f32_e32 v4, v69, v4
	v_mul_f32_e32 v5, v71, v5
	v_mul_f32_e32 v6, v73, v6
	v_mul_f32_e32 v3, v77, v3
	v_cvt_pk_bf16_f32 v4, v4, s0
	v_cvt_pk_bf16_f32 v5, v5, s0
	v_cvt_pk_bf16_f32 v6, v6, s0
	v_cvt_pk_bf16_f32 v3, v3, s0
	ds_write_b16 v74, v4 offset:2176
	ds_write_b16 v74, v5 offset:2240
	ds_write_b16 v74, v6 offset:2304
	ds_write_b16 v74, v3 offset:2368
	ds_read2st64_b32 v[4:5], v79 offset0:10 offset1:11
	v_mov_b32_e32 v54, v7
	v_mov_b32_e32 v22, v39
	v_pk_mul_f32 v[20:21], v[22:23], v[90:91] op_sel_hi:[1,0]
	s_waitcnt lgkmcnt(0)
	v_lshlrev_b32_e32 v6, 16, v4
	v_and_b32_e32 v7, 0xffff0000, v4
	v_lshlrev_b32_e32 v19, 16, v5
	v_and_b32_e32 v18, 0xffff0000, v5
	v_pk_mul_f32 v[4:5], v[54:55], v[90:91] op_sel_hi:[1,0]
	v_pk_fma_f32 v[18:19], v[142:143], v[20:21], v[18:19] neg_lo:[1,0,0] neg_hi:[1,0,0]
	v_pk_fma_f32 v[4:5], v[142:143], v[4:5], v[6:7] neg_lo:[1,0,0] neg_hi:[1,0,0]
	v_pk_mul_f32 v[20:21], v[18:19], v[18:19]
	v_pk_mul_f32 v[6:7], v[4:5], v[4:5]
	s_nop 0
	v_add_f32_e32 v3, v6, v7
	v_add_f32_e32 v3, v3, v21
	v_add_f32_e32 v3, v20, v3
	s_waitcnt lgkmcnt(0)
	s_nop 1
	v_add_f32_dpp v3, v3, v3 quad_perm:[1,0,3,2] row_mask:0xf bank_mask:0xf
	s_waitcnt lgkmcnt(0)
	s_nop 1
	v_add_f32_dpp v3, v3, v3 quad_perm:[2,3,0,1] row_mask:0xf bank_mask:0xf
	s_waitcnt lgkmcnt(0)
	s_nop 1
	v_add_f32_dpp v3, v3, v3 row_half_mirror row_mask:0xf bank_mask:0xf
	s_waitcnt lgkmcnt(0)
	s_nop 1
	v_add_f32_dpp v3, v3, v3 row_mirror row_mask:0xf bank_mask:0xf
	v_mov_b32_e32 v6, v3
	s_nop 1
	v_permlane16_swap_b32_e32 v3, v6
	s_waitcnt lgkmcnt(0)
	v_add_f32_e32 v3, v3, v6
	v_fmamk_f32 v3, v3, 0x3c000000, v249
	v_mul_f32_e32 v6, 0x4b800000, v3
	v_cmp_gt_f32_e32 vcc, s10, v3
	s_nop 1
	v_cndmask_b32_e32 v3, v3, v6, vcc
	v_rsq_f32_e32 v3, v3
	s_nop 0
	v_mul_f32_e32 v6, 0x45800000, v3
	v_cndmask_b32_e32 v3, v3, v6, vcc
	v_mul_f32_e32 v4, v4, v3
	v_mul_f32_e32 v5, v5, v3
	v_mul_f32_e32 v6, v19, v3
	v_mul_f32_e32 v3, v18, v3
	v_mul_f32_e32 v4, v69, v4
	v_mul_f32_e32 v5, v71, v5
	v_mul_f32_e32 v6, v73, v6
	v_mul_f32_e32 v3, v77, v3
	v_cvt_pk_bf16_f32 v4, v4, s0
	v_cvt_pk_bf16_f32 v5, v5, s0
	v_cvt_pk_bf16_f32 v6, v6, s0
	v_cvt_pk_bf16_f32 v3, v3, s0
	ds_write_b16 v74, v4 offset:2448
	ds_write_b16 v74, v5 offset:2512
	ds_write_b16 v74, v6 offset:2576
	ds_write_b16 v74, v3 offset:2640
	ds_read2st64_b32 v[4:5], v79 offset0:12 offset1:13
	v_mov_b32_e32 v6, v8
	v_mov_b32_e32 v7, v56
	s_waitcnt lgkmcnt(0)
	v_lshlrev_b32_e32 v18, 16, v4
	v_and_b32_e32 v19, 0xffff0000, v4
	v_lshlrev_b32_e32 v21, 16, v5
	v_and_b32_e32 v20, 0xffff0000, v5
	v_pk_mul_f32 v[4:5], v[6:7], v[88:89] op_sel_hi:[1,0]
	s_nop 0
	v_pk_fma_f32 v[4:5], v[142:143], v[4:5], v[18:19] neg_lo:[1,0,0] neg_hi:[1,0,0]
	v_mov_b32_e32 v18, v40
	v_mov_b32_e32 v19, v24
	v_pk_mul_f32 v[18:19], v[18:19], v[88:89] op_sel_hi:[1,0]
	v_pk_mul_f32 v[6:7], v[4:5], v[4:5]
	v_pk_fma_f32 v[18:19], v[142:143], v[18:19], v[20:21] neg_lo:[1,0,0] neg_hi:[1,0,0]
	v_add_f32_e32 v3, v6, v7
	v_pk_mul_f32 v[20:21], v[18:19], v[18:19]
	s_nop 0
	v_add_f32_e32 v3, v3, v21
	v_add_f32_e32 v3, v20, v3
	s_waitcnt lgkmcnt(0)
	s_nop 1
	v_add_f32_dpp v3, v3, v3 quad_perm:[1,0,3,2] row_mask:0xf bank_mask:0xf
	s_waitcnt lgkmcnt(0)
	s_nop 1
	v_add_f32_dpp v3, v3, v3 quad_perm:[2,3,0,1] row_mask:0xf bank_mask:0xf
	s_waitcnt lgkmcnt(0)
	s_nop 1
	v_add_f32_dpp v3, v3, v3 row_half_mirror row_mask:0xf bank_mask:0xf
	s_waitcnt lgkmcnt(0)
	s_nop 1
	v_add_f32_dpp v3, v3, v3 row_mirror row_mask:0xf bank_mask:0xf
	v_mov_b32_e32 v6, v3
	s_nop 1
	v_permlane16_swap_b32_e32 v3, v6
	s_waitcnt lgkmcnt(0)
	v_add_f32_e32 v3, v3, v6
	v_fmamk_f32 v3, v3, 0x3c000000, v249
	v_mul_f32_e32 v6, 0x4b800000, v3
	v_cmp_gt_f32_e32 vcc, s10, v3
	s_nop 1
	v_cndmask_b32_e32 v3, v3, v6, vcc
	v_rsq_f32_e32 v3, v3
	s_nop 0
	v_mul_f32_e32 v6, 0x45800000, v3
	v_cndmask_b32_e32 v3, v3, v6, vcc
	v_mul_f32_e32 v4, v4, v3
	v_mul_f32_e32 v5, v5, v3
	v_mul_f32_e32 v6, v19, v3
	v_mul_f32_e32 v3, v18, v3
	v_mul_f32_e32 v4, v69, v4
	v_mul_f32_e32 v5, v71, v5
	v_mul_f32_e32 v6, v73, v6
	v_mul_f32_e32 v3, v77, v3
	v_cvt_pk_bf16_f32 v4, v4, s0
	v_cvt_pk_bf16_f32 v5, v5, s0
	v_cvt_pk_bf16_f32 v6, v6, s0
	v_cvt_pk_bf16_f32 v3, v3, s0
	ds_write_b16 v74, v4 offset:2720
	ds_write_b16 v74, v5 offset:2784
	ds_write_b16 v74, v6 offset:2848
	ds_write_b16 v74, v3 offset:2912
	ds_read2st64_b32 v[4:5], v79 offset0:14 offset1:15
	v_mov_b32_e32 v56, v9
	v_mov_b32_e32 v24, v41
	v_pk_mul_f32 v[18:19], v[24:25], v[86:87] op_sel_hi:[1,0]
	s_waitcnt lgkmcnt(0)
	v_lshlrev_b32_e32 v6, 16, v4
	v_and_b32_e32 v7, 0xffff0000, v4
	v_lshlrev_b32_e32 v9, 16, v5
	v_and_b32_e32 v8, 0xffff0000, v5
	v_pk_mul_f32 v[4:5], v[56:57], v[86:87] op_sel_hi:[1,0]
	v_pk_fma_f32 v[8:9], v[142:143], v[18:19], v[8:9] neg_lo:[1,0,0] neg_hi:[1,0,0]
	v_pk_fma_f32 v[4:5], v[142:143], v[4:5], v[6:7] neg_lo:[1,0,0] neg_hi:[1,0,0]
	v_pk_mul_f32 v[18:19], v[8:9], v[8:9]
	v_pk_mul_f32 v[6:7], v[4:5], v[4:5]
	s_nop 0
	v_add_f32_e32 v3, v6, v7
	v_add_f32_e32 v3, v3, v19
	v_add_f32_e32 v3, v18, v3
	s_waitcnt lgkmcnt(0)
	s_nop 1
	v_add_f32_dpp v3, v3, v3 quad_perm:[1,0,3,2] row_mask:0xf bank_mask:0xf
	s_waitcnt lgkmcnt(0)
	s_nop 1
	v_add_f32_dpp v3, v3, v3 quad_perm:[2,3,0,1] row_mask:0xf bank_mask:0xf
	s_waitcnt lgkmcnt(0)
	s_nop 1
	v_add_f32_dpp v3, v3, v3 row_half_mirror row_mask:0xf bank_mask:0xf
	s_waitcnt lgkmcnt(0)
	s_nop 1
	v_add_f32_dpp v3, v3, v3 row_mirror row_mask:0xf bank_mask:0xf
	v_mov_b32_e32 v6, v3
	s_nop 1
	v_permlane16_swap_b32_e32 v3, v6
	s_waitcnt lgkmcnt(0)
	v_add_f32_e32 v3, v3, v6
	v_fmamk_f32 v3, v3, 0x3c000000, v249
	v_mul_f32_e32 v6, 0x4b800000, v3
	v_cmp_gt_f32_e32 vcc, s10, v3
	s_nop 1
	v_cndmask_b32_e32 v3, v3, v6, vcc
	v_rsq_f32_e32 v3, v3
	s_nop 0
	v_mul_f32_e32 v6, 0x45800000, v3
	v_cndmask_b32_e32 v3, v3, v6, vcc
	v_mul_f32_e32 v4, v4, v3
	v_mul_f32_e32 v5, v5, v3
	v_mul_f32_e32 v6, v9, v3
	v_mul_f32_e32 v3, v8, v3
	v_mul_f32_e32 v4, v69, v4
	v_mul_f32_e32 v5, v71, v5
	v_mul_f32_e32 v6, v73, v6
	v_mul_f32_e32 v3, v77, v3
	v_cvt_pk_bf16_f32 v4, v4, s0
	v_cvt_pk_bf16_f32 v5, v5, s0
	v_cvt_pk_bf16_f32 v6, v6, s0
	v_cvt_pk_bf16_f32 v3, v3, s0
	ds_write_b16 v2, v4 offset:2176
	ds_write_b16 v2, v5 offset:2240
	ds_write_b16 v2, v6 offset:2304
	ds_write_b16 v2, v3 offset:2368
	ds_read2st64_b32 v[4:5], v79 offset0:16 offset1:17
	v_mov_b32_e32 v6, v10
	v_mov_b32_e32 v7, v58
	s_waitcnt lgkmcnt(0)
	v_lshlrev_b32_e32 v8, 16, v4
	v_and_b32_e32 v9, 0xffff0000, v4
	v_lshlrev_b32_e32 v19, 16, v5
	v_and_b32_e32 v18, 0xffff0000, v5
	v_pk_mul_f32 v[4:5], v[6:7], v[84:85] op_sel_hi:[1,0]
	s_nop 0
	v_pk_fma_f32 v[4:5], v[142:143], v[4:5], v[8:9] neg_lo:[1,0,0] neg_hi:[1,0,0]
	v_mov_b32_e32 v8, v42
	v_mov_b32_e32 v9, v26
	v_pk_mul_f32 v[8:9], v[8:9], v[84:85] op_sel_hi:[1,0]
	v_pk_mul_f32 v[6:7], v[4:5], v[4:5]
	v_pk_fma_f32 v[8:9], v[142:143], v[8:9], v[18:19] neg_lo:[1,0,0] neg_hi:[1,0,0]
	v_add_f32_e32 v3, v6, v7
	v_pk_mul_f32 v[18:19], v[8:9], v[8:9]
	s_nop 0
	v_add_f32_e32 v3, v3, v19
	v_add_f32_e32 v3, v18, v3
	s_waitcnt lgkmcnt(0)
	s_nop 1
	v_add_f32_dpp v3, v3, v3 quad_perm:[1,0,3,2] row_mask:0xf bank_mask:0xf
	s_waitcnt lgkmcnt(0)
	s_nop 1
	v_add_f32_dpp v3, v3, v3 quad_perm:[2,3,0,1] row_mask:0xf bank_mask:0xf
	s_waitcnt lgkmcnt(0)
	s_nop 1
	v_add_f32_dpp v3, v3, v3 row_half_mirror row_mask:0xf bank_mask:0xf
	s_waitcnt lgkmcnt(0)
	s_nop 1
	v_add_f32_dpp v3, v3, v3 row_mirror row_mask:0xf bank_mask:0xf
	v_mov_b32_e32 v6, v3
	s_nop 1
	v_permlane16_swap_b32_e32 v3, v6
	s_waitcnt lgkmcnt(0)
	v_add_f32_e32 v3, v3, v6
	v_fmamk_f32 v3, v3, 0x3c000000, v249
	v_mul_f32_e32 v6, 0x4b800000, v3
	v_cmp_gt_f32_e32 vcc, s10, v3
	s_nop 1
	v_cndmask_b32_e32 v3, v3, v6, vcc
	v_rsq_f32_e32 v3, v3
	s_nop 0
	v_mul_f32_e32 v6, 0x45800000, v3
	v_cndmask_b32_e32 v3, v3, v6, vcc
	v_mul_f32_e32 v4, v4, v3
	v_mul_f32_e32 v5, v5, v3
	v_mul_f32_e32 v6, v9, v3
	v_mul_f32_e32 v3, v8, v3
	v_mul_f32_e32 v4, v69, v4
	v_mul_f32_e32 v5, v71, v5
	v_mul_f32_e32 v6, v73, v6
	v_mul_f32_e32 v3, v77, v3
	v_cvt_pk_bf16_f32 v4, v4, s0
	v_cvt_pk_bf16_f32 v5, v5, s0
	v_cvt_pk_bf16_f32 v6, v6, s0
	v_cvt_pk_bf16_f32 v3, v3, s0
	ds_write_b16 v74, v4 offset:4352
	ds_write_b16 v74, v5 offset:4416
	ds_write_b16 v74, v6 offset:4480
	ds_write_b16 v74, v3 offset:4544
	ds_read2st64_b32 v[4:5], v79 offset0:18 offset1:19
	v_mov_b32_e32 v58, v11
	v_mov_b32_e32 v26, v43
	v_pk_mul_f32 v[10:11], v[26:27], v[82:83] op_sel_hi:[1,0]
	s_waitcnt lgkmcnt(0)
	v_lshlrev_b32_e32 v6, 16, v4
	v_and_b32_e32 v7, 0xffff0000, v4
	v_lshlrev_b32_e32 v9, 16, v5
	v_and_b32_e32 v8, 0xffff0000, v5
	v_pk_mul_f32 v[4:5], v[58:59], v[82:83] op_sel_hi:[1,0]
	v_pk_fma_f32 v[8:9], v[142:143], v[10:11], v[8:9] neg_lo:[1,0,0] neg_hi:[1,0,0]
	v_pk_fma_f32 v[4:5], v[142:143], v[4:5], v[6:7] neg_lo:[1,0,0] neg_hi:[1,0,0]
	v_pk_mul_f32 v[10:11], v[8:9], v[8:9]
	v_pk_mul_f32 v[6:7], v[4:5], v[4:5]
	s_nop 0
	v_add_f32_e32 v3, v6, v7
	v_add_f32_e32 v3, v3, v11
	v_add_f32_e32 v3, v10, v3
	s_waitcnt lgkmcnt(0)
	s_nop 1
	v_add_f32_dpp v3, v3, v3 quad_perm:[1,0,3,2] row_mask:0xf bank_mask:0xf
	s_waitcnt lgkmcnt(0)
	s_nop 1
	v_add_f32_dpp v3, v3, v3 quad_perm:[2,3,0,1] row_mask:0xf bank_mask:0xf
	s_waitcnt lgkmcnt(0)
	s_nop 1
	v_add_f32_dpp v3, v3, v3 row_half_mirror row_mask:0xf bank_mask:0xf
	s_waitcnt lgkmcnt(0)
	s_nop 1
	v_add_f32_dpp v3, v3, v3 row_mirror row_mask:0xf bank_mask:0xf
	v_mov_b32_e32 v6, v3
	s_nop 1
	v_permlane16_swap_b32_e32 v3, v6
	s_waitcnt lgkmcnt(0)
	v_add_f32_e32 v3, v3, v6
	v_fmamk_f32 v3, v3, 0x3c000000, v249
	v_mul_f32_e32 v6, 0x4b800000, v3
	v_cmp_gt_f32_e32 vcc, s10, v3
	s_nop 1
	v_cndmask_b32_e32 v3, v3, v6, vcc
	v_rsq_f32_e32 v3, v3
	s_nop 0
	v_mul_f32_e32 v6, 0x45800000, v3
	v_cndmask_b32_e32 v3, v3, v6, vcc
	v_mul_f32_e32 v4, v4, v3
	v_mul_f32_e32 v5, v5, v3
	v_mul_f32_e32 v6, v9, v3
	v_mul_f32_e32 v3, v8, v3
	v_mul_f32_e32 v4, v69, v4
	v_mul_f32_e32 v5, v71, v5
	v_mul_f32_e32 v6, v73, v6
	v_mul_f32_e32 v3, v77, v3
	v_cvt_pk_bf16_f32 v4, v4, s0
	v_cvt_pk_bf16_f32 v5, v5, s0
	v_cvt_pk_bf16_f32 v6, v6, s0
	v_cvt_pk_bf16_f32 v3, v3, s0
	ds_write_b16 v74, v4 offset:4624
	ds_write_b16 v74, v5 offset:4688
	ds_write_b16 v74, v6 offset:4752
	ds_write_b16 v74, v3 offset:4816
	ds_read2st64_b32 v[4:5], v79 offset0:20 offset1:21
	v_mov_b32_e32 v6, v12
	v_mov_b32_e32 v7, v60
	s_waitcnt lgkmcnt(0)
	v_lshlrev_b32_e32 v8, 16, v4
	v_and_b32_e32 v9, 0xffff0000, v4
	v_lshlrev_b32_e32 v11, 16, v5
	v_and_b32_e32 v10, 0xffff0000, v5
	v_pk_mul_f32 v[4:5], v[6:7], v[76:77] op_sel_hi:[1,0]
	s_nop 0
	v_pk_fma_f32 v[4:5], v[142:143], v[4:5], v[8:9] neg_lo:[1,0,0] neg_hi:[1,0,0]
	v_mov_b32_e32 v8, v44
	v_mov_b32_e32 v9, v28
	v_pk_mul_f32 v[8:9], v[8:9], v[76:77] op_sel_hi:[1,0]
	v_pk_mul_f32 v[6:7], v[4:5], v[4:5]
	v_pk_fma_f32 v[8:9], v[142:143], v[8:9], v[10:11] neg_lo:[1,0,0] neg_hi:[1,0,0]
	v_add_f32_e32 v3, v6, v7
	v_pk_mul_f32 v[10:11], v[8:9], v[8:9]
	s_nop 0
	v_add_f32_e32 v3, v3, v11
	v_add_f32_e32 v3, v10, v3
	s_waitcnt lgkmcnt(0)
	s_nop 1
	v_add_f32_dpp v3, v3, v3 quad_perm:[1,0,3,2] row_mask:0xf bank_mask:0xf
	s_waitcnt lgkmcnt(0)
	s_nop 1
	v_add_f32_dpp v3, v3, v3 quad_perm:[2,3,0,1] row_mask:0xf bank_mask:0xf
	s_waitcnt lgkmcnt(0)
	s_nop 1
	v_add_f32_dpp v3, v3, v3 row_half_mirror row_mask:0xf bank_mask:0xf
	s_waitcnt lgkmcnt(0)
	s_nop 1
	v_add_f32_dpp v3, v3, v3 row_mirror row_mask:0xf bank_mask:0xf
	v_mov_b32_e32 v6, v3
	s_nop 1
	v_permlane16_swap_b32_e32 v3, v6
	s_waitcnt lgkmcnt(0)
	v_add_f32_e32 v3, v3, v6
	v_fmamk_f32 v3, v3, 0x3c000000, v249
	v_mul_f32_e32 v6, 0x4b800000, v3
	v_cmp_gt_f32_e32 vcc, s10, v3
	s_nop 1
	v_cndmask_b32_e32 v3, v3, v6, vcc
	v_rsq_f32_e32 v3, v3
	s_nop 0
	v_mul_f32_e32 v6, 0x45800000, v3
	v_cndmask_b32_e32 v3, v3, v6, vcc
	v_mul_f32_e32 v4, v4, v3
	v_mul_f32_e32 v5, v5, v3
	v_mul_f32_e32 v6, v9, v3
	v_mul_f32_e32 v3, v8, v3
	v_mul_f32_e32 v4, v69, v4
	v_mul_f32_e32 v5, v71, v5
	v_mul_f32_e32 v6, v73, v6
	v_mul_f32_e32 v3, v77, v3
	v_cvt_pk_bf16_f32 v4, v4, s0
	v_cvt_pk_bf16_f32 v5, v5, s0
	v_cvt_pk_bf16_f32 v6, v6, s0
	v_cvt_pk_bf16_f32 v3, v3, s0
	ds_write_b16 v74, v4 offset:4896
	ds_write_b16 v74, v5 offset:4960
	ds_write_b16 v74, v6 offset:5024
	ds_write_b16 v74, v3 offset:5088
	ds_read2st64_b32 v[4:5], v79 offset0:22 offset1:23
	v_mov_b32_e32 v60, v13
	v_mov_b32_e32 v28, v45
	v_pk_mul_f32 v[10:11], v[28:29], v[72:73] op_sel_hi:[1,0]
	s_waitcnt lgkmcnt(0)
	v_lshlrev_b32_e32 v6, 16, v4
	v_and_b32_e32 v7, 0xffff0000, v4
	v_lshlrev_b32_e32 v9, 16, v5
	v_and_b32_e32 v8, 0xffff0000, v5
	v_pk_mul_f32 v[4:5], v[60:61], v[72:73] op_sel_hi:[1,0]
	v_pk_fma_f32 v[8:9], v[142:143], v[10:11], v[8:9] neg_lo:[1,0,0] neg_hi:[1,0,0]
	v_pk_fma_f32 v[4:5], v[142:143], v[4:5], v[6:7] neg_lo:[1,0,0] neg_hi:[1,0,0]
	v_pk_mul_f32 v[10:11], v[8:9], v[8:9]
	v_pk_mul_f32 v[6:7], v[4:5], v[4:5]
	s_nop 0
	v_add_f32_e32 v3, v6, v7
	v_add_f32_e32 v3, v3, v11
	v_add_f32_e32 v3, v10, v3
	s_waitcnt lgkmcnt(0)
	s_nop 1
	v_add_f32_dpp v3, v3, v3 quad_perm:[1,0,3,2] row_mask:0xf bank_mask:0xf
	s_waitcnt lgkmcnt(0)
	s_nop 1
	v_add_f32_dpp v3, v3, v3 quad_perm:[2,3,0,1] row_mask:0xf bank_mask:0xf
	s_waitcnt lgkmcnt(0)
	s_nop 1
	v_add_f32_dpp v3, v3, v3 row_half_mirror row_mask:0xf bank_mask:0xf
	s_waitcnt lgkmcnt(0)
	s_nop 1
	v_add_f32_dpp v3, v3, v3 row_mirror row_mask:0xf bank_mask:0xf
	v_mov_b32_e32 v6, v3
	s_nop 1
	v_permlane16_swap_b32_e32 v3, v6
	s_waitcnt lgkmcnt(0)
	v_add_f32_e32 v3, v3, v6
	v_fmamk_f32 v3, v3, 0x3c000000, v249
	v_mul_f32_e32 v6, 0x4b800000, v3
	v_cmp_gt_f32_e32 vcc, s10, v3
	s_nop 1
	v_cndmask_b32_e32 v3, v3, v6, vcc
	v_rsq_f32_e32 v3, v3
	s_nop 0
	v_mul_f32_e32 v6, 0x45800000, v3
	v_cndmask_b32_e32 v3, v3, v6, vcc
	v_mul_f32_e32 v4, v4, v3
	v_mul_f32_e32 v5, v5, v3
	v_mul_f32_e32 v6, v9, v3
	v_mul_f32_e32 v3, v8, v3
	v_mul_f32_e32 v4, v69, v4
	v_mul_f32_e32 v5, v71, v5
	v_mul_f32_e32 v6, v73, v6
	v_mul_f32_e32 v3, v77, v3
	v_cvt_pk_bf16_f32 v4, v4, s0
	v_cvt_pk_bf16_f32 v5, v5, s0
	v_cvt_pk_bf16_f32 v6, v6, s0
	v_cvt_pk_bf16_f32 v3, v3, s0
	ds_write_b16 v2, v4 offset:4352
	ds_write_b16 v2, v5 offset:4416
	ds_write_b16 v2, v6 offset:4480
	ds_write_b16 v2, v3 offset:4544
	ds_read2st64_b32 v[4:5], v79 offset0:24 offset1:25
	v_mov_b32_e32 v6, v14
	v_mov_b32_e32 v7, v62
	s_waitcnt lgkmcnt(0)
	v_lshlrev_b32_e32 v8, 16, v4
	v_and_b32_e32 v9, 0xffff0000, v4
	v_lshlrev_b32_e32 v11, 16, v5
	v_and_b32_e32 v10, 0xffff0000, v5
	v_pk_mul_f32 v[4:5], v[6:7], v[70:71] op_sel_hi:[1,0]
	s_nop 0
	v_pk_fma_f32 v[4:5], v[142:143], v[4:5], v[8:9] neg_lo:[1,0,0] neg_hi:[1,0,0]
	v_mov_b32_e32 v8, v46
	v_mov_b32_e32 v9, v30
	v_pk_mul_f32 v[8:9], v[8:9], v[70:71] op_sel_hi:[1,0]
	v_pk_mul_f32 v[6:7], v[4:5], v[4:5]
	v_pk_fma_f32 v[8:9], v[142:143], v[8:9], v[10:11] neg_lo:[1,0,0] neg_hi:[1,0,0]
	v_add_f32_e32 v3, v6, v7
	v_pk_mul_f32 v[10:11], v[8:9], v[8:9]
	s_nop 0
	v_add_f32_e32 v3, v3, v11
	v_add_f32_e32 v3, v10, v3
	s_waitcnt lgkmcnt(0)
	s_nop 1
	v_add_f32_dpp v3, v3, v3 quad_perm:[1,0,3,2] row_mask:0xf bank_mask:0xf
	s_waitcnt lgkmcnt(0)
	s_nop 1
	v_add_f32_dpp v3, v3, v3 quad_perm:[2,3,0,1] row_mask:0xf bank_mask:0xf
	s_waitcnt lgkmcnt(0)
	s_nop 1
	v_add_f32_dpp v3, v3, v3 row_half_mirror row_mask:0xf bank_mask:0xf
	s_waitcnt lgkmcnt(0)
	s_nop 1
	v_add_f32_dpp v3, v3, v3 row_mirror row_mask:0xf bank_mask:0xf
	v_mov_b32_e32 v6, v3
	s_nop 1
	v_permlane16_swap_b32_e32 v3, v6
	s_waitcnt lgkmcnt(0)
	v_add_f32_e32 v3, v3, v6
	v_fmamk_f32 v3, v3, 0x3c000000, v249
	v_mul_f32_e32 v6, 0x4b800000, v3
	v_cmp_gt_f32_e32 vcc, s10, v3
	s_nop 1
	v_cndmask_b32_e32 v3, v3, v6, vcc
	v_rsq_f32_e32 v3, v3
	s_nop 0
	v_mul_f32_e32 v6, 0x45800000, v3
	v_cndmask_b32_e32 v3, v3, v6, vcc
	v_mul_f32_e32 v4, v4, v3
	v_mul_f32_e32 v5, v5, v3
	v_mul_f32_e32 v6, v9, v3
	v_mul_f32_e32 v3, v8, v3
	v_mul_f32_e32 v4, v69, v4
	v_mul_f32_e32 v5, v71, v5
	v_mul_f32_e32 v6, v73, v6
	v_mul_f32_e32 v3, v77, v3
	v_cvt_pk_bf16_f32 v4, v4, s0
	v_cvt_pk_bf16_f32 v5, v5, s0
	v_cvt_pk_bf16_f32 v6, v6, s0
	v_cvt_pk_bf16_f32 v3, v3, s0
	ds_write_b16 v74, v4 offset:6528
	ds_write_b16 v74, v5 offset:6592
	ds_write_b16 v74, v6 offset:6656
	ds_write_b16 v74, v3 offset:6720
	ds_read2st64_b32 v[4:5], v79 offset0:26 offset1:27
	v_mov_b32_e32 v62, v15
	v_mov_b32_e32 v30, v47
	v_pk_mul_f32 v[10:11], v[30:31], v[68:69] op_sel_hi:[1,0]
	s_waitcnt lgkmcnt(0)
	v_lshlrev_b32_e32 v6, 16, v4
	v_and_b32_e32 v7, 0xffff0000, v4
	v_lshlrev_b32_e32 v9, 16, v5
	v_and_b32_e32 v8, 0xffff0000, v5
	v_pk_mul_f32 v[4:5], v[62:63], v[68:69] op_sel_hi:[1,0]
	v_pk_fma_f32 v[8:9], v[142:143], v[10:11], v[8:9] neg_lo:[1,0,0] neg_hi:[1,0,0]
	v_pk_fma_f32 v[4:5], v[142:143], v[4:5], v[6:7] neg_lo:[1,0,0] neg_hi:[1,0,0]
	v_pk_mul_f32 v[10:11], v[8:9], v[8:9]
	v_pk_mul_f32 v[6:7], v[4:5], v[4:5]
	s_nop 0
	v_add_f32_e32 v3, v6, v7
	v_add_f32_e32 v3, v3, v11
	v_add_f32_e32 v3, v10, v3
	s_waitcnt lgkmcnt(0)
	s_nop 1
	v_add_f32_dpp v3, v3, v3 quad_perm:[1,0,3,2] row_mask:0xf bank_mask:0xf
	s_waitcnt lgkmcnt(0)
	s_nop 1
	v_add_f32_dpp v3, v3, v3 quad_perm:[2,3,0,1] row_mask:0xf bank_mask:0xf
	s_waitcnt lgkmcnt(0)
	s_nop 1
	v_add_f32_dpp v3, v3, v3 row_half_mirror row_mask:0xf bank_mask:0xf
	s_waitcnt lgkmcnt(0)
	s_nop 1
	v_add_f32_dpp v3, v3, v3 row_mirror row_mask:0xf bank_mask:0xf
	v_mov_b32_e32 v6, v3
	s_nop 1
	v_permlane16_swap_b32_e32 v3, v6
	s_waitcnt lgkmcnt(0)
	v_add_f32_e32 v3, v3, v6
	v_fmamk_f32 v3, v3, 0x3c000000, v249
	v_mul_f32_e32 v6, 0x4b800000, v3
	v_cmp_gt_f32_e32 vcc, s10, v3
	s_nop 1
	v_cndmask_b32_e32 v3, v3, v6, vcc
	v_rsq_f32_e32 v3, v3
	s_nop 0
	v_mul_f32_e32 v6, 0x45800000, v3
	v_cndmask_b32_e32 v3, v3, v6, vcc
	v_mul_f32_e32 v4, v4, v3
	v_mul_f32_e32 v5, v5, v3
	v_mul_f32_e32 v6, v9, v3
	v_mul_f32_e32 v3, v8, v3
	v_mul_f32_e32 v4, v69, v4
	v_mul_f32_e32 v5, v71, v5
	v_mul_f32_e32 v6, v73, v6
	v_mul_f32_e32 v3, v77, v3
	v_cvt_pk_bf16_f32 v4, v4, s0
	v_cvt_pk_bf16_f32 v5, v5, s0
	v_cvt_pk_bf16_f32 v6, v6, s0
	v_cvt_pk_bf16_f32 v3, v3, s0
	ds_write_b16 v74, v4 offset:6800
	ds_write_b16 v74, v5 offset:6864
	ds_write_b16 v74, v6 offset:6928
	ds_write_b16 v74, v3 offset:6992
	ds_read2st64_b32 v[4:5], v79 offset0:28 offset1:29
	v_mov_b32_e32 v6, v16
	v_mov_b32_e32 v7, v64
	s_waitcnt lgkmcnt(0)
	v_lshlrev_b32_e32 v8, 16, v4
	v_and_b32_e32 v9, 0xffff0000, v4
	v_lshlrev_b32_e32 v11, 16, v5
	v_and_b32_e32 v10, 0xffff0000, v5
	v_pk_mul_f32 v[4:5], v[6:7], v[66:67] op_sel_hi:[1,0]
	s_nop 0
	v_pk_fma_f32 v[4:5], v[142:143], v[4:5], v[8:9] neg_lo:[1,0,0] neg_hi:[1,0,0]
	v_mov_b32_e32 v8, v48
	v_mov_b32_e32 v9, v32
	v_pk_mul_f32 v[8:9], v[8:9], v[66:67] op_sel_hi:[1,0]
	v_pk_mul_f32 v[6:7], v[4:5], v[4:5]
	v_pk_fma_f32 v[8:9], v[142:143], v[8:9], v[10:11] neg_lo:[1,0,0] neg_hi:[1,0,0]
	v_add_f32_e32 v3, v6, v7
	v_pk_mul_f32 v[10:11], v[8:9], v[8:9]
	s_nop 0
	v_add_f32_e32 v3, v3, v11
	v_add_f32_e32 v3, v10, v3
	s_waitcnt lgkmcnt(0)
	s_nop 1
	v_add_f32_dpp v3, v3, v3 quad_perm:[1,0,3,2] row_mask:0xf bank_mask:0xf
	s_waitcnt lgkmcnt(0)
	s_nop 1
	v_add_f32_dpp v3, v3, v3 quad_perm:[2,3,0,1] row_mask:0xf bank_mask:0xf
	s_waitcnt lgkmcnt(0)
	s_nop 1
	v_add_f32_dpp v3, v3, v3 row_half_mirror row_mask:0xf bank_mask:0xf
	s_waitcnt lgkmcnt(0)
	s_nop 1
	v_add_f32_dpp v3, v3, v3 row_mirror row_mask:0xf bank_mask:0xf
	v_mov_b32_e32 v6, v3
	s_nop 1
	v_permlane16_swap_b32_e32 v3, v6
	s_waitcnt lgkmcnt(0)
	v_add_f32_e32 v3, v3, v6
	v_fmamk_f32 v3, v3, 0x3c000000, v249
	v_mul_f32_e32 v6, 0x4b800000, v3
	v_cmp_gt_f32_e32 vcc, s10, v3
	s_nop 1
	v_cndmask_b32_e32 v3, v3, v6, vcc
	v_rsq_f32_e32 v3, v3
	s_nop 0
	v_mul_f32_e32 v6, 0x45800000, v3
	v_cndmask_b32_e32 v3, v3, v6, vcc
	v_mul_f32_e32 v4, v4, v3
	v_mul_f32_e32 v5, v5, v3
	v_mul_f32_e32 v6, v9, v3
	v_mul_f32_e32 v3, v8, v3
	v_mul_f32_e32 v4, v69, v4
	v_mul_f32_e32 v5, v71, v5
	v_mul_f32_e32 v6, v73, v6
	v_mul_f32_e32 v3, v77, v3
	v_cvt_pk_bf16_f32 v4, v4, s0
	v_cvt_pk_bf16_f32 v5, v5, s0
	v_cvt_pk_bf16_f32 v6, v6, s0
	v_cvt_pk_bf16_f32 v3, v3, s0
	ds_write_b16 v74, v4 offset:7072
	ds_write_b16 v74, v5 offset:7136
	ds_write_b16 v74, v6 offset:7200
	ds_write_b16 v74, v3 offset:7264
	ds_read2st64_b32 v[4:5], v79 offset0:30 offset1:31
	v_mov_b32_e32 v64, v17
	v_mov_b32_e32 v32, v49
	v_pk_mul_f32 v[10:11], v[32:33], v[0:1] op_sel_hi:[1,0]
	s_waitcnt lgkmcnt(0)
	v_lshlrev_b32_e32 v6, 16, v4
	v_and_b32_e32 v7, 0xffff0000, v4
	v_lshlrev_b32_e32 v9, 16, v5
	v_and_b32_e32 v8, 0xffff0000, v5
	v_pk_mul_f32 v[4:5], v[64:65], v[0:1] op_sel_hi:[1,0]
	v_pk_fma_f32 v[8:9], v[142:143], v[10:11], v[8:9] neg_lo:[1,0,0] neg_hi:[1,0,0]
	v_pk_fma_f32 v[4:5], v[142:143], v[4:5], v[6:7] neg_lo:[1,0,0] neg_hi:[1,0,0]
	v_pk_mul_f32 v[10:11], v[8:9], v[8:9]
	v_pk_mul_f32 v[6:7], v[4:5], v[4:5]
	s_nop 0
	v_add_f32_e32 v0, v6, v7
	v_add_f32_e32 v0, v0, v11
	v_add_f32_e32 v0, v10, v0
	s_waitcnt lgkmcnt(0)
	s_nop 1
	v_add_f32_dpp v0, v0, v0 quad_perm:[1,0,3,2] row_mask:0xf bank_mask:0xf
	s_waitcnt lgkmcnt(0)
	s_nop 1
	v_add_f32_dpp v0, v0, v0 quad_perm:[2,3,0,1] row_mask:0xf bank_mask:0xf
	s_waitcnt lgkmcnt(0)
	s_nop 1
	v_add_f32_dpp v0, v0, v0 row_half_mirror row_mask:0xf bank_mask:0xf
	s_waitcnt lgkmcnt(0)
	s_nop 1
	v_add_f32_dpp v0, v0, v0 row_mirror row_mask:0xf bank_mask:0xf
	v_mov_b32_e32 v3, v0
	s_nop 1
	v_permlane16_swap_b32_e32 v0, v3
	s_waitcnt lgkmcnt(0)
	v_add_f32_e32 v0, v0, v3
	v_fmamk_f32 v0, v0, 0x3c000000, v249
	v_mul_f32_e32 v3, 0x4b800000, v0
	v_cmp_gt_f32_e32 vcc, s10, v0
	s_nop 1
	v_cndmask_b32_e32 v0, v0, v3, vcc
	v_rsq_f32_e32 v0, v0
	s_nop 0
	v_mul_f32_e32 v3, 0x45800000, v0
	v_cndmask_b32_e32 v0, v0, v3, vcc
	v_mul_f32_e32 v3, v4, v0
	v_mul_f32_e32 v4, v5, v0
	v_mul_f32_e32 v5, v9, v0
	v_mul_f32_e32 v0, v8, v0
	v_mul_f32_e32 v3, v69, v3
	v_mul_f32_e32 v4, v71, v4
	v_mul_f32_e32 v5, v73, v5
	v_mul_f32_e32 v0, v77, v0
	v_cvt_pk_bf16_f32 v3, v3, s0
	v_cvt_pk_bf16_f32 v4, v4, s0
	v_cvt_pk_bf16_f32 v5, v5, s0
	v_cvt_pk_bf16_f32 v0, v0, s0
	ds_write_b16 v2, v3 offset:6528
	ds_write_b16 v2, v4 offset:6592
	ds_write_b16 v2, v5 offset:6656
	ds_write_b16 v2, v0 offset:6720
	s_add_i32 s4, s1, s60
	s_ashr_i32 s5, s4, 31
	s_lshl_b64 s[4:5], s[4:5], 11
	s_add_u32 s1, s41, s4
	s_addc_u32 s5, s66, s5
	s_add_u32 s4, s1, s61
	v_ashrrev_i32_e32 v6, 4, v172
	v_lshlrev_b32_e32 v0, 4, v172
	s_addc_u32 s5, s5, 0
	v_and_b32_e32 v0, 0xf0, v0
	v_mul_lo_u32 v2, v6, s77
	s_waitcnt lgkmcnt(0)
	v_lshl_add_u64 v[8:9], s[4:5], 0, v[0:1]
	v_add3_u32 v0, v67, v0, v2
	ds_read_b128 v[2:5], v0
	v_ashrrev_i32_e32 v7, 31, v6
	v_lshlrev_b64 v[6:7], 11, v[6:7]
	v_lshl_add_u64 v[6:7], v[8:9], 0, v[6:7]
	v_add_co_u32_e32 v8, vcc, s88, v6
	s_waitcnt lgkmcnt(0)
	global_store_dwordx4 v[6:7], v[2:5], off
	ds_read_b128 v[2:5], v0 offset:1088
	v_addc_co_u32_e32 v9, vcc, 0, v7, vcc
	v_readlane_b32 s1, v253, 61
	s_add_i32 s68, s68, s1
	s_waitcnt lgkmcnt(0)
	global_store_dwordx4 v[8:9], v[2:5], off
	ds_read_b128 v[2:5], v0 offset:2176
	v_add_co_u32_e32 v8, vcc, s14, v6
	v_readlane_b32 s1, v253, 63
	s_nop 0
	v_addc_co_u32_e32 v9, vcc, 0, v7, vcc
	s_waitcnt lgkmcnt(0)
	global_store_dwordx4 v[8:9], v[2:5], off
	ds_read_b128 v[2:5], v0 offset:3264
	v_add_co_u32_e32 v8, vcc, s89, v6
	s_add_i32 s69, s69, s90
	s_nop 0
	v_addc_co_u32_e32 v9, vcc, 0, v7, vcc
	s_waitcnt lgkmcnt(0)
	global_store_dwordx4 v[8:9], v[2:5], off
	ds_read_b128 v[2:5], v0 offset:4352
	v_add_co_u32_e32 v8, vcc, s81, v6
	s_add_i32 s67, s67, s1
	s_nop 0
	v_addc_co_u32_e32 v9, vcc, 0, v7, vcc
	s_waitcnt lgkmcnt(0)
	global_store_dwordx4 v[8:9], v[2:5], off
	ds_read_b128 v[2:5], v0 offset:5440
	v_add_co_u32_e32 v8, vcc, s20, v6
	s_cmpk_gt_i32 s69, 0xff
	s_nop 0
	v_addc_co_u32_e32 v9, vcc, 0, v7, vcc
	s_waitcnt lgkmcnt(0)
	global_store_dwordx4 v[8:9], v[2:5], off
	ds_read_b128 v[2:5], v0 offset:6528
	v_add_co_u32_e32 v8, vcc, s18, v6
	s_nop 1
	v_addc_co_u32_e32 v9, vcc, 0, v7, vcc
	s_waitcnt lgkmcnt(0)
	global_store_dwordx4 v[8:9], v[2:5], off
	ds_read_b128 v[2:5], v0 offset:7616
	v_add_co_u32_e32 v6, vcc, 0xe000, v6
	s_nop 1
	v_addc_co_u32_e32 v7, vcc, 0, v7, vcc
	s_waitcnt lgkmcnt(0)
	global_store_dwordx4 v[6:7], v[2:5], off
	s_barrier
	s_cbranch_scc1 .LBB0_94

.LBB0_64:
	v_readlane_b32 s4, v255, 34
	v_readlane_b32 s5, v255, 35
	s_load_dwordx2 s[50:51], s[4:5], 0xb0
	v_rcp_f32_e32 v94, v69
	v_lshlrev_b32_e32 v69, 2, v145
	v_rcp_f32_e32 v98, v67
	v_rcp_f32_e32 v90, v71
	v_rcp_f32_e32 v86, v73
	s_waitcnt lgkmcnt(0)
	global_load_dword v67, v69, s[50:51]
	global_load_dword v71, v69, s[50:51] offset:128
	global_load_dword v73, v69, s[50:51] offset:256
	v_readlane_b32 s4, v251, 48
	global_load_dword v69, v69, s[50:51] offset:384
	v_rcp_f32_e32 v82, v75
	v_rcp_f32_e32 v96, v68
	v_rcp_f32_e32 v68, v79
	v_rcp_f32_e32 v88, v72
	v_rcp_f32_e32 v84, v74
	v_rcp_f32_e32 v74, v76
	v_rcp_f32_e32 v72, v77
	v_rcp_f32_e32 v100, v66
	v_mov_b32_e32 v106, v34
	v_mov_b32_e32 v107, v18
	s_mov_b32 s5, 0x800000
	v_rcp_f32_e32 v66, v80
	v_ashrrev_i32_e32 v80, 3, v162
	v_rcp_f32_e32 v92, v70
	v_rcp_f32_e32 v70, v78
	v_rcp_f32_e32 v0, v81
	v_and_b32_e32 v81, 0xffffffc, v80
	s_and_b32 s10, s67, 0x700
	s_addk_i32 s10, 0x100
	s_waitcnt vmcnt(3)
	v_mul_f32_e32 v67, 0x3f24fd5c, v67
	s_waitcnt vmcnt(2)
	v_mul_f32_e32 v71, 0x3f24fd5c, v71
	s_waitcnt vmcnt(1)
	v_mul_f32_e32 v73, 0x3f24fd5c, v73
	s_waitcnt vmcnt(0)
	v_mul_f32_e32 v75, 0x3f24fd5c, v69
	v_mov_b32_e32 v69, s4
	s_mov_b32 s4, 1
	v_add_u32_e32 v79, 0, v160
	ds_read2st64_b32 v[76:77], v79 offset1:1
	v_add_u32_e32 v69, 0, v69
	v_lshl_add_u32 v78, v145, 1, v69
	s_waitcnt lgkmcnt(0)
	v_lshlrev_b32_e32 v102, 16, v76
	v_and_b32_e32 v103, 0xffff0000, v76
	v_lshlrev_b32_e32 v105, 16, v77
	v_and_b32_e32 v104, 0xffff0000, v77
	v_mov_b32_e32 v76, v2
	v_mov_b32_e32 v77, v50
	v_pk_mul_f32 v[76:77], v[76:77], v[100:101] op_sel_hi:[1,0]
	v_pk_mul_f32 v[100:101], v[106:107], v[100:101] op_sel_hi:[1,0]
	v_pk_fma_f32 v[102:103], v[142:143], v[76:77], v[102:103] neg_lo:[1,0,0] neg_hi:[1,0,0]
	v_pk_fma_f32 v[100:101], v[142:143], v[100:101], v[104:105] neg_lo:[1,0,0] neg_hi:[1,0,0]
	v_pk_mul_f32 v[76:77], v[102:103], v[102:103]
	v_pk_mul_f32 v[104:105], v[100:101], v[100:101]
	v_add_f32_e32 v2, v76, v77
	v_add_f32_e32 v2, v2, v105
	v_add_f32_e32 v2, v104, v2
	v_mad_u64_u32 v[76:77], s[22:23], v81, s77, v[78:79]
	s_waitcnt lgkmcnt(0)
	s_nop 1
	v_add_f32_dpp v2, v2, v2 quad_perm:[1,0,3,2] row_mask:0xf bank_mask:0xf
	s_waitcnt lgkmcnt(0)
	s_nop 1
	v_add_f32_dpp v2, v2, v2 quad_perm:[2,3,0,1] row_mask:0xf bank_mask:0xf
	s_waitcnt lgkmcnt(0)
	s_nop 1
	v_add_f32_dpp v2, v2, v2 row_half_mirror row_mask:0xf bank_mask:0xf
	s_waitcnt lgkmcnt(0)
	s_nop 1
	v_add_f32_dpp v2, v2, v2 row_mirror row_mask:0xf bank_mask:0xf
	v_mov_b32_e32 v18, v2
	s_nop 1
	v_permlane16_swap_b32_e32 v2, v18
	s_waitcnt lgkmcnt(0)
	v_add_f32_e32 v2, v2, v18
	v_fmamk_f32 v2, v2, 0x3c000000, v249
	v_cmp_gt_f32_e32 vcc, s5, v2
	v_mul_f32_e32 v18, 0x4b800000, v2
	s_nop 0
	v_cndmask_b32_e32 v2, v2, v18, vcc
	v_rsq_f32_e32 v2, v2
	s_nop 0
	v_mul_f32_e32 v18, 0x45800000, v2
	v_cndmask_b32_e32 v2, v2, v18, vcc
	v_mul_f32_e32 v18, v102, v2
	v_mul_f32_e32 v18, v67, v18
	v_cvt_pk_bf16_f32 v18, v18, s0
	ds_write_b16 v76, v18
	v_mul_f32_e32 v18, v103, v2
	v_mul_f32_e32 v18, v71, v18
	v_cvt_pk_bf16_f32 v18, v18, s0
	ds_write_b16 v76, v18 offset:64
	v_mul_f32_e32 v18, v101, v2
	v_mul_f32_e32 v2, v100, v2
	v_mul_f32_e32 v18, v73, v18
	v_mul_f32_e32 v2, v75, v2
	v_cvt_pk_bf16_f32 v18, v18, s0
	v_cvt_pk_bf16_f32 v2, v2, s0
	ds_write_b16 v76, v18 offset:128
	ds_write_b16 v76, v2 offset:192
	ds_read2st64_b32 v[100:101], v79 offset0:2 offset1:3
	v_mov_b32_e32 v50, v3
	v_pk_mul_f32 v[50:51], v[50:51], v[98:99] op_sel_hi:[1,0]
	v_mov_b32_e32 v18, v35
	v_pk_mul_f32 v[18:19], v[18:19], v[98:99] op_sel_hi:[1,0]
	s_waitcnt lgkmcnt(0)
	v_lshlrev_b32_e32 v2, 16, v100
	v_and_b32_e32 v3, 0xffff0000, v100
	v_lshlrev_b32_e32 v103, 16, v101
	v_and_b32_e32 v102, 0xffff0000, v101
	v_pk_fma_f32 v[2:3], v[142:143], v[50:51], v[2:3] neg_lo:[1,0,0] neg_hi:[1,0,0]
	v_pk_fma_f32 v[18:19], v[142:143], v[18:19], v[102:103] neg_lo:[1,0,0] neg_hi:[1,0,0]
	v_pk_mul_f32 v[50:51], v[2:3], v[2:3]
	v_pk_mul_f32 v[34:35], v[18:19], v[18:19]
	v_add_f32_e32 v50, v50, v51
	v_add_f32_e32 v35, v50, v35
	v_add_f32_e32 v34, v34, v35
	s_waitcnt lgkmcnt(0)
	s_nop 1
	v_add_f32_dpp v34, v34, v34 quad_perm:[1,0,3,2] row_mask:0xf bank_mask:0xf
	s_waitcnt lgkmcnt(0)
	s_nop 1
	v_add_f32_dpp v34, v34, v34 quad_perm:[2,3,0,1] row_mask:0xf bank_mask:0xf
	s_waitcnt lgkmcnt(0)
	s_nop 1
	v_add_f32_dpp v34, v34, v34 row_half_mirror row_mask:0xf bank_mask:0xf
	s_waitcnt lgkmcnt(0)
	s_nop 1
	v_add_f32_dpp v34, v34, v34 row_mirror row_mask:0xf bank_mask:0xf
	v_mov_b32_e32 v35, v34
	s_nop 1
	v_permlane16_swap_b32_e32 v34, v35
	s_waitcnt lgkmcnt(0)
	v_add_f32_e32 v34, v34, v35
	v_fmamk_f32 v34, v34, 0x3c000000, v249
	v_mul_f32_e32 v35, 0x4b800000, v34
	v_cmp_gt_f32_e32 vcc, s5, v34
	s_nop 1
	v_cndmask_b32_e32 v34, v34, v35, vcc
	v_rsq_f32_e32 v34, v34
	s_nop 0
	v_mul_f32_e32 v35, 0x45800000, v34
	v_cndmask_b32_e32 v34, v34, v35, vcc
	v_mul_f32_e32 v2, v2, v34
	v_mul_f32_e32 v3, v3, v34
	v_mul_f32_e32 v19, v19, v34
	v_mul_f32_e32 v18, v18, v34
	v_mul_f32_e32 v2, v67, v2
	v_mul_f32_e32 v3, v71, v3
	v_mul_f32_e32 v19, v73, v19
	v_mul_f32_e32 v18, v75, v18
	v_cvt_pk_bf16_f32 v2, v2, s0
	v_cvt_pk_bf16_f32 v3, v3, s0
	v_cvt_pk_bf16_f32 v19, v19, s0
	v_cvt_pk_bf16_f32 v18, v18, s0
	ds_write_b16 v76, v2 offset:272
	ds_write_b16 v76, v3 offset:336
	ds_write_b16 v76, v19 offset:400
	ds_write_b16 v76, v18 offset:464
	ds_read2st64_b32 v[2:3], v79 offset0:4 offset1:5
	v_mov_b32_e32 v18, v4
	v_mov_b32_e32 v19, v52
	s_waitcnt lgkmcnt(0)
	v_lshlrev_b32_e32 v34, 16, v2
	v_and_b32_e32 v35, 0xffff0000, v2
	v_lshlrev_b32_e32 v51, 16, v3
	v_and_b32_e32 v50, 0xffff0000, v3
	v_pk_mul_f32 v[2:3], v[18:19], v[96:97] op_sel_hi:[1,0]
	s_nop 0
	v_pk_fma_f32 v[2:3], v[142:143], v[2:3], v[34:35] neg_lo:[1,0,0] neg_hi:[1,0,0]
	v_mov_b32_e32 v34, v36
	v_mov_b32_e32 v35, v20
	v_pk_mul_f32 v[34:35], v[34:35], v[96:97] op_sel_hi:[1,0]
	v_pk_mul_f32 v[18:19], v[2:3], v[2:3]
	v_pk_fma_f32 v[34:35], v[142:143], v[34:35], v[50:51] neg_lo:[1,0,0] neg_hi:[1,0,0]
	v_add_f32_e32 v4, v18, v19
	v_pk_mul_f32 v[50:51], v[34:35], v[34:35]
	s_nop 0
	v_add_f32_e32 v4, v4, v51
	v_add_f32_e32 v4, v50, v4
	s_waitcnt lgkmcnt(0)
	s_nop 1
	v_add_f32_dpp v4, v4, v4 quad_perm:[1,0,3,2] row_mask:0xf bank_mask:0xf
	s_waitcnt lgkmcnt(0)
	s_nop 1
	v_add_f32_dpp v4, v4, v4 quad_perm:[2,3,0,1] row_mask:0xf bank_mask:0xf
	s_waitcnt lgkmcnt(0)
	s_nop 1
	v_add_f32_dpp v4, v4, v4 row_half_mirror row_mask:0xf bank_mask:0xf
	s_waitcnt lgkmcnt(0)
	s_nop 1
	v_add_f32_dpp v4, v4, v4 row_mirror row_mask:0xf bank_mask:0xf
	v_mov_b32_e32 v18, v4
	s_nop 1
	v_permlane16_swap_b32_e32 v4, v18
	s_waitcnt lgkmcnt(0)
	v_add_f32_e32 v4, v4, v18
	v_fmamk_f32 v4, v4, 0x3c000000, v249
	v_mul_f32_e32 v18, 0x4b800000, v4
	v_cmp_gt_f32_e32 vcc, s5, v4
	s_nop 1
	v_cndmask_b32_e32 v4, v4, v18, vcc
	v_rsq_f32_e32 v4, v4
	s_nop 0
	v_mul_f32_e32 v18, 0x45800000, v4
	v_cndmask_b32_e32 v4, v4, v18, vcc
	v_mul_f32_e32 v2, v2, v4
	v_mul_f32_e32 v3, v3, v4
	v_mul_f32_e32 v18, v35, v4
	v_mul_f32_e32 v4, v34, v4
	v_mul_f32_e32 v2, v67, v2
	v_mul_f32_e32 v3, v71, v3
	v_mul_f32_e32 v18, v73, v18
	v_mul_f32_e32 v4, v75, v4
	v_cvt_pk_bf16_f32 v2, v2, s0
	v_cvt_pk_bf16_f32 v3, v3, s0
	v_cvt_pk_bf16_f32 v18, v18, s0
	v_cvt_pk_bf16_f32 v4, v4, s0
	ds_write_b16 v76, v2 offset:544
	ds_write_b16 v76, v3 offset:608
	ds_write_b16 v76, v18 offset:672
	ds_write_b16 v76, v4 offset:736
	ds_read2st64_b32 v[2:3], v79 offset0:6 offset1:7
	v_mov_b32_e32 v52, v5
	v_mov_b32_e32 v20, v37
	s_waitcnt lgkmcnt(0)
	v_lshlrev_b32_e32 v18, 16, v2
	v_and_b32_e32 v19, 0xffff0000, v2
	v_lshlrev_b32_e32 v35, 16, v3
	v_and_b32_e32 v34, 0xffff0000, v3
	v_pk_mul_f32 v[2:3], v[52:53], v[94:95] op_sel_hi:[1,0]
	s_nop 0
	v_pk_fma_f32 v[4:5], v[142:143], v[2:3], v[18:19] neg_lo:[1,0,0] neg_hi:[1,0,0]
	v_pk_mul_f32 v[18:19], v[20:21], v[94:95] op_sel_hi:[1,0]
	v_pk_mul_f32 v[2:3], v[4:5], v[4:5]
	v_pk_fma_f32 v[18:19], v[142:143], v[18:19], v[34:35] neg_lo:[1,0,0] neg_hi:[1,0,0]
	v_add_f32_e32 v2, v2, v3
	v_pk_mul_f32 v[20:21], v[18:19], v[18:19]
	s_nop 0
	v_add_f32_e32 v2, v2, v21
	v_add_f32_e32 v2, v20, v2
	s_waitcnt lgkmcnt(0)
	s_nop 1
	v_add_f32_dpp v2, v2, v2 quad_perm:[1,0,3,2] row_mask:0xf bank_mask:0xf
	s_waitcnt lgkmcnt(0)
	s_nop 1
	v_add_f32_dpp v2, v2, v2 quad_perm:[2,3,0,1] row_mask:0xf bank_mask:0xf
	s_waitcnt lgkmcnt(0)
	s_nop 1
	v_add_f32_dpp v2, v2, v2 row_half_mirror row_mask:0xf bank_mask:0xf
	s_waitcnt lgkmcnt(0)
	s_nop 1
	v_add_f32_dpp v2, v2, v2 row_mirror row_mask:0xf bank_mask:0xf
	v_mov_b32_e32 v3, v2
	s_nop 1
	v_permlane16_swap_b32_e32 v2, v3
	s_waitcnt lgkmcnt(0)
	v_add_f32_e32 v2, v2, v3
	v_fmamk_f32 v2, v2, 0x3c000000, v249
	v_cmp_gt_f32_e32 vcc, s5, v2
	v_mul_f32_e32 v3, 0x4b800000, v2
	s_nop 0
	v_cndmask_b32_e32 v2, v2, v3, vcc
	v_rsq_f32_e32 v2, v2
	s_nop 0
	v_mul_f32_e32 v3, 0x45800000, v2
	v_cndmask_b32_e32 v20, v2, v3, vcc
	v_or_b32_e32 v2, 3, v80
	v_mad_u64_u32 v[2:3], s[22:23], v2, s77, v[78:79]
	v_mul_f32_e32 v3, v4, v20
	v_mul_f32_e32 v3, v67, v3
	v_cvt_pk_bf16_f32 v3, v3, s0
	ds_write_b16 v2, v3
	v_mul_f32_e32 v3, v5, v20
	v_mul_f32_e32 v3, v71, v3
	v_cvt_pk_bf16_f32 v3, v3, s0
	ds_write_b16 v2, v3 offset:64
	v_mul_f32_e32 v3, v19, v20
	v_mul_f32_e32 v3, v73, v3
	v_cvt_pk_bf16_f32 v3, v3, s0
	ds_write_b16 v2, v3 offset:128
	v_mul_f32_e32 v3, v18, v20
	v_mul_f32_e32 v3, v75, v3
	v_cvt_pk_bf16_f32 v3, v3, s0
	ds_write_b16 v2, v3 offset:192
	ds_read2st64_b32 v[4:5], v79 offset0:8 offset1:9
	v_mov_b32_e32 v18, v6
	v_mov_b32_e32 v19, v54
	s_waitcnt lgkmcnt(0)
	v_lshlrev_b32_e32 v20, 16, v4
	v_and_b32_e32 v21, 0xffff0000, v4
	v_lshlrev_b32_e32 v35, 16, v5
	v_and_b32_e32 v34, 0xffff0000, v5
	v_pk_mul_f32 v[4:5], v[18:19], v[92:93] op_sel_hi:[1,0]
	s_nop 0
	v_pk_fma_f32 v[4:5], v[142:143], v[4:5], v[20:21] neg_lo:[1,0,0] neg_hi:[1,0,0]
	v_mov_b32_e32 v20, v38
	v_mov_b32_e32 v21, v22
	v_pk_mul_f32 v[20:21], v[20:21], v[92:93] op_sel_hi:[1,0]
	v_pk_mul_f32 v[18:19], v[4:5], v[4:5]
	v_pk_fma_f32 v[20:21], v[142:143], v[20:21], v[34:35] neg_lo:[1,0,0] neg_hi:[1,0,0]
	v_add_f32_e32 v3, v18, v19
	v_pk_mul_f32 v[34:35], v[20:21], v[20:21]
	s_nop 0
	v_add_f32_e32 v3, v3, v35
	v_add_f32_e32 v3, v34, v3
	s_waitcnt lgkmcnt(0)
	s_nop 1
	v_add_f32_dpp v3, v3, v3 quad_perm:[1,0,3,2] row_mask:0xf bank_mask:0xf
	s_waitcnt lgkmcnt(0)
	s_nop 1
	v_add_f32_dpp v3, v3, v3 quad_perm:[2,3,0,1] row_mask:0xf bank_mask:0xf
	s_waitcnt lgkmcnt(0)
	s_nop 1
	v_add_f32_dpp v3, v3, v3 row_half_mirror row_mask:0xf bank_mask:0xf
	s_waitcnt lgkmcnt(0)
	s_nop 1
	v_add_f32_dpp v3, v3, v3 row_mirror row_mask:0xf bank_mask:0xf
	v_mov_b32_e32 v6, v3
	s_nop 1
	v_permlane16_swap_b32_e32 v3, v6
	s_waitcnt lgkmcnt(0)
	v_add_f32_e32 v3, v3, v6
	v_fmamk_f32 v3, v3, 0x3c000000, v249
	v_mul_f32_e32 v6, 0x4b800000, v3
	v_cmp_gt_f32_e32 vcc, s5, v3
	s_nop 1
	v_cndmask_b32_e32 v3, v3, v6, vcc
	v_rsq_f32_e32 v3, v3
	s_nop 0
	v_mul_f32_e32 v6, 0x45800000, v3
	v_cndmask_b32_e32 v3, v3, v6, vcc
	v_mul_f32_e32 v4, v4, v3
	v_mul_f32_e32 v5, v5, v3
	v_mul_f32_e32 v6, v21, v3
	v_mul_f32_e32 v3, v20, v3
	v_mul_f32_e32 v4, v67, v4
	v_mul_f32_e32 v5, v71, v5
	v_mul_f32_e32 v6, v73, v6
	v_mul_f32_e32 v3, v75, v3
	v_cvt_pk_bf16_f32 v4, v4, s0
	v_cvt_pk_bf16_f32 v5, v5, s0
	v_cvt_pk_bf16_f32 v6, v6, s0
	v_cvt_pk_bf16_f32 v3, v3, s0
	ds_write_b16 v76, v4 offset:2176
	ds_write_b16 v76, v5 offset:2240
	ds_write_b16 v76, v6 offset:2304
	ds_write_b16 v76, v3 offset:2368
	ds_read2st64_b32 v[4:5], v79 offset0:10 offset1:11
	v_mov_b32_e32 v54, v7
	v_mov_b32_e32 v22, v39
	v_pk_mul_f32 v[20:21], v[22:23], v[90:91] op_sel_hi:[1,0]
	s_waitcnt lgkmcnt(0)
	v_lshlrev_b32_e32 v6, 16, v4
	v_and_b32_e32 v7, 0xffff0000, v4
	v_lshlrev_b32_e32 v19, 16, v5
	v_and_b32_e32 v18, 0xffff0000, v5
	v_pk_mul_f32 v[4:5], v[54:55], v[90:91] op_sel_hi:[1,0]
	v_pk_fma_f32 v[18:19], v[142:143], v[20:21], v[18:19] neg_lo:[1,0,0] neg_hi:[1,0,0]
	v_pk_fma_f32 v[4:5], v[142:143], v[4:5], v[6:7] neg_lo:[1,0,0] neg_hi:[1,0,0]
	v_pk_mul_f32 v[20:21], v[18:19], v[18:19]
	v_pk_mul_f32 v[6:7], v[4:5], v[4:5]
	s_nop 0
	v_add_f32_e32 v3, v6, v7
	v_add_f32_e32 v3, v3, v21
	v_add_f32_e32 v3, v20, v3
	s_waitcnt lgkmcnt(0)
	s_nop 1
	v_add_f32_dpp v3, v3, v3 quad_perm:[1,0,3,2] row_mask:0xf bank_mask:0xf
	s_waitcnt lgkmcnt(0)
	s_nop 1
	v_add_f32_dpp v3, v3, v3 quad_perm:[2,3,0,1] row_mask:0xf bank_mask:0xf
	s_waitcnt lgkmcnt(0)
	s_nop 1
	v_add_f32_dpp v3, v3, v3 row_half_mirror row_mask:0xf bank_mask:0xf
	s_waitcnt lgkmcnt(0)
	s_nop 1
	v_add_f32_dpp v3, v3, v3 row_mirror row_mask:0xf bank_mask:0xf
	v_mov_b32_e32 v6, v3
	s_nop 1
	v_permlane16_swap_b32_e32 v3, v6
	s_waitcnt lgkmcnt(0)
	v_add_f32_e32 v3, v3, v6
	v_fmamk_f32 v3, v3, 0x3c000000, v249
	v_mul_f32_e32 v6, 0x4b800000, v3
	v_cmp_gt_f32_e32 vcc, s5, v3
	s_nop 1
	v_cndmask_b32_e32 v3, v3, v6, vcc
	v_rsq_f32_e32 v3, v3
	s_nop 0
	v_mul_f32_e32 v6, 0x45800000, v3
	v_cndmask_b32_e32 v3, v3, v6, vcc
	v_mul_f32_e32 v4, v4, v3
	v_mul_f32_e32 v5, v5, v3
	v_mul_f32_e32 v6, v19, v3
	v_mul_f32_e32 v3, v18, v3
	v_mul_f32_e32 v4, v67, v4
	v_mul_f32_e32 v5, v71, v5
	v_mul_f32_e32 v6, v73, v6
	v_mul_f32_e32 v3, v75, v3
	v_cvt_pk_bf16_f32 v4, v4, s0
	v_cvt_pk_bf16_f32 v5, v5, s0
	v_cvt_pk_bf16_f32 v6, v6, s0
	v_cvt_pk_bf16_f32 v3, v3, s0
	ds_write_b16 v76, v4 offset:2448
	ds_write_b16 v76, v5 offset:2512
	ds_write_b16 v76, v6 offset:2576
	ds_write_b16 v76, v3 offset:2640
	ds_read2st64_b32 v[4:5], v79 offset0:12 offset1:13
	v_mov_b32_e32 v6, v8
	v_mov_b32_e32 v7, v56
	s_waitcnt lgkmcnt(0)
	v_lshlrev_b32_e32 v18, 16, v4
	v_and_b32_e32 v19, 0xffff0000, v4
	v_lshlrev_b32_e32 v21, 16, v5
	v_and_b32_e32 v20, 0xffff0000, v5
	v_pk_mul_f32 v[4:5], v[6:7], v[88:89] op_sel_hi:[1,0]
	s_nop 0
	v_pk_fma_f32 v[4:5], v[142:143], v[4:5], v[18:19] neg_lo:[1,0,0] neg_hi:[1,0,0]
	v_mov_b32_e32 v18, v40
	v_mov_b32_e32 v19, v24
	v_pk_mul_f32 v[18:19], v[18:19], v[88:89] op_sel_hi:[1,0]
	v_pk_mul_f32 v[6:7], v[4:5], v[4:5]
	v_pk_fma_f32 v[18:19], v[142:143], v[18:19], v[20:21] neg_lo:[1,0,0] neg_hi:[1,0,0]
	v_add_f32_e32 v3, v6, v7
	v_pk_mul_f32 v[20:21], v[18:19], v[18:19]
	s_nop 0
	v_add_f32_e32 v3, v3, v21
	v_add_f32_e32 v3, v20, v3
	s_waitcnt lgkmcnt(0)
	s_nop 1
	v_add_f32_dpp v3, v3, v3 quad_perm:[1,0,3,2] row_mask:0xf bank_mask:0xf
	s_waitcnt lgkmcnt(0)
	s_nop 1
	v_add_f32_dpp v3, v3, v3 quad_perm:[2,3,0,1] row_mask:0xf bank_mask:0xf
	s_waitcnt lgkmcnt(0)
	s_nop 1
	v_add_f32_dpp v3, v3, v3 row_half_mirror row_mask:0xf bank_mask:0xf
	s_waitcnt lgkmcnt(0)
	s_nop 1
	v_add_f32_dpp v3, v3, v3 row_mirror row_mask:0xf bank_mask:0xf
	v_mov_b32_e32 v6, v3
	s_nop 1
	v_permlane16_swap_b32_e32 v3, v6
	s_waitcnt lgkmcnt(0)
	v_add_f32_e32 v3, v3, v6
	v_fmamk_f32 v3, v3, 0x3c000000, v249
	v_mul_f32_e32 v6, 0x4b800000, v3
	v_cmp_gt_f32_e32 vcc, s5, v3
	s_nop 1
	v_cndmask_b32_e32 v3, v3, v6, vcc
	v_rsq_f32_e32 v3, v3
	s_nop 0
	v_mul_f32_e32 v6, 0x45800000, v3
	v_cndmask_b32_e32 v3, v3, v6, vcc
	v_mul_f32_e32 v4, v4, v3
	v_mul_f32_e32 v5, v5, v3
	v_mul_f32_e32 v6, v19, v3
	v_mul_f32_e32 v3, v18, v3
	v_mul_f32_e32 v4, v67, v4
	v_mul_f32_e32 v5, v71, v5
	v_mul_f32_e32 v6, v73, v6
	v_mul_f32_e32 v3, v75, v3
	v_cvt_pk_bf16_f32 v4, v4, s0
	v_cvt_pk_bf16_f32 v5, v5, s0
	v_cvt_pk_bf16_f32 v6, v6, s0
	v_cvt_pk_bf16_f32 v3, v3, s0
	ds_write_b16 v76, v4 offset:2720
	ds_write_b16 v76, v5 offset:2784
	ds_write_b16 v76, v6 offset:2848
	ds_write_b16 v76, v3 offset:2912
	ds_read2st64_b32 v[4:5], v79 offset0:14 offset1:15
	v_mov_b32_e32 v56, v9
	v_mov_b32_e32 v24, v41
	v_pk_mul_f32 v[18:19], v[24:25], v[86:87] op_sel_hi:[1,0]
	s_waitcnt lgkmcnt(0)
	v_lshlrev_b32_e32 v6, 16, v4
	v_and_b32_e32 v7, 0xffff0000, v4
	v_lshlrev_b32_e32 v9, 16, v5
	v_and_b32_e32 v8, 0xffff0000, v5
	v_pk_mul_f32 v[4:5], v[56:57], v[86:87] op_sel_hi:[1,0]
	v_pk_fma_f32 v[8:9], v[142:143], v[18:19], v[8:9] neg_lo:[1,0,0] neg_hi:[1,0,0]
	v_pk_fma_f32 v[4:5], v[142:143], v[4:5], v[6:7] neg_lo:[1,0,0] neg_hi:[1,0,0]
	v_pk_mul_f32 v[18:19], v[8:9], v[8:9]
	v_pk_mul_f32 v[6:7], v[4:5], v[4:5]
	s_nop 0
	v_add_f32_e32 v3, v6, v7
	v_add_f32_e32 v3, v3, v19
	v_add_f32_e32 v3, v18, v3
	s_waitcnt lgkmcnt(0)
	s_nop 1
	v_add_f32_dpp v3, v3, v3 quad_perm:[1,0,3,2] row_mask:0xf bank_mask:0xf
	s_waitcnt lgkmcnt(0)
	s_nop 1
	v_add_f32_dpp v3, v3, v3 quad_perm:[2,3,0,1] row_mask:0xf bank_mask:0xf
	s_waitcnt lgkmcnt(0)
	s_nop 1
	v_add_f32_dpp v3, v3, v3 row_half_mirror row_mask:0xf bank_mask:0xf
	s_waitcnt lgkmcnt(0)
	s_nop 1
	v_add_f32_dpp v3, v3, v3 row_mirror row_mask:0xf bank_mask:0xf
	v_mov_b32_e32 v6, v3
	s_nop 1
	v_permlane16_swap_b32_e32 v3, v6
	s_waitcnt lgkmcnt(0)
	v_add_f32_e32 v3, v3, v6
	v_fmamk_f32 v3, v3, 0x3c000000, v249
	v_mul_f32_e32 v6, 0x4b800000, v3
	v_cmp_gt_f32_e32 vcc, s5, v3
	s_nop 1
	v_cndmask_b32_e32 v3, v3, v6, vcc
	v_rsq_f32_e32 v3, v3
	s_nop 0
	v_mul_f32_e32 v6, 0x45800000, v3
	v_cndmask_b32_e32 v3, v3, v6, vcc
	v_mul_f32_e32 v4, v4, v3
	v_mul_f32_e32 v5, v5, v3
	v_mul_f32_e32 v6, v9, v3
	v_mul_f32_e32 v3, v8, v3
	v_mul_f32_e32 v4, v67, v4
	v_mul_f32_e32 v5, v71, v5
	v_mul_f32_e32 v6, v73, v6
	v_mul_f32_e32 v3, v75, v3
	v_cvt_pk_bf16_f32 v4, v4, s0
	v_cvt_pk_bf16_f32 v5, v5, s0
	v_cvt_pk_bf16_f32 v6, v6, s0
	v_cvt_pk_bf16_f32 v3, v3, s0
	ds_write_b16 v2, v4 offset:2176
	ds_write_b16 v2, v5 offset:2240
	ds_write_b16 v2, v6 offset:2304
	ds_write_b16 v2, v3 offset:2368
	ds_read2st64_b32 v[4:5], v79 offset0:16 offset1:17
	v_mov_b32_e32 v6, v10
	v_mov_b32_e32 v7, v58
	s_waitcnt lgkmcnt(0)
	v_lshlrev_b32_e32 v8, 16, v4
	v_and_b32_e32 v9, 0xffff0000, v4
	v_lshlrev_b32_e32 v19, 16, v5
	v_and_b32_e32 v18, 0xffff0000, v5
	v_pk_mul_f32 v[4:5], v[6:7], v[84:85] op_sel_hi:[1,0]
	s_nop 0
	v_pk_fma_f32 v[4:5], v[142:143], v[4:5], v[8:9] neg_lo:[1,0,0] neg_hi:[1,0,0]
	v_mov_b32_e32 v8, v42
	v_mov_b32_e32 v9, v26
	v_pk_mul_f32 v[8:9], v[8:9], v[84:85] op_sel_hi:[1,0]
	v_pk_mul_f32 v[6:7], v[4:5], v[4:5]
	v_pk_fma_f32 v[8:9], v[142:143], v[8:9], v[18:19] neg_lo:[1,0,0] neg_hi:[1,0,0]
	v_add_f32_e32 v3, v6, v7
	v_pk_mul_f32 v[18:19], v[8:9], v[8:9]
	s_nop 0
	v_add_f32_e32 v3, v3, v19
	v_add_f32_e32 v3, v18, v3
	s_waitcnt lgkmcnt(0)
	s_nop 1
	v_add_f32_dpp v3, v3, v3 quad_perm:[1,0,3,2] row_mask:0xf bank_mask:0xf
	s_waitcnt lgkmcnt(0)
	s_nop 1
	v_add_f32_dpp v3, v3, v3 quad_perm:[2,3,0,1] row_mask:0xf bank_mask:0xf
	s_waitcnt lgkmcnt(0)
	s_nop 1
	v_add_f32_dpp v3, v3, v3 row_half_mirror row_mask:0xf bank_mask:0xf
	s_waitcnt lgkmcnt(0)
	s_nop 1
	v_add_f32_dpp v3, v3, v3 row_mirror row_mask:0xf bank_mask:0xf
	v_mov_b32_e32 v6, v3
	s_nop 1
	v_permlane16_swap_b32_e32 v3, v6
	s_waitcnt lgkmcnt(0)
	v_add_f32_e32 v3, v3, v6
	v_fmamk_f32 v3, v3, 0x3c000000, v249
	v_mul_f32_e32 v6, 0x4b800000, v3
	v_cmp_gt_f32_e32 vcc, s5, v3
	s_nop 1
	v_cndmask_b32_e32 v3, v3, v6, vcc
	v_rsq_f32_e32 v3, v3
	s_nop 0
	v_mul_f32_e32 v6, 0x45800000, v3
	v_cndmask_b32_e32 v3, v3, v6, vcc
	v_mul_f32_e32 v4, v4, v3
	v_mul_f32_e32 v5, v5, v3
	v_mul_f32_e32 v6, v9, v3
	v_mul_f32_e32 v3, v8, v3
	v_mul_f32_e32 v4, v67, v4
	v_mul_f32_e32 v5, v71, v5
	v_mul_f32_e32 v6, v73, v6
	v_mul_f32_e32 v3, v75, v3
	v_cvt_pk_bf16_f32 v4, v4, s0
	v_cvt_pk_bf16_f32 v5, v5, s0
	v_cvt_pk_bf16_f32 v6, v6, s0
	v_cvt_pk_bf16_f32 v3, v3, s0
	ds_write_b16 v76, v4 offset:4352
	ds_write_b16 v76, v5 offset:4416
	ds_write_b16 v76, v6 offset:4480
	ds_write_b16 v76, v3 offset:4544
	ds_read2st64_b32 v[4:5], v79 offset0:18 offset1:19
	v_mov_b32_e32 v58, v11
	v_mov_b32_e32 v26, v43
	v_pk_mul_f32 v[10:11], v[26:27], v[82:83] op_sel_hi:[1,0]
	s_waitcnt lgkmcnt(0)
	v_lshlrev_b32_e32 v6, 16, v4
	v_and_b32_e32 v7, 0xffff0000, v4
	v_lshlrev_b32_e32 v9, 16, v5
	v_and_b32_e32 v8, 0xffff0000, v5
	v_pk_mul_f32 v[4:5], v[58:59], v[82:83] op_sel_hi:[1,0]
	v_pk_fma_f32 v[8:9], v[142:143], v[10:11], v[8:9] neg_lo:[1,0,0] neg_hi:[1,0,0]
	v_pk_fma_f32 v[4:5], v[142:143], v[4:5], v[6:7] neg_lo:[1,0,0] neg_hi:[1,0,0]
	v_pk_mul_f32 v[10:11], v[8:9], v[8:9]
	v_pk_mul_f32 v[6:7], v[4:5], v[4:5]
	s_nop 0
	v_add_f32_e32 v3, v6, v7
	v_add_f32_e32 v3, v3, v11
	v_add_f32_e32 v3, v10, v3
	s_waitcnt lgkmcnt(0)
	s_nop 1
	v_add_f32_dpp v3, v3, v3 quad_perm:[1,0,3,2] row_mask:0xf bank_mask:0xf
	s_waitcnt lgkmcnt(0)
	s_nop 1
	v_add_f32_dpp v3, v3, v3 quad_perm:[2,3,0,1] row_mask:0xf bank_mask:0xf
	s_waitcnt lgkmcnt(0)
	s_nop 1
	v_add_f32_dpp v3, v3, v3 row_half_mirror row_mask:0xf bank_mask:0xf
	s_waitcnt lgkmcnt(0)
	s_nop 1
	v_add_f32_dpp v3, v3, v3 row_mirror row_mask:0xf bank_mask:0xf
	ds_bpermute_b32 v6, v170, v3
	s_waitcnt lgkmcnt(0)
	v_add_f32_e32 v3, v3, v6
	v_fmamk_f32 v3, v3, 0x3c000000, v249
	v_mul_f32_e32 v6, 0x4b800000, v3
	v_cmp_gt_f32_e32 vcc, s5, v3
	s_nop 1
	v_cndmask_b32_e32 v3, v3, v6, vcc
	v_rsq_f32_e32 v3, v3
	s_nop 0
	v_mul_f32_e32 v6, 0x45800000, v3
	v_cndmask_b32_e32 v3, v3, v6, vcc
	v_mul_f32_e32 v4, v4, v3
	v_mul_f32_e32 v5, v5, v3
	v_mul_f32_e32 v6, v9, v3
	v_mul_f32_e32 v3, v8, v3
	v_mul_f32_e32 v4, v67, v4
	v_mul_f32_e32 v5, v71, v5
	v_mul_f32_e32 v6, v73, v6
	v_mul_f32_e32 v3, v75, v3
	v_cvt_pk_bf16_f32 v4, v4, s0
	v_cvt_pk_bf16_f32 v5, v5, s0
	v_cvt_pk_bf16_f32 v6, v6, s0
	v_cvt_pk_bf16_f32 v3, v3, s0
	ds_write_b16 v76, v4 offset:4624
	ds_write_b16 v76, v5 offset:4688
	ds_write_b16 v76, v6 offset:4752
	ds_write_b16 v76, v3 offset:4816
	ds_read2st64_b32 v[4:5], v79 offset0:20 offset1:21
	v_mov_b32_e32 v6, v12
	v_mov_b32_e32 v7, v60
	s_waitcnt lgkmcnt(0)
	v_lshlrev_b32_e32 v8, 16, v4
	v_and_b32_e32 v9, 0xffff0000, v4
	v_lshlrev_b32_e32 v11, 16, v5
	v_and_b32_e32 v10, 0xffff0000, v5
	v_pk_mul_f32 v[4:5], v[6:7], v[74:75] op_sel_hi:[1,0]
	s_nop 0
	v_pk_fma_f32 v[4:5], v[142:143], v[4:5], v[8:9] neg_lo:[1,0,0] neg_hi:[1,0,0]
	v_mov_b32_e32 v8, v44
	v_mov_b32_e32 v9, v28
	v_pk_mul_f32 v[8:9], v[8:9], v[74:75] op_sel_hi:[1,0]
	v_pk_mul_f32 v[6:7], v[4:5], v[4:5]
	v_pk_fma_f32 v[8:9], v[142:143], v[8:9], v[10:11] neg_lo:[1,0,0] neg_hi:[1,0,0]
	v_add_f32_e32 v3, v6, v7
	v_pk_mul_f32 v[10:11], v[8:9], v[8:9]
	s_nop 0
	v_add_f32_e32 v3, v3, v11
	v_add_f32_e32 v3, v10, v3
	s_waitcnt lgkmcnt(0)
	s_nop 1
	v_add_f32_dpp v3, v3, v3 quad_perm:[1,0,3,2] row_mask:0xf bank_mask:0xf
	s_waitcnt lgkmcnt(0)
	s_nop 1
	v_add_f32_dpp v3, v3, v3 quad_perm:[2,3,0,1] row_mask:0xf bank_mask:0xf
	s_waitcnt lgkmcnt(0)
	s_nop 1
	v_add_f32_dpp v3, v3, v3 row_half_mirror row_mask:0xf bank_mask:0xf
	s_waitcnt lgkmcnt(0)
	s_nop 1
	v_add_f32_dpp v3, v3, v3 row_mirror row_mask:0xf bank_mask:0xf
	ds_bpermute_b32 v6, v170, v3
	s_waitcnt lgkmcnt(0)
	v_add_f32_e32 v3, v3, v6
	v_fmamk_f32 v3, v3, 0x3c000000, v249
	v_mul_f32_e32 v6, 0x4b800000, v3
	v_cmp_gt_f32_e32 vcc, s5, v3
	s_nop 1
	v_cndmask_b32_e32 v3, v3, v6, vcc
	v_rsq_f32_e32 v3, v3
	s_nop 0
	v_mul_f32_e32 v6, 0x45800000, v3
	v_cndmask_b32_e32 v3, v3, v6, vcc
	v_mul_f32_e32 v4, v4, v3
	v_mul_f32_e32 v5, v5, v3
	v_mul_f32_e32 v6, v9, v3
	v_mul_f32_e32 v3, v8, v3
	v_mul_f32_e32 v4, v67, v4
	v_mul_f32_e32 v5, v71, v5
	v_mul_f32_e32 v6, v73, v6
	v_mul_f32_e32 v3, v75, v3
	v_cvt_pk_bf16_f32 v4, v4, s0
	v_cvt_pk_bf16_f32 v5, v5, s0
	v_cvt_pk_bf16_f32 v6, v6, s0
	v_cvt_pk_bf16_f32 v3, v3, s0
	ds_write_b16 v76, v4 offset:4896
	ds_write_b16 v76, v5 offset:4960
	ds_write_b16 v76, v6 offset:5024
	ds_write_b16 v76, v3 offset:5088
	ds_read2st64_b32 v[4:5], v79 offset0:22 offset1:23
	v_mov_b32_e32 v60, v13
	v_mov_b32_e32 v28, v45
	v_pk_mul_f32 v[10:11], v[28:29], v[72:73] op_sel_hi:[1,0]
	s_waitcnt lgkmcnt(0)
	v_lshlrev_b32_e32 v6, 16, v4
	v_and_b32_e32 v7, 0xffff0000, v4
	v_lshlrev_b32_e32 v9, 16, v5
	v_and_b32_e32 v8, 0xffff0000, v5
	v_pk_mul_f32 v[4:5], v[60:61], v[72:73] op_sel_hi:[1,0]
	v_pk_fma_f32 v[8:9], v[142:143], v[10:11], v[8:9] neg_lo:[1,0,0] neg_hi:[1,0,0]
	v_pk_fma_f32 v[4:5], v[142:143], v[4:5], v[6:7] neg_lo:[1,0,0] neg_hi:[1,0,0]
	v_pk_mul_f32 v[10:11], v[8:9], v[8:9]
	v_pk_mul_f32 v[6:7], v[4:5], v[4:5]
	s_nop 0
	v_add_f32_e32 v3, v6, v7
	v_add_f32_e32 v3, v3, v11
	v_add_f32_e32 v3, v10, v3
	s_waitcnt lgkmcnt(0)
	s_nop 1
	v_add_f32_dpp v3, v3, v3 quad_perm:[1,0,3,2] row_mask:0xf bank_mask:0xf
	s_waitcnt lgkmcnt(0)
	s_nop 1
	v_add_f32_dpp v3, v3, v3 quad_perm:[2,3,0,1] row_mask:0xf bank_mask:0xf
	s_waitcnt lgkmcnt(0)
	s_nop 1
	v_add_f32_dpp v3, v3, v3 row_half_mirror row_mask:0xf bank_mask:0xf
	s_waitcnt lgkmcnt(0)
	s_nop 1
	v_add_f32_dpp v3, v3, v3 row_mirror row_mask:0xf bank_mask:0xf
	ds_bpermute_b32 v6, v170, v3
	s_waitcnt lgkmcnt(0)
	v_add_f32_e32 v3, v3, v6
	v_fmamk_f32 v3, v3, 0x3c000000, v249
	v_mul_f32_e32 v6, 0x4b800000, v3
	v_cmp_gt_f32_e32 vcc, s5, v3
	s_nop 1
	v_cndmask_b32_e32 v3, v3, v6, vcc
	v_rsq_f32_e32 v3, v3
	s_nop 0
	v_mul_f32_e32 v6, 0x45800000, v3
	v_cndmask_b32_e32 v3, v3, v6, vcc
	v_mul_f32_e32 v4, v4, v3
	v_mul_f32_e32 v5, v5, v3
	v_mul_f32_e32 v6, v9, v3
	v_mul_f32_e32 v3, v8, v3
	v_mul_f32_e32 v4, v67, v4
	v_mul_f32_e32 v5, v71, v5
	v_mul_f32_e32 v6, v73, v6
	v_mul_f32_e32 v3, v75, v3
	v_cvt_pk_bf16_f32 v4, v4, s0
	v_cvt_pk_bf16_f32 v5, v5, s0
	v_cvt_pk_bf16_f32 v6, v6, s0
	v_cvt_pk_bf16_f32 v3, v3, s0
	ds_write_b16 v2, v4 offset:4352
	ds_write_b16 v2, v5 offset:4416
	ds_write_b16 v2, v6 offset:4480
	ds_write_b16 v2, v3 offset:4544
	ds_read2st64_b32 v[4:5], v79 offset0:24 offset1:25
	v_mov_b32_e32 v6, v14
	v_mov_b32_e32 v7, v62
	s_waitcnt lgkmcnt(0)
	v_lshlrev_b32_e32 v8, 16, v4
	v_and_b32_e32 v9, 0xffff0000, v4
	v_lshlrev_b32_e32 v11, 16, v5
	v_and_b32_e32 v10, 0xffff0000, v5
	v_pk_mul_f32 v[4:5], v[6:7], v[70:71] op_sel_hi:[1,0]
	s_nop 0
	v_pk_fma_f32 v[4:5], v[142:143], v[4:5], v[8:9] neg_lo:[1,0,0] neg_hi:[1,0,0]
	v_mov_b32_e32 v8, v46
	v_mov_b32_e32 v9, v30
	v_pk_mul_f32 v[8:9], v[8:9], v[70:71] op_sel_hi:[1,0]
	v_pk_mul_f32 v[6:7], v[4:5], v[4:5]
	v_pk_fma_f32 v[8:9], v[142:143], v[8:9], v[10:11] neg_lo:[1,0,0] neg_hi:[1,0,0]
	v_add_f32_e32 v3, v6, v7
	v_pk_mul_f32 v[10:11], v[8:9], v[8:9]
	s_nop 0
	v_add_f32_e32 v3, v3, v11
	v_add_f32_e32 v3, v10, v3
	s_waitcnt lgkmcnt(0)
	s_nop 1
	v_add_f32_dpp v3, v3, v3 quad_perm:[1,0,3,2] row_mask:0xf bank_mask:0xf
	s_waitcnt lgkmcnt(0)
	s_nop 1
	v_add_f32_dpp v3, v3, v3 quad_perm:[2,3,0,1] row_mask:0xf bank_mask:0xf
	s_waitcnt lgkmcnt(0)
	s_nop 1
	v_add_f32_dpp v3, v3, v3 row_half_mirror row_mask:0xf bank_mask:0xf
	s_waitcnt lgkmcnt(0)
	s_nop 1
	v_add_f32_dpp v3, v3, v3 row_mirror row_mask:0xf bank_mask:0xf
	ds_bpermute_b32 v6, v170, v3
	s_waitcnt lgkmcnt(0)
	v_add_f32_e32 v3, v3, v6
	v_fmamk_f32 v3, v3, 0x3c000000, v249
	v_mul_f32_e32 v6, 0x4b800000, v3
	v_cmp_gt_f32_e32 vcc, s5, v3
	s_nop 1
	v_cndmask_b32_e32 v3, v3, v6, vcc
	v_rsq_f32_e32 v3, v3
	s_nop 0
	v_mul_f32_e32 v6, 0x45800000, v3
	v_cndmask_b32_e32 v3, v3, v6, vcc
	v_mul_f32_e32 v4, v4, v3
	v_mul_f32_e32 v5, v5, v3
	v_mul_f32_e32 v6, v9, v3
	v_mul_f32_e32 v3, v8, v3
	v_mul_f32_e32 v4, v67, v4
	v_mul_f32_e32 v5, v71, v5
	v_mul_f32_e32 v6, v73, v6
	v_mul_f32_e32 v3, v75, v3
	v_cvt_pk_bf16_f32 v4, v4, s0
	v_cvt_pk_bf16_f32 v5, v5, s0
	v_cvt_pk_bf16_f32 v6, v6, s0
	v_cvt_pk_bf16_f32 v3, v3, s0
	ds_write_b16 v76, v4 offset:6528
	ds_write_b16 v76, v5 offset:6592
	ds_write_b16 v76, v6 offset:6656
	ds_write_b16 v76, v3 offset:6720
	ds_read2st64_b32 v[4:5], v79 offset0:26 offset1:27
	v_mov_b32_e32 v62, v15
	v_mov_b32_e32 v30, v47
	v_pk_mul_f32 v[10:11], v[30:31], v[68:69] op_sel_hi:[1,0]
	s_waitcnt lgkmcnt(0)
	v_lshlrev_b32_e32 v6, 16, v4
	v_and_b32_e32 v7, 0xffff0000, v4
	v_lshlrev_b32_e32 v9, 16, v5
	v_and_b32_e32 v8, 0xffff0000, v5
	v_pk_mul_f32 v[4:5], v[62:63], v[68:69] op_sel_hi:[1,0]
	v_pk_fma_f32 v[8:9], v[142:143], v[10:11], v[8:9] neg_lo:[1,0,0] neg_hi:[1,0,0]
	v_pk_fma_f32 v[4:5], v[142:143], v[4:5], v[6:7] neg_lo:[1,0,0] neg_hi:[1,0,0]
	v_pk_mul_f32 v[10:11], v[8:9], v[8:9]
	v_pk_mul_f32 v[6:7], v[4:5], v[4:5]
	s_nop 0
	v_add_f32_e32 v3, v6, v7
	v_add_f32_e32 v3, v3, v11
	v_add_f32_e32 v3, v10, v3
	s_waitcnt lgkmcnt(0)
	s_nop 1
	v_add_f32_dpp v3, v3, v3 quad_perm:[1,0,3,2] row_mask:0xf bank_mask:0xf
	s_waitcnt lgkmcnt(0)
	s_nop 1
	v_add_f32_dpp v3, v3, v3 quad_perm:[2,3,0,1] row_mask:0xf bank_mask:0xf
	s_waitcnt lgkmcnt(0)
	s_nop 1
	v_add_f32_dpp v3, v3, v3 row_half_mirror row_mask:0xf bank_mask:0xf
	s_waitcnt lgkmcnt(0)
	s_nop 1
	v_add_f32_dpp v3, v3, v3 row_mirror row_mask:0xf bank_mask:0xf
	ds_bpermute_b32 v6, v170, v3
	s_waitcnt lgkmcnt(0)
	v_add_f32_e32 v3, v3, v6
	v_fmamk_f32 v3, v3, 0x3c000000, v249
	v_mul_f32_e32 v6, 0x4b800000, v3
	v_cmp_gt_f32_e32 vcc, s5, v3
	s_nop 1
	v_cndmask_b32_e32 v3, v3, v6, vcc
	v_rsq_f32_e32 v3, v3
	s_nop 0
	v_mul_f32_e32 v6, 0x45800000, v3
	v_cndmask_b32_e32 v3, v3, v6, vcc
	v_mul_f32_e32 v4, v4, v3
	v_mul_f32_e32 v5, v5, v3
	v_mul_f32_e32 v6, v9, v3
	v_mul_f32_e32 v3, v8, v3
	v_mul_f32_e32 v4, v67, v4
	v_mul_f32_e32 v5, v71, v5
	v_mul_f32_e32 v6, v73, v6
	v_mul_f32_e32 v3, v75, v3
	v_cvt_pk_bf16_f32 v4, v4, s0
	v_cvt_pk_bf16_f32 v5, v5, s0
	v_cvt_pk_bf16_f32 v6, v6, s0
	v_cvt_pk_bf16_f32 v3, v3, s0
	ds_write_b16 v76, v4 offset:6800
	ds_write_b16 v76, v5 offset:6864
	ds_write_b16 v76, v6 offset:6928
	ds_write_b16 v76, v3 offset:6992
	ds_read2st64_b32 v[4:5], v79 offset0:28 offset1:29
	v_mov_b32_e32 v6, v16
	v_mov_b32_e32 v7, v64
	s_waitcnt lgkmcnt(0)
	v_lshlrev_b32_e32 v8, 16, v4
	v_and_b32_e32 v9, 0xffff0000, v4
	v_lshlrev_b32_e32 v11, 16, v5
	v_and_b32_e32 v10, 0xffff0000, v5
	v_pk_mul_f32 v[4:5], v[6:7], v[66:67] op_sel_hi:[1,0]
	s_nop 0
	v_pk_fma_f32 v[4:5], v[142:143], v[4:5], v[8:9] neg_lo:[1,0,0] neg_hi:[1,0,0]
	v_mov_b32_e32 v8, v48
	v_mov_b32_e32 v9, v32
	v_pk_mul_f32 v[8:9], v[8:9], v[66:67] op_sel_hi:[1,0]
	v_pk_mul_f32 v[6:7], v[4:5], v[4:5]
	v_pk_fma_f32 v[8:9], v[142:143], v[8:9], v[10:11] neg_lo:[1,0,0] neg_hi:[1,0,0]
	v_add_f32_e32 v3, v6, v7
	v_pk_mul_f32 v[10:11], v[8:9], v[8:9]
	s_nop 0
	v_add_f32_e32 v3, v3, v11
	v_add_f32_e32 v3, v10, v3
	s_waitcnt lgkmcnt(0)
	s_nop 1
	v_add_f32_dpp v3, v3, v3 quad_perm:[1,0,3,2] row_mask:0xf bank_mask:0xf
	s_waitcnt lgkmcnt(0)
	s_nop 1
	v_add_f32_dpp v3, v3, v3 quad_perm:[2,3,0,1] row_mask:0xf bank_mask:0xf
	s_waitcnt lgkmcnt(0)
	s_nop 1
	v_add_f32_dpp v3, v3, v3 row_half_mirror row_mask:0xf bank_mask:0xf
	s_waitcnt lgkmcnt(0)
	s_nop 1
	v_add_f32_dpp v3, v3, v3 row_mirror row_mask:0xf bank_mask:0xf
	ds_bpermute_b32 v6, v170, v3
	s_waitcnt lgkmcnt(0)
	v_add_f32_e32 v3, v3, v6
	v_fmamk_f32 v3, v3, 0x3c000000, v249
	v_mul_f32_e32 v6, 0x4b800000, v3
	v_cmp_gt_f32_e32 vcc, s5, v3
	s_nop 1
	v_cndmask_b32_e32 v3, v3, v6, vcc
	v_rsq_f32_e32 v3, v3
	s_nop 0
	v_mul_f32_e32 v6, 0x45800000, v3
	v_cndmask_b32_e32 v3, v3, v6, vcc
	v_mul_f32_e32 v4, v4, v3
	v_mul_f32_e32 v5, v5, v3
	v_mul_f32_e32 v6, v9, v3
	v_mul_f32_e32 v3, v8, v3
	v_mul_f32_e32 v4, v67, v4
	v_mul_f32_e32 v5, v71, v5
	v_mul_f32_e32 v6, v73, v6
	v_mul_f32_e32 v3, v75, v3
	v_cvt_pk_bf16_f32 v4, v4, s0
	v_cvt_pk_bf16_f32 v5, v5, s0
	v_cvt_pk_bf16_f32 v6, v6, s0
	v_cvt_pk_bf16_f32 v3, v3, s0
	ds_write_b16 v76, v4 offset:7072
	ds_write_b16 v76, v5 offset:7136
	ds_write_b16 v76, v6 offset:7200
	ds_write_b16 v76, v3 offset:7264
	ds_read2st64_b32 v[4:5], v79 offset0:30 offset1:31
	v_mov_b32_e32 v64, v17
	v_mov_b32_e32 v32, v49
	v_pk_mul_f32 v[10:11], v[32:33], v[0:1] op_sel_hi:[1,0]
	s_waitcnt lgkmcnt(0)
	v_lshlrev_b32_e32 v6, 16, v4
	v_and_b32_e32 v7, 0xffff0000, v4
	v_lshlrev_b32_e32 v9, 16, v5
	v_and_b32_e32 v8, 0xffff0000, v5
	v_pk_mul_f32 v[4:5], v[64:65], v[0:1] op_sel_hi:[1,0]
	v_pk_fma_f32 v[8:9], v[142:143], v[10:11], v[8:9] neg_lo:[1,0,0] neg_hi:[1,0,0]
	v_pk_fma_f32 v[4:5], v[142:143], v[4:5], v[6:7] neg_lo:[1,0,0] neg_hi:[1,0,0]
	v_pk_mul_f32 v[10:11], v[8:9], v[8:9]
	v_pk_mul_f32 v[6:7], v[4:5], v[4:5]
	s_nop 0
	v_add_f32_e32 v0, v6, v7
	v_add_f32_e32 v0, v0, v11
	v_add_f32_e32 v0, v10, v0
	s_waitcnt lgkmcnt(0)
	s_nop 1
	v_add_f32_dpp v0, v0, v0 quad_perm:[1,0,3,2] row_mask:0xf bank_mask:0xf
	s_waitcnt lgkmcnt(0)
	s_nop 1
	v_add_f32_dpp v0, v0, v0 quad_perm:[2,3,0,1] row_mask:0xf bank_mask:0xf
	s_waitcnt lgkmcnt(0)
	s_nop 1
	v_add_f32_dpp v0, v0, v0 row_half_mirror row_mask:0xf bank_mask:0xf
	s_waitcnt lgkmcnt(0)
	s_nop 1
	v_add_f32_dpp v0, v0, v0 row_mirror row_mask:0xf bank_mask:0xf
	ds_bpermute_b32 v3, v170, v0
	s_waitcnt lgkmcnt(0)
	v_add_f32_e32 v0, v0, v3
	v_fmamk_f32 v0, v0, 0x3c000000, v249
	v_mul_f32_e32 v3, 0x4b800000, v0
	v_cmp_gt_f32_e32 vcc, s5, v0
	s_nop 1
	v_cndmask_b32_e32 v0, v0, v3, vcc
	v_rsq_f32_e32 v0, v0
	s_nop 0
	v_mul_f32_e32 v3, 0x45800000, v0
	v_cndmask_b32_e32 v0, v0, v3, vcc
	v_mul_f32_e32 v3, v4, v0
	v_mul_f32_e32 v4, v5, v0
	v_mul_f32_e32 v5, v9, v0
	v_mul_f32_e32 v0, v8, v0
	v_mul_f32_e32 v3, v67, v3
	v_mul_f32_e32 v4, v71, v4
	v_mul_f32_e32 v5, v73, v5
	v_mul_f32_e32 v0, v75, v0
	v_cvt_pk_bf16_f32 v3, v3, s0
	v_cvt_pk_bf16_f32 v4, v4, s0
	v_cvt_pk_bf16_f32 v5, v5, s0
	v_cvt_pk_bf16_f32 v0, v0, s0
	ds_write_b16 v2, v3 offset:6528
	ds_write_b16 v2, v4 offset:6592
	ds_write_b16 v2, v5 offset:6656
	ds_write_b16 v2, v0 offset:6720
	s_lshl_b32 s60, s70, 12
	s_add_i32 s22, s1, s60
	s_ashr_i32 s23, s22, 31
	s_lshl_b64 s[22:23], s[22:23], 11
	s_add_u32 s1, s41, s22
	s_addc_u32 s5, s66, s23
	s_lshl_b32 s61, s71, 1
	s_add_u32 s22, s1, s61
	v_ashrrev_i32_e32 v6, 4, v162
	v_lshlrev_b32_e32 v0, 4, v162
	s_addc_u32 s23, s5, 0
	v_and_b32_e32 v0, 0xf0, v0
	v_mul_lo_u32 v2, v6, s77
	s_waitcnt lgkmcnt(0)
	v_lshl_add_u64 v[8:9], s[22:23], 0, v[0:1]
	v_add3_u32 v0, v69, v0, v2
	ds_read_b128 v[2:5], v0
	v_ashrrev_i32_e32 v7, 31, v6
	v_lshlrev_b64 v[6:7], 11, v[6:7]
	v_lshl_add_u64 v[10:11], v[8:9], 0, v[6:7]
	ds_read_b128 v[6:9], v0 offset:1088
	s_waitcnt lgkmcnt(1)
	global_store_dwordx4 v[10:11], v[2:5], off
	v_mov_b32_e32 v172, v226
	s_movk_i32 s26, 0x1800
	v_add_co_u32_e32 v2, vcc, s88, v10
	v_mov_b32_e32 v145, v1
	s_nop 0
	v_addc_co_u32_e32 v3, vcc, 0, v11, vcc
	s_waitcnt lgkmcnt(0)
	global_store_dwordx4 v[2:3], v[6:9], off
	ds_read_b128 v[2:5], v0 offset:2176
	ds_read_b128 v[6:9], v0 offset:3264
	v_add_co_u32_e32 v12, vcc, s14, v10
	v_readlane_b32 s1, v251, 7
	s_nop 0
	v_addc_co_u32_e32 v13, vcc, 0, v11, vcc
	s_waitcnt lgkmcnt(1)
	global_store_dwordx4 v[12:13], v[2:5], off
	s_add_i32 s1, s11, s1
	v_mov_b32_e32 v16, v1
	v_add_co_u32_e32 v2, vcc, s89, v10
	v_mov_b32_e32 v17, v1
	s_nop 0
	v_addc_co_u32_e32 v3, vcc, 0, v11, vcc
	s_waitcnt lgkmcnt(0)
	global_store_dwordx4 v[2:3], v[6:9], off
	ds_read_b128 v[2:5], v0 offset:4352
	ds_read_b128 v[6:9], v0 offset:5440
	v_add_co_u32_e32 v12, vcc, s81, v10
	s_add_i32 s5, s11, 0x100
	s_nop 0
	v_addc_co_u32_e32 v13, vcc, 0, v11, vcc
	s_waitcnt lgkmcnt(1)
	global_store_dwordx4 v[12:13], v[2:5], off
	v_mov_b32_e32 v14, v1
	v_mov_b32_e32 v15, v1
	v_add_co_u32_e32 v2, vcc, s20, v10
	s_lshr_b32 s5, s5, 6
	s_nop 0
	v_addc_co_u32_e32 v3, vcc, 0, v11, vcc
	s_waitcnt lgkmcnt(0)
	global_store_dwordx4 v[2:3], v[6:9], off
	ds_read_b128 v[2:5], v0 offset:6528
	ds_read_b128 v[6:9], v0 offset:7616
	v_add_co_u32_e32 v12, vcc, s18, v10
	s_or_b32 s11, s1, 31
	s_nop 0
	v_addc_co_u32_e32 v13, vcc, 0, v11, vcc
	s_waitcnt lgkmcnt(1)
	global_store_dwordx4 v[12:13], v[2:5], off
	v_mov_b32_e32 v12, v1
	v_mov_b32_e32 v13, v1
	v_add_co_u32_e32 v2, vcc, s3, v10
	v_mov_b32_e32 v243, 0xff800000
	s_nop 0
	v_addc_co_u32_e32 v3, vcc, 0, v11, vcc
	s_waitcnt lgkmcnt(0)
	global_store_dwordx4 v[2:3], v[6:9], off
	s_barrier
	s_nop 0
	v_mov_b32_e32 v6, v227
	v_mov_b64_e32 v[2:3], s[48:49]
	v_ashrrev_i32_e32 v8, 3, v6
	v_lshlrev_b32_e32 v7, 4, v6
	v_mad_i64_i32 v[4:5], s[22:23], v8, s26, v[2:3]
	v_and_b32_e32 v0, 0x70, v7
	v_and_b32_e32 v144, 0xf0, v7
	v_add_u32_e32 v7, 0x200, v6
	v_lshl_add_u64 v[150:151], v[4:5], 0, v[0:1]
	v_lshl_add_u64 v[4:5], s[30:31], 0, v[144:145]
	v_ashrrev_i32_e32 v9, 4, v6
	v_ashrrev_i32_e32 v7, 4, v7
	v_and_b32_e32 v145, 31, v172
	v_ashrrev_i32_e32 v10, 5, v172
	v_mad_i64_i32 v[152:153], s[22:23], v9, s26, v[4:5]
	v_mad_i64_i32 v[154:155], s[22:23], v7, s26, v[4:5]
	v_or_b32_e32 v173, s1, v145
	v_lshlrev_b32_e32 v4, 3, v10
	v_mad_u64_u32 v[2:3], s[30:31], v173, s26, v[2:3]
	v_ashrrev_i32_e32 v5, 31, v4
	v_lshl_add_u64 v[156:157], v[4:5], 1, v[2:3]
	global_load_dwordx4 v[114:117], v[150:151], off offset:2048
	global_load_dwordx4 v[118:121], v[152:153], off
	global_load_dwordx4 v[122:125], v[154:155], off
	global_load_dwordx4 v[126:129], v[156:157], off
	global_load_dwordx4 v[130:133], v[156:157], off offset:32
	global_load_dwordx4 v[134:137], v[156:157], off offset:64
	global_load_dwordx4 v[138:141], v[156:157], off offset:96
	v_mul_lo_u32 v174, v8, s96
	v_add_u32_e32 v2, 0, v174
	v_add_u32_e32 v238, v2, v0
	v_add_u32_e32 v2, 0, v144
	s_movk_i32 s78, 0x140
	v_mul_lo_u32 v175, v9, s78
	s_movk_i32 s78, 0x140
	v_mul_lo_u32 v176, v7, s78
	v_lshlrev_b32_e32 v241, 2, v172
	v_add_u32_e32 v239, v2, v175
	v_add_u32_e32 v240, v2, v176
	v_and_b32_e32 v2, 16, v172
	v_lshrrev_b32_e32 v3, 2, v172
	v_lshlrev_b32_e32 v179, 2, v10
	v_and_or_b32 v3, v3, 3, v179
	v_and_or_b32 v2, v241, 12, v2
	v_lshlrev_b32_e32 v181, 1, v2
	s_movk_i32 s78, 0x140
	v_mul_lo_u32 v182, v3, s78
	v_mov_b64_e32 v[2:3], s[28:29]
	v_and_b32_e32 v6, 15, v6
	v_mad_i64_i32 v[4:5], s[28:29], v7, s26, v[2:3]
	v_lshlrev_b32_e32 v6, 4, v6
	v_mov_b32_e32 v7, v1
	v_lshl_add_u64 v[4:5], v[4:5], 0, v[6:7]
	v_lshl_add_u64 v[146:147], s[16:17], 0, v[4:5]
	v_mad_i64_i32 v[4:5], s[28:29], v9, s26, v[2:3]
	v_lshl_add_u64 v[4:5], v[4:5], 0, v[6:7]
	v_mad_i64_i32 v[2:3], s[28:29], v8, s26, v[2:3]
	v_lshlrev_b32_e32 v178, 4, v10
	v_lshl_add_u64 v[148:149], s[16:17], 0, v[4:5]
	v_lshl_add_u64 v[158:159], v[2:3], 0, v[0:1]
	v_mov_b32_e32 v2, v1
	v_mov_b32_e32 v3, v1
	v_mov_b32_e32 v4, v1
	v_mov_b32_e32 v5, v1
	v_mov_b32_e32 v6, v1
	v_mov_b32_e32 v8, v1
	v_mov_b32_e32 v9, v1
	v_mov_b32_e32 v10, v1
	v_mov_b32_e32 v11, v1
	v_mov_b64_e32 v[64:65], v[16:17]
	v_mov_b64_e32 v[48:49], v[16:17]
	v_mov_b64_e32 v[32:33], v[16:17]
	v_mov_b64_e32 v[80:81], v[16:17]
	s_mov_b32 s22, 0
	v_mul_u32_u24_e32 v177, 0x90, v145
	v_cmp_gt_u32_e64 s[42:43], 32, v172
	v_lshl_add_u32 v180, v145, 2, s91
	v_subrev_u32_e32 v183, 32, v173
	v_subrev_u32_e32 v184, 33, v173
	v_subrev_u32_e32 v185, 34, v173
	v_subrev_u32_e32 v186, 35, v173
	v_add_u32_e32 v187, -8, v173
	v_subrev_u32_e32 v188, 40, v173
	v_add_u32_e32 v189, -9, v173
	v_subrev_u32_e32 v195, 41, v173
	v_add_u32_e32 v196, -10, v173
	v_subrev_u32_e32 v197, 42, v173
	v_add_u32_e32 v198, -11, v173
	v_subrev_u32_e32 v199, 43, v173
	v_add_u32_e32 v200, -16, v173
	v_subrev_u32_e32 v201, 48, v173
	v_subrev_u32_e32 v202, 17, v173
	v_subrev_u32_e32 v203, 49, v173
	v_subrev_u32_e32 v204, 18, v173
	v_subrev_u32_e32 v205, 50, v173
	v_subrev_u32_e32 v228, 19, v173
	v_subrev_u32_e32 v229, 51, v173
	v_subrev_u32_e32 v230, 24, v173
	v_subrev_u32_e32 v231, 56, v173
	v_subrev_u32_e32 v232, 25, v173
	v_subrev_u32_e32 v233, 57, v173
	v_subrev_u32_e32 v234, 26, v173
	v_subrev_u32_e32 v235, 58, v173
	v_subrev_u32_e32 v236, 27, v173
	v_subrev_u32_e32 v237, 59, v173
	v_lshl_add_u64 v[160:161], s[44:45], 0, v[158:159]
	v_mov_b64_e32 v[162:163], v[148:149]
	v_mov_b64_e32 v[164:165], v[146:147]
	v_mov_b64_e32 v[62:63], v[14:15]
	v_mov_b64_e32 v[60:61], v[12:13]
	v_mov_b64_e32 v[58:59], v[10:11]
	v_mov_b64_e32 v[56:57], v[8:9]
	v_mov_b64_e32 v[54:55], v[6:7]
	v_mov_b64_e32 v[52:53], v[4:5]
	v_mov_b64_e32 v[50:51], v[2:3]
	v_mov_b64_e32 v[46:47], v[14:15]
	v_mov_b64_e32 v[44:45], v[12:13]
	v_mov_b64_e32 v[42:43], v[10:11]
	v_mov_b64_e32 v[40:41], v[8:9]
	v_mov_b64_e32 v[38:39], v[6:7]
	v_mov_b64_e32 v[36:37], v[4:5]
	v_mov_b64_e32 v[34:35], v[2:3]
	v_mov_b64_e32 v[30:31], v[14:15]
	v_mov_b64_e32 v[28:29], v[12:13]
	v_mov_b64_e32 v[26:27], v[10:11]
	v_mov_b64_e32 v[24:25], v[8:9]
	v_mov_b64_e32 v[22:23], v[6:7]
	v_mov_b64_e32 v[20:21], v[4:5]
	v_mov_b64_e32 v[18:19], v[2:3]
	v_mov_b64_e32 v[78:79], v[14:15]
	v_mov_b64_e32 v[76:77], v[12:13]
	v_mov_b64_e32 v[74:75], v[10:11]
	v_mov_b64_e32 v[72:73], v[8:9]
	v_mov_b64_e32 v[70:71], v[6:7]
	v_mov_b64_e32 v[68:69], v[4:5]
	v_mov_b64_e32 v[66:67], v[2:3]
	s_waitcnt vmcnt(6)
	ds_write_b128 v238, v[114:117]
	s_waitcnt vmcnt(5)
	ds_write_b128 v239, v[118:121] offset:9216
	s_waitcnt vmcnt(4)
	ds_write_b128 v240, v[122:125] offset:9216
	s_waitcnt vmcnt(0) lgkmcnt(0)
	s_barrier
	s_cmp_lt_u32 s4, s5
	s_cselect_b64 s[28:29], -1, 0
	s_cmp_ge_u32 s4, s5
	s_cbranch_scc1 .LBB0_66

.LBB0_140:
	v_lshl_or_b32 v168, s36, 8, v188
	v_lshl_add_u32 v170, s40, 8, v186
	v_ashrrev_i32_e32 v169, 31, v168
	v_cmp_lt_i32_e32 vcc, v218, v213
	v_readlane_b32 s40, v255, 36
	v_lshlrev_b64 v[198:199], 1, v[168:169]
	v_cndmask_b32_e32 v130, v211, v218, vcc
	v_cmp_lt_i32_e32 vcc, v219, v213
	v_readlane_b32 s41, v255, 37
	v_ashrrev_i32_e32 v171, 31, v170
	v_lshlrev_b32_e32 v196, 2, v130
	v_cndmask_b32_e32 v130, v211, v219, vcc
	v_lshl_add_u64 v[172:173], s[40:41], 0, v[198:199]
	v_lshlrev_b64 v[200:201], 11, v[170:171]
	v_lshlrev_b32_e32 v195, 2, v130
	v_lshl_add_u64 v[130:131], v[172:173], 0, v[200:201]
	global_load_dwordx4 v[190:193], v[130:131], off
	global_load_dwordx4 v[154:157], v[130:131], off offset:256
	v_or_b32_e32 v182, 16, v170
	v_ashrrev_i32_e32 v183, 31, v182
	v_or_b32_e32 v178, 32, v170
	v_lshlrev_b64 v[184:185], 11, v[182:183]
	v_ashrrev_i32_e32 v179, 31, v178
	v_or_b32_e32 v174, 48, v170
	v_lshl_add_u64 v[130:131], v[172:173], 0, v[184:185]
	v_lshlrev_b64 v[180:181], 11, v[178:179]
	v_ashrrev_i32_e32 v175, 31, v174
	global_load_dwordx4 v[150:153], v[130:131], off
	global_load_dwordx4 v[146:149], v[130:131], off offset:256
	v_lshl_add_u64 v[130:131], v[172:173], 0, v[180:181]
	v_lshlrev_b64 v[176:177], 11, v[174:175]
	global_load_dwordx4 v[142:145], v[130:131], off
	global_load_dwordx4 v[138:141], v[130:131], off offset:256
	v_lshl_add_u64 v[130:131], v[172:173], 0, v[176:177]
	global_load_dwordx4 v[134:137], v[130:131], off
	s_nop 0
	global_load_dwordx4 v[130:133], v[130:131], off offset:256
	s_lshl_b32 s62, s36, 2
	s_ashr_i32 s63, s62, 31
	s_waitcnt vmcnt(0)
	v_lshlrev_b32_e32 v202, 16, v190
	v_and_b32_e32 v203, 0xffff0000, v190
	v_lshlrev_b32_e32 v190, 16, v191
	v_and_b32_e32 v191, 0xffff0000, v191
	v_lshlrev_b32_e32 v204, 16, v192
	v_and_b32_e32 v205, 0xffff0000, v192
	v_lshlrev_b32_e32 v192, 16, v193
	v_and_b32_e32 v193, 0xffff0000, v193
	v_pk_add_f32 v[128:129], v[128:129], v[190:191]
	v_pk_add_f32 v[126:127], v[126:127], v[202:203]
	v_pk_add_f32 v[190:191], v[124:125], v[192:193]
	v_mul_f32_e32 v124, v127, v127
	v_mul_f32_e32 v125, v129, v129
	v_pk_add_f32 v[122:123], v[122:123], v[204:205]
	v_fmac_f32_e32 v124, v126, v126
	v_fmac_f32_e32 v125, v128, v128
	v_add_f32_e32 v124, v124, v125
	v_mul_f32_e32 v125, v123, v123
	v_mul_f32_e32 v192, v191, v191
	v_fmac_f32_e32 v125, v122, v122
	v_fmac_f32_e32 v192, v190, v190
	v_add_f32_e32 v125, v125, v192
	v_add_f32_e32 v192, v124, v125
	v_cvt_pk_bf16_f32 v124, v126, v127
	v_cvt_pk_bf16_f32 v126, v122, v123
	v_lshl_add_u64 v[122:123], s[40:41], 0, v[200:201]
	v_cvt_pk_bf16_f32 v125, v128, v129
	v_cvt_pk_bf16_f32 v127, v190, v191
	v_lshl_add_u64 v[122:123], v[122:123], 0, v[198:199]
	global_store_dwordx4 v[122:123], v[124:127], off
	v_lshlrev_b32_e32 v128, 16, v156
	v_and_b32_e32 v129, 0xffff0000, v156
	v_lshlrev_b32_e32 v124, 16, v154
	v_and_b32_e32 v125, 0xffff0000, v154
	v_lshlrev_b32_e32 v126, 16, v155
	v_and_b32_e32 v127, 0xffff0000, v155
	v_lshlrev_b32_e32 v154, 16, v157
	v_and_b32_e32 v155, 0xffff0000, v157
	v_pk_add_f32 v[120:121], v[120:121], v[126:127]
	v_pk_add_f32 v[118:119], v[118:119], v[124:125]
	v_pk_add_f32 v[124:125], v[116:117], v[154:155]
	v_pk_add_f32 v[116:117], v[114:115], v[128:129]
	v_mul_f32_e32 v114, v119, v119
	v_mul_f32_e32 v115, v121, v121
	v_fmac_f32_e32 v114, v118, v118
	v_fmac_f32_e32 v115, v120, v120
	v_add_f32_e32 v114, v114, v115
	v_mul_f32_e32 v115, v117, v117
	v_mul_f32_e32 v126, v125, v125
	v_fmac_f32_e32 v115, v116, v116
	v_fmac_f32_e32 v126, v124, v124
	v_add_f32_e32 v115, v115, v126
	v_add_f32_e32 v114, v114, v115
	v_add_f32_e32 v126, v192, v114
	v_cvt_pk_bf16_f32 v114, v118, v119
	v_cvt_pk_bf16_f32 v115, v120, v121
	v_cvt_pk_bf16_f32 v116, v116, v117
	v_cvt_pk_bf16_f32 v117, v124, v125
	global_store_dwordx4 v[122:123], v[114:117], off offset:256
	ds_bpermute_b32 v114, v196, v126
	s_waitcnt lgkmcnt(0)
	v_add_f32_e32 v114, v126, v114
	v_mov_b32_e32 v115, v114
	s_nop 1
	v_permlane32_swap_b32_e32 v114, v115
	s_and_saveexec_b64 s[64:65], s[44:45]
	s_cbranch_execz .LBB0_142
	v_readlane_b32 s40, v255, 40
	v_lshlrev_b64 v[116:117], 6, v[170:171]
	v_readlane_b32 s41, v255, 41
	s_lshl_b32 s36, s22, 2
	s_waitcnt lgkmcnt(0)
	v_add_f32_e32 v114, v114, v115
	v_lshl_add_u64 v[116:117], s[40:41], 0, v[116:117]
	v_lshl_add_u64 v[116:117], s[62:63], 2, v[116:117]
	v_lshl_add_u64 v[116:117], v[116:117], 0, s[36:37]
	global_store_dword v[116:117], v114, off
.LBB0_142:
	s_or_b64 exec, exec, s[64:65]
	v_lshlrev_b32_e32 v114, 16, v150
	s_waitcnt lgkmcnt(0)
	v_and_b32_e32 v115, 0xffff0000, v150
	v_lshlrev_b32_e32 v116, 16, v151
	v_and_b32_e32 v117, 0xffff0000, v151
	v_lshlrev_b32_e32 v118, 16, v152
	v_and_b32_e32 v119, 0xffff0000, v152
	v_lshlrev_b32_e32 v120, 16, v153
	v_and_b32_e32 v121, 0xffff0000, v153
	v_pk_add_f32 v[112:113], v[112:113], v[116:117]
	v_pk_add_f32 v[110:111], v[110:111], v[114:115]
	v_pk_add_f32 v[114:115], v[108:109], v[120:121]
	v_pk_add_f32 v[108:109], v[106:107], v[118:119]
	v_mul_f32_e32 v106, v111, v111
	v_mul_f32_e32 v107, v113, v113
	v_fmac_f32_e32 v106, v110, v110
	v_fmac_f32_e32 v107, v112, v112
	v_add_f32_e32 v106, v106, v107
	v_mul_f32_e32 v107, v109, v109
	v_mul_f32_e32 v116, v115, v115
	v_fmac_f32_e32 v107, v108, v108
	v_fmac_f32_e32 v116, v114, v114
	v_add_f32_e32 v107, v107, v116
	v_add_f32_e32 v118, v106, v107
	v_cvt_pk_bf16_f32 v106, v110, v111
	v_cvt_pk_bf16_f32 v107, v112, v113
	v_lshlrev_b32_e32 v110, 16, v146
	v_and_b32_e32 v111, 0xffff0000, v146
	v_lshlrev_b32_e32 v112, 16, v147
	v_and_b32_e32 v113, 0xffff0000, v147
	v_cvt_pk_bf16_f32 v108, v108, v109
	v_cvt_pk_bf16_f32 v109, v114, v115
	v_lshlrev_b32_e32 v114, 16, v148
	v_and_b32_e32 v115, 0xffff0000, v148
	v_pk_add_f32 v[104:105], v[104:105], v[112:113]
	v_pk_add_f32 v[102:103], v[102:103], v[110:111]
	v_lshlrev_b32_e32 v116, 16, v149
	v_and_b32_e32 v117, 0xffff0000, v149
	v_pk_add_f32 v[112:113], v[98:99], v[114:115]
	v_mul_f32_e32 v98, v103, v103
	v_mul_f32_e32 v99, v105, v105
	v_pk_add_f32 v[110:111], v[100:101], v[116:117]
	v_fmac_f32_e32 v98, v102, v102
	v_fmac_f32_e32 v99, v104, v104
	v_add_f32_e32 v98, v98, v99
	v_mul_f32_e32 v99, v113, v113
	v_mul_f32_e32 v100, v111, v111
	v_fmac_f32_e32 v99, v112, v112
	v_fmac_f32_e32 v100, v110, v110
	v_add_f32_e32 v99, v99, v100
	v_add_f32_e32 v98, v98, v99
	v_add_f32_e32 v101, v118, v98
	v_mov_b32_e32 v116, v101
	s_nop 1
	v_permlane16_swap_b32_e32 v101, v116
	v_readlane_b32 s40, v255, 36
	v_readlane_b32 s41, v255, 37
	v_cvt_pk_bf16_f32 v100, v102, v103
	v_cvt_pk_bf16_f32 v102, v112, v113
	v_lshl_add_u64 v[98:99], s[40:41], 0, v[184:185]
	v_lshl_add_u64 v[114:115], v[168:169], 1, v[98:99]
	s_waitcnt lgkmcnt(0)
	v_add_f32_e32 v98, v101, v116
	v_mov_b32_e32 v99, v98
	s_nop 1
	v_permlane32_swap_b32_e32 v98, v99
	v_cvt_pk_bf16_f32 v101, v104, v105
	v_cvt_pk_bf16_f32 v103, v110, v111
	global_store_dwordx4 v[114:115], v[106:109], off
	global_store_dwordx4 v[114:115], v[100:103], off offset:256
	s_and_saveexec_b64 s[64:65], s[44:45]
	s_cbranch_execz .LBB0_144
	v_readlane_b32 s40, v255, 40
	v_lshlrev_b64 v[100:101], 6, v[182:183]
	v_readlane_b32 s41, v255, 41
	s_lshl_b32 s36, s22, 2
	s_waitcnt lgkmcnt(0)
	v_add_f32_e32 v98, v98, v99
	v_lshl_add_u64 v[100:101], s[40:41], 0, v[100:101]
	v_lshl_add_u64 v[100:101], s[62:63], 2, v[100:101]
	v_lshl_add_u64 v[100:101], v[100:101], 0, s[36:37]
	global_store_dword v[100:101], v98, off
.LBB0_144:
	s_or_b64 exec, exec, s[64:65]
	v_lshlrev_b32_e32 v98, 16, v142
	s_waitcnt lgkmcnt(0)
	v_and_b32_e32 v99, 0xffff0000, v142
	v_lshlrev_b32_e32 v100, 16, v143
	v_and_b32_e32 v101, 0xffff0000, v143
	v_lshlrev_b32_e32 v102, 16, v144
	v_and_b32_e32 v103, 0xffff0000, v144
	v_lshlrev_b32_e32 v104, 16, v145
	v_and_b32_e32 v105, 0xffff0000, v145
	v_pk_add_f32 v[96:97], v[96:97], v[100:101]
	v_pk_add_f32 v[94:95], v[94:95], v[98:99]
	v_pk_add_f32 v[98:99], v[92:93], v[104:105]
	v_pk_add_f32 v[92:93], v[90:91], v[102:103]
	v_mul_f32_e32 v90, v95, v95
	v_mul_f32_e32 v91, v97, v97
	v_fmac_f32_e32 v90, v94, v94
	v_fmac_f32_e32 v91, v96, v96
	v_add_f32_e32 v90, v90, v91
	v_mul_f32_e32 v91, v93, v93
	v_mul_f32_e32 v100, v99, v99
	v_fmac_f32_e32 v91, v92, v92
	v_fmac_f32_e32 v100, v98, v98
	v_add_f32_e32 v91, v91, v100
	v_add_f32_e32 v102, v90, v91
	v_cvt_pk_bf16_f32 v90, v94, v95
	v_cvt_pk_bf16_f32 v91, v96, v97
	v_lshlrev_b32_e32 v94, 16, v138
	v_and_b32_e32 v95, 0xffff0000, v138
	v_lshlrev_b32_e32 v96, 16, v139
	v_and_b32_e32 v97, 0xffff0000, v139
	v_cvt_pk_bf16_f32 v92, v92, v93
	v_cvt_pk_bf16_f32 v93, v98, v99
	v_lshlrev_b32_e32 v98, 16, v140
	v_and_b32_e32 v99, 0xffff0000, v140
	v_pk_add_f32 v[88:89], v[88:89], v[96:97]
	v_pk_add_f32 v[86:87], v[86:87], v[94:95]
	v_lshlrev_b32_e32 v100, 16, v141
	v_and_b32_e32 v101, 0xffff0000, v141
	v_pk_add_f32 v[96:97], v[82:83], v[98:99]
	v_mul_f32_e32 v82, v87, v87
	v_mul_f32_e32 v83, v89, v89
	v_pk_add_f32 v[94:95], v[84:85], v[100:101]
	v_fmac_f32_e32 v82, v86, v86
	v_fmac_f32_e32 v83, v88, v88
	v_add_f32_e32 v82, v82, v83
	v_mul_f32_e32 v83, v97, v97
	v_mul_f32_e32 v84, v95, v95
	v_fmac_f32_e32 v83, v96, v96
	v_fmac_f32_e32 v84, v94, v94
	v_add_f32_e32 v83, v83, v84
	v_add_f32_e32 v82, v82, v83
	v_add_f32_e32 v85, v102, v82
	v_mov_b32_e32 v100, v85
	s_nop 1
	v_permlane16_swap_b32_e32 v85, v100
	v_readlane_b32 s40, v255, 36
	v_readlane_b32 s41, v255, 37
	v_cvt_pk_bf16_f32 v84, v86, v87
	v_cvt_pk_bf16_f32 v86, v96, v97
	v_lshl_add_u64 v[82:83], s[40:41], 0, v[180:181]
	v_lshl_add_u64 v[98:99], v[168:169], 1, v[82:83]
	s_waitcnt lgkmcnt(0)
	v_add_f32_e32 v82, v85, v100
	v_mov_b32_e32 v83, v82
	s_nop 1
	v_permlane32_swap_b32_e32 v82, v83
	v_cvt_pk_bf16_f32 v85, v88, v89
	v_cvt_pk_bf16_f32 v87, v94, v95
	global_store_dwordx4 v[98:99], v[90:93], off
	global_store_dwordx4 v[98:99], v[84:87], off offset:256
	s_and_saveexec_b64 s[64:65], s[44:45]
	s_cbranch_execz .LBB0_146
	v_readlane_b32 s40, v255, 40
	v_lshlrev_b64 v[84:85], 6, v[178:179]
	v_readlane_b32 s41, v255, 41
	s_lshl_b32 s36, s22, 2
	s_waitcnt lgkmcnt(0)
	v_add_f32_e32 v82, v82, v83
	v_lshl_add_u64 v[84:85], s[40:41], 0, v[84:85]
	v_lshl_add_u64 v[84:85], s[62:63], 2, v[84:85]
	v_lshl_add_u64 v[84:85], v[84:85], 0, s[36:37]
	global_store_dword v[84:85], v82, off
.LBB0_146:
	s_or_b64 exec, exec, s[64:65]
	v_lshlrev_b32_e32 v82, 16, v134
	s_waitcnt lgkmcnt(0)
	v_and_b32_e32 v83, 0xffff0000, v134
	v_lshlrev_b32_e32 v84, 16, v135
	v_and_b32_e32 v85, 0xffff0000, v135
	v_lshlrev_b32_e32 v86, 16, v136
	v_and_b32_e32 v87, 0xffff0000, v136
	v_lshlrev_b32_e32 v88, 16, v137
	v_and_b32_e32 v89, 0xffff0000, v137
	v_pk_add_f32 v[80:81], v[80:81], v[84:85]
	v_pk_add_f32 v[78:79], v[78:79], v[82:83]
	v_pk_add_f32 v[82:83], v[76:77], v[88:89]
	v_pk_add_f32 v[76:77], v[74:75], v[86:87]
	v_mul_f32_e32 v74, v79, v79
	v_mul_f32_e32 v75, v81, v81
	v_fmac_f32_e32 v74, v78, v78
	v_fmac_f32_e32 v75, v80, v80
	v_add_f32_e32 v74, v74, v75
	v_mul_f32_e32 v75, v77, v77
	v_mul_f32_e32 v84, v83, v83
	v_fmac_f32_e32 v75, v76, v76
	v_fmac_f32_e32 v84, v82, v82
	v_add_f32_e32 v75, v75, v84
	v_add_f32_e32 v86, v74, v75
	v_cvt_pk_bf16_f32 v74, v78, v79
	v_cvt_pk_bf16_f32 v75, v80, v81
	v_lshlrev_b32_e32 v78, 16, v130
	v_and_b32_e32 v79, 0xffff0000, v130
	v_lshlrev_b32_e32 v80, 16, v131
	v_and_b32_e32 v81, 0xffff0000, v131
	v_cvt_pk_bf16_f32 v76, v76, v77
	v_cvt_pk_bf16_f32 v77, v82, v83
	v_lshlrev_b32_e32 v82, 16, v132
	v_and_b32_e32 v83, 0xffff0000, v132
	v_pk_add_f32 v[72:73], v[72:73], v[80:81]
	v_pk_add_f32 v[70:71], v[70:71], v[78:79]
	v_lshlrev_b32_e32 v84, 16, v133
	v_and_b32_e32 v85, 0xffff0000, v133
	v_pk_add_f32 v[80:81], v[66:67], v[82:83]
	v_mul_f32_e32 v66, v71, v71
	v_mul_f32_e32 v67, v73, v73
	v_pk_add_f32 v[78:79], v[68:69], v[84:85]
	v_fmac_f32_e32 v66, v70, v70
	v_fmac_f32_e32 v67, v72, v72
	v_add_f32_e32 v66, v66, v67
	v_mul_f32_e32 v67, v81, v81
	v_mul_f32_e32 v68, v79, v79
	v_fmac_f32_e32 v67, v80, v80
	v_fmac_f32_e32 v68, v78, v78
	v_add_f32_e32 v67, v67, v68
	v_add_f32_e32 v66, v66, v67
	v_add_f32_e32 v69, v86, v66
	v_mov_b32_e32 v84, v69
	s_nop 1
	v_permlane16_swap_b32_e32 v69, v84
	v_readlane_b32 s40, v255, 36
	v_readlane_b32 s41, v255, 37
	v_cvt_pk_bf16_f32 v68, v70, v71
	v_cvt_pk_bf16_f32 v70, v80, v81
	v_lshl_add_u64 v[66:67], s[40:41], 0, v[176:177]
	v_lshl_add_u64 v[82:83], v[168:169], 1, v[66:67]
	s_waitcnt lgkmcnt(0)
	v_add_f32_e32 v66, v69, v84
	v_mov_b32_e32 v67, v66
	s_nop 1
	v_permlane32_swap_b32_e32 v66, v67
	v_cvt_pk_bf16_f32 v69, v72, v73
	v_cvt_pk_bf16_f32 v71, v78, v79
	global_store_dwordx4 v[82:83], v[74:77], off
	global_store_dwordx4 v[82:83], v[68:71], off offset:256
	s_and_saveexec_b64 s[64:65], s[44:45]
	s_cbranch_execz .LBB0_148
	v_readlane_b32 s40, v255, 40
	v_lshlrev_b64 v[68:69], 6, v[174:175]
	v_readlane_b32 s41, v255, 41
	s_lshl_b32 s36, s22, 2
	s_waitcnt lgkmcnt(0)
	v_add_f32_e32 v66, v66, v67
	v_lshl_add_u64 v[68:69], s[40:41], 0, v[68:69]
	v_lshl_add_u64 v[68:69], s[62:63], 2, v[68:69]
	v_lshl_add_u64 v[68:69], v[68:69], 0, s[36:37]
	global_store_dword v[68:69], v66, off
.LBB0_148:
	s_or_b64 exec, exec, s[64:65]
	v_add_u32_e32 v106, 0x80, v170
	v_ashrrev_i32_e32 v107, 31, v106
	v_lshlrev_b64 v[112:113], 11, v[106:107]
	s_waitcnt lgkmcnt(0)
	v_lshl_add_u64 v[66:67], v[172:173], 0, v[112:113]
	global_load_dwordx4 v[108:111], v[66:67], off
	global_load_dwordx4 v[90:93], v[66:67], off offset:256
	v_add_u32_e32 v102, 0x90, v170
	v_ashrrev_i32_e32 v103, 31, v102
	v_add_u32_e32 v98, 0xa0, v170
	v_lshlrev_b64 v[104:105], 11, v[102:103]
	v_ashrrev_i32_e32 v99, 31, v98
	v_add_u32_e32 v94, 0xb0, v170
	v_lshl_add_u64 v[66:67], v[172:173], 0, v[104:105]
	v_lshlrev_b64 v[100:101], 11, v[98:99]
	v_ashrrev_i32_e32 v95, 31, v94
	global_load_dwordx4 v[86:89], v[66:67], off
	global_load_dwordx4 v[82:85], v[66:67], off offset:256
	v_lshl_add_u64 v[66:67], v[172:173], 0, v[100:101]
	v_lshlrev_b64 v[96:97], 11, v[94:95]
	global_load_dwordx4 v[78:81], v[66:67], off
	global_load_dwordx4 v[74:77], v[66:67], off offset:256
	v_lshl_add_u64 v[66:67], v[172:173], 0, v[96:97]
	global_load_dwordx4 v[70:73], v[66:67], off
	s_nop 0
	global_load_dwordx4 v[66:69], v[66:67], off offset:256
	v_readlane_b32 s40, v255, 36
	v_readlane_b32 s41, v255, 37
	s_waitcnt vmcnt(7)
	v_lshlrev_b32_e32 v114, 16, v108
	v_and_b32_e32 v115, 0xffff0000, v108
	v_lshlrev_b32_e32 v108, 16, v109
	v_and_b32_e32 v109, 0xffff0000, v109
	v_lshlrev_b32_e32 v116, 16, v110
	v_and_b32_e32 v117, 0xffff0000, v110
	v_lshlrev_b32_e32 v110, 16, v111
	v_and_b32_e32 v111, 0xffff0000, v111
	v_pk_add_f32 v[64:65], v[64:65], v[108:109]
	v_pk_add_f32 v[62:63], v[62:63], v[114:115]
	v_pk_add_f32 v[108:109], v[60:61], v[110:111]
	v_mul_f32_e32 v60, v63, v63
	v_mul_f32_e32 v61, v65, v65
	v_pk_add_f32 v[58:59], v[58:59], v[116:117]
	v_fmac_f32_e32 v60, v62, v62
	v_fmac_f32_e32 v61, v64, v64
	v_add_f32_e32 v60, v60, v61
	v_mul_f32_e32 v61, v59, v59
	v_mul_f32_e32 v110, v109, v109
	v_fmac_f32_e32 v61, v58, v58
	v_fmac_f32_e32 v110, v108, v108
	v_add_f32_e32 v61, v61, v110
	v_add_f32_e32 v110, v60, v61
	v_cvt_pk_bf16_f32 v60, v62, v63
	v_cvt_pk_bf16_f32 v62, v58, v59
	v_lshl_add_u64 v[58:59], s[40:41], 0, v[112:113]
	v_cvt_pk_bf16_f32 v61, v64, v65
	v_cvt_pk_bf16_f32 v63, v108, v109
	v_lshl_add_u64 v[58:59], v[168:169], 1, v[58:59]
	global_store_dwordx4 v[58:59], v[60:63], off
	s_waitcnt vmcnt(7)
	v_lshlrev_b32_e32 v64, 16, v92
	v_and_b32_e32 v65, 0xffff0000, v92
	v_lshlrev_b32_e32 v60, 16, v90
	v_and_b32_e32 v61, 0xffff0000, v90
	v_lshlrev_b32_e32 v62, 16, v91
	v_and_b32_e32 v63, 0xffff0000, v91
	v_lshlrev_b32_e32 v90, 16, v93
	v_and_b32_e32 v91, 0xffff0000, v93
	v_pk_add_f32 v[56:57], v[56:57], v[62:63]
	v_pk_add_f32 v[54:55], v[54:55], v[60:61]
	v_pk_add_f32 v[60:61], v[52:53], v[90:91]
	v_pk_add_f32 v[52:53], v[50:51], v[64:65]
	v_mul_f32_e32 v50, v55, v55
	v_mul_f32_e32 v51, v57, v57
	v_fmac_f32_e32 v50, v54, v54
	v_fmac_f32_e32 v51, v56, v56
	v_add_f32_e32 v50, v50, v51
	v_mul_f32_e32 v51, v53, v53
	v_mul_f32_e32 v62, v61, v61
	v_fmac_f32_e32 v51, v52, v52
	v_fmac_f32_e32 v62, v60, v60
	v_add_f32_e32 v51, v51, v62
	v_add_f32_e32 v50, v50, v51
	v_add_f32_e32 v62, v110, v50
	v_cvt_pk_bf16_f32 v50, v54, v55
	v_cvt_pk_bf16_f32 v51, v56, v57
	v_cvt_pk_bf16_f32 v52, v52, v53
	v_cvt_pk_bf16_f32 v53, v60, v61
	global_store_dwordx4 v[58:59], v[50:53], off offset:256
	ds_bpermute_b32 v50, v196, v62
	s_waitcnt lgkmcnt(0)
	v_add_f32_e32 v50, v62, v50
	v_mov_b32_e32 v51, v50
	s_nop 1
	v_permlane32_swap_b32_e32 v50, v51
	s_and_saveexec_b64 s[64:65], s[44:45]
	s_cbranch_execz .LBB0_150
	v_readlane_b32 s40, v255, 40
	v_lshlrev_b64 v[52:53], 6, v[106:107]
	v_readlane_b32 s41, v255, 41
	s_lshl_b32 s36, s22, 2
	s_waitcnt lgkmcnt(0)
	v_add_f32_e32 v50, v50, v51
	v_lshl_add_u64 v[52:53], s[40:41], 0, v[52:53]
	v_lshl_add_u64 v[52:53], s[62:63], 2, v[52:53]
	v_lshl_add_u64 v[52:53], v[52:53], 0, s[36:37]
	global_store_dword v[52:53], v50, off
.LBB0_150:
	s_or_b64 exec, exec, s[64:65]
	s_waitcnt vmcnt(7)
	v_lshlrev_b32_e32 v50, 16, v86
	s_waitcnt lgkmcnt(0)
	v_and_b32_e32 v51, 0xffff0000, v86
	v_lshlrev_b32_e32 v52, 16, v87
	v_and_b32_e32 v53, 0xffff0000, v87
	v_lshlrev_b32_e32 v54, 16, v88
	v_and_b32_e32 v55, 0xffff0000, v88
	v_lshlrev_b32_e32 v56, 16, v89
	v_and_b32_e32 v57, 0xffff0000, v89
	v_pk_add_f32 v[48:49], v[48:49], v[52:53]
	v_pk_add_f32 v[46:47], v[46:47], v[50:51]
	v_pk_add_f32 v[50:51], v[44:45], v[56:57]
	v_pk_add_f32 v[44:45], v[42:43], v[54:55]
	v_mul_f32_e32 v42, v47, v47
	v_mul_f32_e32 v43, v49, v49
	v_fmac_f32_e32 v42, v46, v46
	v_fmac_f32_e32 v43, v48, v48
	v_add_f32_e32 v42, v42, v43
	v_mul_f32_e32 v43, v45, v45
	v_mul_f32_e32 v52, v51, v51
	v_fmac_f32_e32 v43, v44, v44
	v_fmac_f32_e32 v52, v50, v50
	v_add_f32_e32 v43, v43, v52
	v_add_f32_e32 v54, v42, v43
	v_cvt_pk_bf16_f32 v42, v46, v47
	v_cvt_pk_bf16_f32 v43, v48, v49
	s_waitcnt vmcnt(6)
	v_lshlrev_b32_e32 v46, 16, v82
	v_and_b32_e32 v47, 0xffff0000, v82
	v_lshlrev_b32_e32 v48, 16, v83
	v_and_b32_e32 v49, 0xffff0000, v83
	v_cvt_pk_bf16_f32 v44, v44, v45
	v_cvt_pk_bf16_f32 v45, v50, v51
	v_lshlrev_b32_e32 v50, 16, v84
	v_and_b32_e32 v51, 0xffff0000, v84
	v_pk_add_f32 v[40:41], v[40:41], v[48:49]
	v_pk_add_f32 v[38:39], v[38:39], v[46:47]
	v_lshlrev_b32_e32 v52, 16, v85
	v_and_b32_e32 v53, 0xffff0000, v85
	v_pk_add_f32 v[48:49], v[34:35], v[50:51]
	v_mul_f32_e32 v34, v39, v39
	v_mul_f32_e32 v35, v41, v41
	v_pk_add_f32 v[46:47], v[36:37], v[52:53]
	v_fmac_f32_e32 v34, v38, v38
	v_fmac_f32_e32 v35, v40, v40
	v_add_f32_e32 v34, v34, v35
	v_mul_f32_e32 v35, v49, v49
	v_mul_f32_e32 v36, v47, v47
	v_fmac_f32_e32 v35, v48, v48
	v_fmac_f32_e32 v36, v46, v46
	v_add_f32_e32 v35, v35, v36
	v_add_f32_e32 v34, v34, v35
	v_add_f32_e32 v37, v54, v34
	ds_bpermute_b32 v52, v196, v37
	v_readlane_b32 s40, v255, 36
	v_readlane_b32 s41, v255, 37
	v_cvt_pk_bf16_f32 v36, v38, v39
	v_cvt_pk_bf16_f32 v38, v48, v49
	v_lshl_add_u64 v[34:35], s[40:41], 0, v[104:105]
	v_lshl_add_u64 v[50:51], v[168:169], 1, v[34:35]
	s_waitcnt lgkmcnt(0)
	v_add_f32_e32 v34, v37, v52
	v_mov_b32_e32 v35, v34
	s_nop 1
	v_permlane32_swap_b32_e32 v34, v35
	v_cvt_pk_bf16_f32 v37, v40, v41
	v_cvt_pk_bf16_f32 v39, v46, v47
	global_store_dwordx4 v[50:51], v[42:45], off
	global_store_dwordx4 v[50:51], v[36:39], off offset:256
	s_and_saveexec_b64 s[64:65], s[44:45]
	s_cbranch_execz .LBB0_152
	v_readlane_b32 s40, v255, 40
	v_lshlrev_b64 v[36:37], 6, v[102:103]
	v_readlane_b32 s41, v255, 41
	s_lshl_b32 s36, s22, 2
	s_waitcnt lgkmcnt(0)
	v_add_f32_e32 v34, v34, v35
	v_lshl_add_u64 v[36:37], s[40:41], 0, v[36:37]
	v_lshl_add_u64 v[36:37], s[62:63], 2, v[36:37]
	v_lshl_add_u64 v[36:37], v[36:37], 0, s[36:37]
	global_store_dword v[36:37], v34, off
.LBB0_152:
	s_or_b64 exec, exec, s[64:65]
	s_waitcnt vmcnt(7)
	v_lshlrev_b32_e32 v34, 16, v78
	s_waitcnt lgkmcnt(0)
	v_and_b32_e32 v35, 0xffff0000, v78
	v_lshlrev_b32_e32 v36, 16, v79
	v_and_b32_e32 v37, 0xffff0000, v79
	v_lshlrev_b32_e32 v38, 16, v80
	v_and_b32_e32 v39, 0xffff0000, v80
	v_lshlrev_b32_e32 v40, 16, v81
	v_and_b32_e32 v41, 0xffff0000, v81
	v_pk_add_f32 v[32:33], v[32:33], v[36:37]
	v_pk_add_f32 v[30:31], v[30:31], v[34:35]
	v_pk_add_f32 v[34:35], v[28:29], v[40:41]
	v_pk_add_f32 v[28:29], v[26:27], v[38:39]
	v_mul_f32_e32 v26, v31, v31
	v_mul_f32_e32 v27, v33, v33
	v_fmac_f32_e32 v26, v30, v30
	v_fmac_f32_e32 v27, v32, v32
	v_add_f32_e32 v26, v26, v27
	v_mul_f32_e32 v27, v29, v29
	v_mul_f32_e32 v36, v35, v35
	v_fmac_f32_e32 v27, v28, v28
	v_fmac_f32_e32 v36, v34, v34
	v_add_f32_e32 v27, v27, v36
	v_add_f32_e32 v38, v26, v27
	v_cvt_pk_bf16_f32 v26, v30, v31
	v_cvt_pk_bf16_f32 v27, v32, v33
	s_waitcnt vmcnt(6)
	v_lshlrev_b32_e32 v30, 16, v74
	v_and_b32_e32 v31, 0xffff0000, v74
	v_lshlrev_b32_e32 v32, 16, v75
	v_and_b32_e32 v33, 0xffff0000, v75
	v_cvt_pk_bf16_f32 v28, v28, v29
	v_cvt_pk_bf16_f32 v29, v34, v35
	v_lshlrev_b32_e32 v34, 16, v76
	v_and_b32_e32 v35, 0xffff0000, v76
	v_pk_add_f32 v[24:25], v[24:25], v[32:33]
	v_pk_add_f32 v[22:23], v[22:23], v[30:31]
	v_lshlrev_b32_e32 v36, 16, v77
	v_and_b32_e32 v37, 0xffff0000, v77
	v_pk_add_f32 v[32:33], v[18:19], v[34:35]
	v_mul_f32_e32 v18, v23, v23
	v_mul_f32_e32 v19, v25, v25
	v_pk_add_f32 v[30:31], v[20:21], v[36:37]
	v_fmac_f32_e32 v18, v22, v22
	v_fmac_f32_e32 v19, v24, v24
	v_add_f32_e32 v18, v18, v19
	v_mul_f32_e32 v19, v33, v33
	v_mul_f32_e32 v20, v31, v31
	v_fmac_f32_e32 v19, v32, v32
	v_fmac_f32_e32 v20, v30, v30
	v_add_f32_e32 v19, v19, v20
	v_add_f32_e32 v18, v18, v19
	v_add_f32_e32 v21, v38, v18
	v_mov_b32_e32 v36, v21
	s_nop 1
	v_permlane16_swap_b32_e32 v21, v36
	v_readlane_b32 s40, v255, 36
	v_readlane_b32 s41, v255, 37
	v_cvt_pk_bf16_f32 v20, v22, v23
	v_cvt_pk_bf16_f32 v22, v32, v33
	v_lshl_add_u64 v[18:19], s[40:41], 0, v[100:101]
	v_lshl_add_u64 v[34:35], v[168:169], 1, v[18:19]
	s_waitcnt lgkmcnt(0)
	v_add_f32_e32 v18, v21, v36
	v_mov_b32_e32 v19, v18
	s_nop 1
	v_permlane32_swap_b32_e32 v18, v19
	v_cvt_pk_bf16_f32 v21, v24, v25
	v_cvt_pk_bf16_f32 v23, v30, v31
	global_store_dwordx4 v[34:35], v[26:29], off
	global_store_dwordx4 v[34:35], v[20:23], off offset:256
	s_and_saveexec_b64 s[64:65], s[44:45]
	s_cbranch_execz .LBB0_154
	v_readlane_b32 s40, v255, 40
	v_lshlrev_b64 v[20:21], 6, v[98:99]
	v_readlane_b32 s41, v255, 41
	s_lshl_b32 s36, s22, 2
	s_waitcnt lgkmcnt(0)
	v_add_f32_e32 v18, v18, v19
	v_lshl_add_u64 v[20:21], s[40:41], 0, v[20:21]
	v_lshl_add_u64 v[20:21], s[62:63], 2, v[20:21]
	v_lshl_add_u64 v[20:21], v[20:21], 0, s[36:37]
	global_store_dword v[20:21], v18, off
.LBB0_154:
	s_or_b64 exec, exec, s[64:65]
	s_waitcnt vmcnt(7)
	v_lshlrev_b32_e32 v18, 16, v70
	s_waitcnt lgkmcnt(0)
	v_and_b32_e32 v19, 0xffff0000, v70
	v_lshlrev_b32_e32 v20, 16, v71
	v_and_b32_e32 v21, 0xffff0000, v71
	v_lshlrev_b32_e32 v22, 16, v72
	v_and_b32_e32 v23, 0xffff0000, v72
	v_lshlrev_b32_e32 v24, 16, v73
	v_and_b32_e32 v25, 0xffff0000, v73
	v_pk_add_f32 v[16:17], v[16:17], v[20:21]
	v_pk_add_f32 v[14:15], v[14:15], v[18:19]
	v_pk_add_f32 v[18:19], v[12:13], v[24:25]
	v_pk_add_f32 v[12:13], v[10:11], v[22:23]
	v_mul_f32_e32 v10, v15, v15
	v_mul_f32_e32 v11, v17, v17
	v_fmac_f32_e32 v10, v14, v14
	v_fmac_f32_e32 v11, v16, v16
	v_add_f32_e32 v10, v10, v11
	v_mul_f32_e32 v11, v13, v13
	v_mul_f32_e32 v20, v19, v19
	v_fmac_f32_e32 v11, v12, v12
	v_fmac_f32_e32 v20, v18, v18
	v_add_f32_e32 v11, v11, v20
	v_add_f32_e32 v22, v10, v11
	v_cvt_pk_bf16_f32 v10, v14, v15
	v_cvt_pk_bf16_f32 v11, v16, v17
	s_waitcnt vmcnt(6)
	v_lshlrev_b32_e32 v14, 16, v66
	v_and_b32_e32 v15, 0xffff0000, v66
	v_lshlrev_b32_e32 v16, 16, v67
	v_and_b32_e32 v17, 0xffff0000, v67
	v_cvt_pk_bf16_f32 v12, v12, v13
	v_cvt_pk_bf16_f32 v13, v18, v19
	v_lshlrev_b32_e32 v18, 16, v68
	v_and_b32_e32 v19, 0xffff0000, v68
	v_pk_add_f32 v[8:9], v[8:9], v[16:17]
	v_pk_add_f32 v[6:7], v[6:7], v[14:15]
	v_lshlrev_b32_e32 v20, 16, v69
	v_and_b32_e32 v21, 0xffff0000, v69
	v_pk_add_f32 v[16:17], v[2:3], v[18:19]
	v_mul_f32_e32 v2, v7, v7
	v_mul_f32_e32 v3, v9, v9
	v_pk_add_f32 v[14:15], v[4:5], v[20:21]
	v_fmac_f32_e32 v2, v6, v6
	v_fmac_f32_e32 v3, v8, v8
	v_add_f32_e32 v2, v2, v3
	v_mul_f32_e32 v3, v17, v17
	v_mul_f32_e32 v4, v15, v15
	v_fmac_f32_e32 v3, v16, v16
	v_fmac_f32_e32 v4, v14, v14
	v_add_f32_e32 v3, v3, v4
	v_add_f32_e32 v2, v2, v3
	v_add_f32_e32 v5, v22, v2
	v_mov_b32_e32 v20, v5
	s_nop 1
	v_permlane16_swap_b32_e32 v5, v20
	v_readlane_b32 s40, v255, 36
	v_readlane_b32 s41, v255, 37
	v_cvt_pk_bf16_f32 v4, v6, v7
	v_cvt_pk_bf16_f32 v6, v16, v17
	v_lshl_add_u64 v[2:3], s[40:41], 0, v[96:97]
	v_lshl_add_u64 v[18:19], v[168:169], 1, v[2:3]
	s_waitcnt lgkmcnt(0)
	v_add_f32_e32 v2, v5, v20
	v_mov_b32_e32 v3, v2
	s_nop 1
	v_permlane32_swap_b32_e32 v2, v3
	v_cvt_pk_bf16_f32 v5, v8, v9
	v_cvt_pk_bf16_f32 v7, v14, v15
	global_store_dwordx4 v[18:19], v[10:13], off
	global_store_dwordx4 v[18:19], v[4:7], off offset:256
	s_and_saveexec_b64 s[64:65], s[44:45]
	s_cbranch_execz .LBB0_156
	v_readlane_b32 s40, v255, 40
	v_lshlrev_b64 v[4:5], 6, v[94:95]
	v_readlane_b32 s41, v255, 41
	s_lshl_b32 s36, s22, 2
	s_waitcnt lgkmcnt(0)
	v_add_f32_e32 v2, v2, v3
	v_lshl_add_u64 v[4:5], s[40:41], 0, v[4:5]
	v_lshl_add_u64 v[4:5], s[62:63], 2, v[4:5]
	v_lshl_add_u64 v[4:5], v[4:5], 0, s[36:37]
	global_store_dword v[4:5], v2, off

.LBB0_184:
	s_lshl_b32 s9, s1, 8
	s_add_i32 s9, s9, s22
	s_lshl_b32 s5, s4, 5
	v_or_b32_e32 v158, s9, v145
	s_lshl_b32 s9, s40, 8
	v_bfe_u32 v0, v144, 4, 2
	s_or_b32 s5, s9, s5
	v_cmp_lt_i32_e32 vcc, v218, v213
	v_lshl_or_b32 v162, v0, 3, s5
	v_readlane_b32 s10, v255, 36
	v_cndmask_b32_e32 v130, v211, v218, vcc
	v_cmp_lt_i32_e32 vcc, v219, v213
	v_ashrrev_i32_e32 v163, 31, v162
	v_lshlrev_b32_e32 v182, 2, v130
	v_cndmask_b32_e32 v130, v211, v219, vcc
	v_readlane_b32 s11, v255, 37
	v_ashrrev_i32_e32 v159, 31, v158
	v_lshlrev_b32_e32 v183, 2, v130
	v_lshl_add_u64 v[180:181], v[162:163], 1, s[10:11]
	v_lshlrev_b64 v[130:131], 11, v[158:159]
	v_lshl_add_u64 v[134:135], v[180:181], 0, v[130:131]
	s_barrier
	global_load_dwordx4 v[130:133], v[134:135], off
	v_or_b32_e32 v160, 16, v158
	v_ashrrev_i32_e32 v161, 31, v160
	v_or_b32_e32 v156, 32, v158
	v_ashrrev_i32_e32 v157, 31, v156
	v_or_b32_e32 v154, 48, v158
	v_ashrrev_i32_e32 v155, 31, v154
	v_and_b32_e32 v184, 63, v144
	s_lshl_b32 s42, s40, 2
	v_cmp_gt_u32_e32 vcc, 16, v184
	s_ashr_i32 s43, s42, 31
	s_waitcnt vmcnt(0)
	v_lshlrev_b32_e32 v164, 16, v130
	v_and_b32_e32 v165, 0xffff0000, v130
	v_lshlrev_b32_e32 v166, 16, v131
	v_and_b32_e32 v167, 0xffff0000, v131
	v_lshlrev_b32_e32 v168, 16, v132
	v_and_b32_e32 v169, 0xffff0000, v132
	v_lshlrev_b32_e32 v170, 16, v133
	v_and_b32_e32 v171, 0xffff0000, v133
	global_load_dwordx4 v[130:133], v[134:135], off offset:256
	s_waitcnt vmcnt(0)
	v_lshlrev_b32_e32 v172, 16, v130
	v_and_b32_e32 v173, 0xffff0000, v130
	v_lshlrev_b32_e32 v174, 16, v131
	v_and_b32_e32 v175, 0xffff0000, v131
	v_lshlrev_b64 v[130:131], 11, v[160:161]
	v_lshl_add_u64 v[130:131], v[180:181], 0, v[130:131]
	global_load_dwordx4 v[150:153], v[130:131], off
	global_load_dwordx4 v[146:149], v[130:131], off offset:256
	v_lshlrev_b64 v[130:131], 11, v[156:157]
	v_lshl_add_u64 v[130:131], v[180:181], 0, v[130:131]
	global_load_dwordx4 v[142:145], v[130:131], off
	global_load_dwordx4 v[138:141], v[130:131], off offset:256
	v_lshlrev_b64 v[130:131], 11, v[154:155]
	v_lshl_add_u64 v[130:131], v[180:181], 0, v[130:131]
	v_lshlrev_b32_e32 v176, 16, v132
	v_and_b32_e32 v177, 0xffff0000, v132
	v_lshlrev_b32_e32 v178, 16, v133
	v_and_b32_e32 v179, 0xffff0000, v133
	global_load_dwordx4 v[134:137], v[130:131], off
	s_nop 0
	global_load_dwordx4 v[130:133], v[130:131], off offset:256
	v_pk_add_f32 v[128:129], v[128:129], v[166:167]
	v_pk_add_f32 v[126:127], v[126:127], v[164:165]
	v_mul_f32_e32 v165, v129, v129
	v_mul_f32_e32 v164, v127, v127
	v_fmac_f32_e32 v164, v126, v126
	v_fmac_f32_e32 v165, v128, v128
	v_pk_add_f32 v[124:125], v[124:125], v[170:171]
	v_pk_add_f32 v[122:123], v[122:123], v[168:169]
	v_add_f32_e32 v164, v164, v165
	v_mul_f32_e32 v165, v123, v123
	v_mul_f32_e32 v166, v125, v125
	v_fmac_f32_e32 v165, v122, v122
	v_fmac_f32_e32 v166, v124, v124
	v_add_f32_e32 v165, v165, v166
	v_add_f32_e32 v166, v164, v165
	v_pk_add_f32 v[120:121], v[120:121], v[174:175]
	v_pk_add_f32 v[164:165], v[118:119], v[172:173]
	v_mul_f32_e32 v119, v121, v121
	v_mul_f32_e32 v118, v165, v165
	v_fmac_f32_e32 v118, v164, v164
	v_fmac_f32_e32 v119, v120, v120
	v_add_f32_e32 v118, v118, v119
	v_add_f32_e32 v118, v166, v118
	v_pk_add_f32 v[166:167], v[116:117], v[178:179]
	v_pk_add_f32 v[168:169], v[114:115], v[176:177]
	v_mul_f32_e32 v115, v167, v167
	v_mul_f32_e32 v114, v169, v169
	v_fmac_f32_e32 v114, v168, v168
	v_fmac_f32_e32 v115, v166, v166
	v_add_f32_e32 v114, v114, v115
	v_add_f32_e32 v114, v114, v118
	v_mov_b32_e32 v115, v114
	s_nop 1
	v_permlane16_swap_b32_e32 v114, v115
	v_readlane_b32 s10, v255, 40
	v_lshlrev_b64 v[116:117], 6, v[158:159]
	v_readlane_b32 s11, v255, 41
	s_waitcnt lgkmcnt(0)
	v_add_f32_e32 v114, v114, v115
	v_mov_b32_e32 v115, v114
	s_nop 1
	v_permlane32_swap_b32_e32 v114, v115
	v_lshl_add_u64 v[172:173], s[10:11], 0, v[116:117]
	s_and_saveexec_b64 s[44:45], vcc
	s_mov_b32 s9, 0x800000
	s_cbranch_execz .LBB0_186
	s_waitcnt lgkmcnt(0)
	v_add_f32_e32 v116, v114, v115
	v_lshl_add_u64 v[114:115], s[42:43], 2, v[172:173]
	s_lshl_b32 s36, s4, 2
	v_lshl_add_u64 v[114:115], v[114:115], 0, s[36:37]
	global_store_dword v[114:115], v116, off sc1
.LBB0_186:
	s_or_b64 exec, exec, s[44:45]
	s_waitcnt vmcnt(5)
	v_lshlrev_b32_e32 v114, 16, v150
	s_waitcnt lgkmcnt(0)
	v_and_b32_e32 v115, 0xffff0000, v150
	v_lshlrev_b32_e32 v116, 16, v151
	v_and_b32_e32 v117, 0xffff0000, v151
	v_pk_add_f32 v[112:113], v[112:113], v[116:117]
	v_pk_add_f32 v[110:111], v[110:111], v[114:115]
	v_lshlrev_b32_e32 v118, 16, v152
	v_and_b32_e32 v119, 0xffff0000, v152
	v_lshlrev_b32_e32 v150, 16, v153
	v_and_b32_e32 v151, 0xffff0000, v153
	v_mul_f32_e32 v114, v111, v111
	v_mul_f32_e32 v115, v113, v113
	s_waitcnt vmcnt(4)
	v_lshlrev_b32_e32 v152, 16, v146
	v_and_b32_e32 v153, 0xffff0000, v146
	v_lshlrev_b32_e32 v146, 16, v147
	v_and_b32_e32 v147, 0xffff0000, v147
	v_fmac_f32_e32 v114, v110, v110
	v_fmac_f32_e32 v115, v112, v112
	v_pk_add_f32 v[108:109], v[108:109], v[150:151]
	v_pk_add_f32 v[106:107], v[106:107], v[118:119]
	v_lshlrev_b32_e32 v170, 16, v148
	v_and_b32_e32 v171, 0xffff0000, v148
	v_lshlrev_b32_e32 v148, 16, v149
	v_and_b32_e32 v149, 0xffff0000, v149
	v_add_f32_e32 v114, v114, v115
	v_mul_f32_e32 v115, v107, v107
	v_mul_f32_e32 v116, v109, v109
	v_pk_add_f32 v[118:119], v[104:105], v[146:147]
	v_pk_add_f32 v[146:147], v[102:103], v[152:153]
	v_fmac_f32_e32 v115, v106, v106
	v_fmac_f32_e32 v116, v108, v108
	v_mul_f32_e32 v102, v147, v147
	v_mul_f32_e32 v103, v119, v119
	v_pk_add_f32 v[148:149], v[100:101], v[148:149]
	v_pk_add_f32 v[150:151], v[98:99], v[170:171]
	v_add_f32_e32 v115, v115, v116
	v_fmac_f32_e32 v102, v146, v146
	v_fmac_f32_e32 v103, v118, v118
	v_mul_f32_e32 v98, v151, v151
	v_mul_f32_e32 v99, v149, v149
	v_add_f32_e32 v114, v114, v115
	v_add_f32_e32 v102, v102, v103
	v_fmac_f32_e32 v98, v150, v150
	v_fmac_f32_e32 v99, v148, v148
	v_add_f32_e32 v102, v114, v102
	v_add_f32_e32 v98, v98, v99
	v_add_f32_e32 v98, v98, v102
	v_mov_b32_e32 v99, v98
	s_nop 1
	v_permlane16_swap_b32_e32 v98, v99
	v_readlane_b32 s10, v255, 40
	v_lshlrev_b64 v[100:101], 6, v[160:161]
	v_readlane_b32 s11, v255, 41
	s_waitcnt lgkmcnt(0)
	v_add_f32_e32 v98, v98, v99
	v_mov_b32_e32 v99, v98
	s_nop 1
	v_permlane32_swap_b32_e32 v98, v99
	v_lshl_add_u64 v[174:175], s[10:11], 0, v[100:101]
	s_and_saveexec_b64 s[44:45], vcc
	s_cbranch_execz .LBB0_188
	s_waitcnt lgkmcnt(0)
	v_add_f32_e32 v100, v98, v99
	v_lshl_add_u64 v[98:99], s[42:43], 2, v[174:175]
	s_lshl_b32 s36, s4, 2
	v_lshl_add_u64 v[98:99], v[98:99], 0, s[36:37]
	global_store_dword v[98:99], v100, off sc1
.LBB0_188:
	s_or_b64 exec, exec, s[44:45]
	s_waitcnt vmcnt(3)
	v_lshlrev_b32_e32 v98, 16, v142
	s_waitcnt lgkmcnt(0)
	v_and_b32_e32 v99, 0xffff0000, v142
	v_lshlrev_b32_e32 v100, 16, v143
	v_and_b32_e32 v101, 0xffff0000, v143
	v_lshlrev_b32_e32 v104, 16, v144
	v_and_b32_e32 v105, 0xffff0000, v144
	v_lshlrev_b32_e32 v102, 16, v145
	v_and_b32_e32 v103, 0xffff0000, v145
	s_waitcnt vmcnt(2)
	v_lshlrev_b32_e32 v116, 16, v138
	v_and_b32_e32 v117, 0xffff0000, v138
	v_lshlrev_b32_e32 v138, 16, v139
	v_and_b32_e32 v139, 0xffff0000, v139
	v_pk_add_f32 v[96:97], v[96:97], v[100:101]
	v_pk_add_f32 v[98:99], v[94:95], v[98:99]
	v_pk_add_f32 v[102:103], v[92:93], v[102:103]
	v_pk_add_f32 v[114:115], v[90:91], v[104:105]
	v_lshlrev_b32_e32 v144, 16, v140
	v_and_b32_e32 v145, 0xffff0000, v140
	v_lshlrev_b32_e32 v142, 16, v141
	v_and_b32_e32 v143, 0xffff0000, v141
	v_mul_f32_e32 v94, v99, v99
	v_mul_f32_e32 v95, v97, v97
	v_mul_f32_e32 v90, v115, v115
	v_mul_f32_e32 v91, v103, v103
	v_pk_add_f32 v[138:139], v[88:89], v[138:139]
	v_pk_add_f32 v[140:141], v[86:87], v[116:117]
	v_fmac_f32_e32 v94, v98, v98
	v_fmac_f32_e32 v95, v96, v96
	v_fmac_f32_e32 v90, v114, v114
	v_fmac_f32_e32 v91, v102, v102
	v_mul_f32_e32 v86, v141, v141
	v_mul_f32_e32 v87, v139, v139
	v_pk_add_f32 v[142:143], v[84:85], v[142:143]
	v_pk_add_f32 v[152:153], v[82:83], v[144:145]
	v_add_f32_e32 v94, v94, v95
	v_add_f32_e32 v90, v90, v91
	v_fmac_f32_e32 v86, v140, v140
	v_fmac_f32_e32 v87, v138, v138
	v_mul_f32_e32 v82, v153, v153
	v_mul_f32_e32 v83, v143, v143
	v_add_f32_e32 v90, v94, v90
	v_add_f32_e32 v86, v86, v87
	v_fmac_f32_e32 v82, v152, v152
	v_fmac_f32_e32 v83, v142, v142
	v_add_f32_e32 v86, v90, v86
	v_add_f32_e32 v82, v82, v83
	v_add_f32_e32 v82, v82, v86
	v_mov_b32_e32 v83, v82
	s_nop 1
	v_permlane16_swap_b32_e32 v82, v83
	v_readlane_b32 s10, v255, 40
	v_lshlrev_b64 v[84:85], 6, v[156:157]
	v_readlane_b32 s11, v255, 41
	s_waitcnt lgkmcnt(0)
	v_add_f32_e32 v82, v82, v83
	v_mov_b32_e32 v83, v82
	s_nop 1
	v_permlane32_swap_b32_e32 v82, v83
	v_lshl_add_u64 v[176:177], s[10:11], 0, v[84:85]
	s_and_saveexec_b64 s[44:45], vcc
	s_cbranch_execz .LBB0_190
	s_waitcnt lgkmcnt(0)
	v_add_f32_e32 v84, v82, v83
	v_lshl_add_u64 v[82:83], s[42:43], 2, v[176:177]
	s_lshl_b32 s36, s4, 2
	v_lshl_add_u64 v[82:83], v[82:83], 0, s[36:37]
	global_store_dword v[82:83], v84, off sc1
.LBB0_190:
	s_or_b64 exec, exec, s[44:45]
	s_waitcnt vmcnt(1)
	v_lshlrev_b32_e32 v82, 16, v134
	s_waitcnt lgkmcnt(0)
	v_and_b32_e32 v83, 0xffff0000, v134
	v_lshlrev_b32_e32 v84, 16, v135
	v_and_b32_e32 v85, 0xffff0000, v135
	v_lshlrev_b32_e32 v86, 16, v136
	v_and_b32_e32 v87, 0xffff0000, v136
	v_lshlrev_b32_e32 v88, 16, v137
	v_and_b32_e32 v89, 0xffff0000, v137
	s_waitcnt vmcnt(0)
	v_lshlrev_b32_e32 v90, 16, v130
	v_and_b32_e32 v91, 0xffff0000, v130
	v_lshlrev_b32_e32 v92, 16, v131
	v_and_b32_e32 v93, 0xffff0000, v131
	v_pk_add_f32 v[94:95], v[80:81], v[84:85]
	v_pk_add_f32 v[100:101], v[78:79], v[82:83]
	v_pk_add_f32 v[104:105], v[76:77], v[88:89]
	v_pk_add_f32 v[116:117], v[74:75], v[86:87]
	v_lshlrev_b32_e32 v136, 16, v132
	v_and_b32_e32 v137, 0xffff0000, v132
	v_lshlrev_b32_e32 v132, 16, v133
	v_and_b32_e32 v133, 0xffff0000, v133
	v_mul_f32_e32 v78, v101, v101
	v_mul_f32_e32 v79, v95, v95
	v_mul_f32_e32 v74, v117, v117
	v_mul_f32_e32 v75, v105, v105
	v_pk_add_f32 v[130:131], v[72:73], v[92:93]
	v_pk_add_f32 v[134:135], v[70:71], v[90:91]
	v_fmac_f32_e32 v78, v100, v100
	v_fmac_f32_e32 v79, v94, v94
	v_fmac_f32_e32 v74, v116, v116
	v_fmac_f32_e32 v75, v104, v104
	v_mul_f32_e32 v70, v135, v135
	v_mul_f32_e32 v71, v131, v131
	v_pk_add_f32 v[144:145], v[68:69], v[132:133]
	v_pk_add_f32 v[170:171], v[66:67], v[136:137]
	v_add_f32_e32 v78, v78, v79
	v_add_f32_e32 v74, v74, v75
	v_fmac_f32_e32 v70, v134, v134
	v_fmac_f32_e32 v71, v130, v130
	v_mul_f32_e32 v66, v171, v171
	v_mul_f32_e32 v67, v145, v145
	v_add_f32_e32 v74, v78, v74
	v_add_f32_e32 v70, v70, v71
	v_fmac_f32_e32 v66, v170, v170
	v_fmac_f32_e32 v67, v144, v144
	v_add_f32_e32 v70, v74, v70
	v_add_f32_e32 v66, v66, v67
	v_add_f32_e32 v66, v66, v70
	v_mov_b32_e32 v67, v66
	s_nop 1
	v_permlane16_swap_b32_e32 v66, v67
	v_readlane_b32 s10, v255, 40
	v_lshlrev_b64 v[68:69], 6, v[154:155]
	v_readlane_b32 s11, v255, 41
	s_waitcnt lgkmcnt(0)
	v_add_f32_e32 v66, v66, v67
	v_mov_b32_e32 v67, v66
	s_nop 1
	v_permlane32_swap_b32_e32 v66, v67
	v_lshl_add_u64 v[178:179], s[10:11], 0, v[68:69]
	s_and_saveexec_b64 s[44:45], vcc
	s_cbranch_execz .LBB0_192
	s_waitcnt lgkmcnt(0)
	v_add_f32_e32 v68, v66, v67
	v_lshl_add_u64 v[66:67], s[42:43], 2, v[178:179]
	s_lshl_b32 s36, s4, 2
	v_lshl_add_u64 v[66:67], v[66:67], 0, s[36:37]
	global_store_dword v[66:67], v68, off sc1
.LBB0_192:
	s_or_b64 exec, exec, s[44:45]
	v_add_u32_e32 v136, 0x80, v158
	v_ashrrev_i32_e32 v137, 31, v136
	s_waitcnt lgkmcnt(0)
	v_lshlrev_b64 v[66:67], 11, v[136:137]
	v_lshl_add_u64 v[70:71], v[180:181], 0, v[66:67]
	global_load_dwordx4 v[66:69], v[70:71], off
	v_add_u32_e32 v132, 0x90, v158
	v_ashrrev_i32_e32 v133, 31, v132
	v_add_u32_e32 v92, 0xa0, v158
	v_ashrrev_i32_e32 v93, 31, v92
	v_add_u32_e32 v90, 0xb0, v158
	v_ashrrev_i32_e32 v91, 31, v90
	s_waitcnt vmcnt(0)
	v_lshlrev_b32_e32 v186, 16, v66
	v_and_b32_e32 v187, 0xffff0000, v66
	v_lshlrev_b32_e32 v188, 16, v67
	v_and_b32_e32 v189, 0xffff0000, v67
	v_lshlrev_b32_e32 v190, 16, v68
	v_and_b32_e32 v191, 0xffff0000, v68
	v_lshlrev_b32_e32 v192, 16, v69
	v_and_b32_e32 v193, 0xffff0000, v69
	global_load_dwordx4 v[66:69], v[70:71], off offset:256
	s_waitcnt vmcnt(0)
	v_lshlrev_b32_e32 v196, 16, v66
	v_and_b32_e32 v197, 0xffff0000, v66
	v_lshlrev_b32_e32 v198, 16, v67
	v_and_b32_e32 v199, 0xffff0000, v67
	v_lshlrev_b64 v[66:67], 11, v[132:133]
	v_lshl_add_u64 v[66:67], v[180:181], 0, v[66:67]
	global_load_dwordx4 v[86:89], v[66:67], off
	global_load_dwordx4 v[82:85], v[66:67], off offset:256
	v_lshlrev_b64 v[66:67], 11, v[92:93]
	v_lshl_add_u64 v[66:67], v[180:181], 0, v[66:67]
	global_load_dwordx4 v[78:81], v[66:67], off
	global_load_dwordx4 v[74:77], v[66:67], off offset:256
	v_lshlrev_b64 v[66:67], 11, v[90:91]
	v_lshl_add_u64 v[66:67], v[180:181], 0, v[66:67]
	v_lshlrev_b32_e32 v200, 16, v68
	v_and_b32_e32 v201, 0xffff0000, v68
	v_lshlrev_b32_e32 v202, 16, v69
	v_and_b32_e32 v203, 0xffff0000, v69
	global_load_dwordx4 v[70:73], v[66:67], off
	s_nop 0
	global_load_dwordx4 v[66:69], v[66:67], off offset:256
	v_pk_add_f32 v[64:65], v[64:65], v[188:189]
	v_pk_add_f32 v[62:63], v[62:63], v[186:187]
	v_mul_f32_e32 v181, v65, v65
	v_mul_f32_e32 v180, v63, v63
	v_fmac_f32_e32 v180, v62, v62
	v_fmac_f32_e32 v181, v64, v64
	v_pk_add_f32 v[60:61], v[60:61], v[192:193]
	v_pk_add_f32 v[58:59], v[58:59], v[190:191]
	v_add_f32_e32 v180, v180, v181
	v_mul_f32_e32 v181, v59, v59
	v_mul_f32_e32 v185, v61, v61
	v_fmac_f32_e32 v181, v58, v58
	v_fmac_f32_e32 v185, v60, v60
	v_add_f32_e32 v181, v181, v185
	v_pk_add_f32 v[56:57], v[56:57], v[198:199]
	v_pk_add_f32 v[54:55], v[54:55], v[196:197]
	v_add_f32_e32 v180, v180, v181
	v_mul_f32_e32 v181, v55, v55
	v_mul_f32_e32 v185, v57, v57
	v_fmac_f32_e32 v181, v54, v54
	v_fmac_f32_e32 v185, v56, v56
	v_add_f32_e32 v181, v181, v185
	v_pk_add_f32 v[52:53], v[52:53], v[202:203]
	v_pk_add_f32 v[50:51], v[50:51], v[200:201]
	v_add_f32_e32 v180, v180, v181
	v_mul_f32_e32 v181, v51, v51
	v_mul_f32_e32 v185, v53, v53
	v_fmac_f32_e32 v181, v50, v50
	v_fmac_f32_e32 v185, v52, v52
	v_add_f32_e32 v181, v181, v185
	v_add_f32_e32 v180, v181, v180
	v_mov_b32_e32 v181, v180
	s_nop 1
	v_permlane16_swap_b32_e32 v180, v181
	v_readlane_b32 s10, v255, 40
	v_readlane_b32 s11, v255, 41
	s_waitcnt lgkmcnt(0)
	v_add_f32_e32 v185, v180, v181
	v_mov_b32_e32 v186, v185
	s_nop 1
	v_permlane32_swap_b32_e32 v185, v186
	v_lshlrev_b64 v[180:181], 6, v[136:137]
	v_lshl_add_u64 v[180:181], s[10:11], 0, v[180:181]
	s_and_saveexec_b64 s[44:45], vcc
	s_cbranch_execz .LBB0_194
	s_waitcnt lgkmcnt(0)
	v_add_f32_e32 v185, v185, v186
	v_lshl_add_u64 v[186:187], s[42:43], 2, v[180:181]
	s_lshl_b32 s36, s4, 2
	v_lshl_add_u64 v[186:187], v[186:187], 0, s[36:37]
	global_store_dword v[186:187], v185, off sc1
.LBB0_194:
	s_or_b64 exec, exec, s[44:45]
	s_waitcnt vmcnt(5) lgkmcnt(0)
	v_lshlrev_b32_e32 v186, 16, v86
	v_and_b32_e32 v187, 0xffff0000, v86
	v_lshlrev_b32_e32 v86, 16, v87
	v_and_b32_e32 v87, 0xffff0000, v87
	v_pk_add_f32 v[48:49], v[48:49], v[86:87]
	v_pk_add_f32 v[46:47], v[46:47], v[186:187]
	v_lshlrev_b32_e32 v188, 16, v88
	v_and_b32_e32 v189, 0xffff0000, v88
	v_lshlrev_b32_e32 v88, 16, v89
	v_and_b32_e32 v89, 0xffff0000, v89
	s_waitcnt vmcnt(4)
	v_lshlrev_b32_e32 v190, 16, v82
	v_and_b32_e32 v191, 0xffff0000, v82
	v_lshlrev_b32_e32 v82, 16, v83
	v_and_b32_e32 v83, 0xffff0000, v83
	v_mul_f32_e32 v86, v47, v47
	v_mul_f32_e32 v87, v49, v49
	v_fmac_f32_e32 v86, v46, v46
	v_fmac_f32_e32 v87, v48, v48
	v_pk_add_f32 v[44:45], v[44:45], v[88:89]
	v_pk_add_f32 v[42:43], v[42:43], v[188:189]
	v_pk_add_f32 v[40:41], v[40:41], v[82:83]
	v_pk_add_f32 v[38:39], v[38:39], v[190:191]
	v_lshlrev_b32_e32 v192, 16, v84
	v_and_b32_e32 v193, 0xffff0000, v84
	v_lshlrev_b32_e32 v84, 16, v85
	v_and_b32_e32 v85, 0xffff0000, v85
	v_add_f32_e32 v86, v86, v87
	v_mul_f32_e32 v87, v43, v43
	v_mul_f32_e32 v88, v45, v45
	v_mul_f32_e32 v82, v39, v39
	v_mul_f32_e32 v83, v41, v41
	v_fmac_f32_e32 v87, v42, v42
	v_fmac_f32_e32 v88, v44, v44
	v_fmac_f32_e32 v82, v38, v38
	v_fmac_f32_e32 v83, v40, v40
	v_pk_add_f32 v[36:37], v[36:37], v[84:85]
	v_pk_add_f32 v[34:35], v[34:35], v[192:193]
	v_add_f32_e32 v87, v87, v88
	v_add_f32_e32 v82, v82, v83
	v_mul_f32_e32 v83, v35, v35
	v_mul_f32_e32 v84, v37, v37
	v_add_f32_e32 v86, v86, v87
	v_fmac_f32_e32 v83, v34, v34
	v_fmac_f32_e32 v84, v36, v36
	v_add_f32_e32 v82, v86, v82
	v_add_f32_e32 v83, v83, v84
	v_add_f32_e32 v82, v83, v82
	v_mov_b32_e32 v83, v82
	s_nop 1
	v_permlane16_swap_b32_e32 v82, v83
	v_readlane_b32 s10, v255, 40
	v_readlane_b32 s11, v255, 41
	s_waitcnt lgkmcnt(0)
	v_add_f32_e32 v84, v82, v83
	v_mov_b32_e32 v85, v84
	s_nop 1
	v_permlane32_swap_b32_e32 v84, v85
	v_lshlrev_b64 v[82:83], 6, v[132:133]
	v_lshl_add_u64 v[82:83], s[10:11], 0, v[82:83]
	s_and_saveexec_b64 s[44:45], vcc
	s_cbranch_execz .LBB0_196
	s_waitcnt lgkmcnt(0)
	v_add_f32_e32 v86, v84, v85
	v_lshl_add_u64 v[84:85], s[42:43], 2, v[82:83]
	s_lshl_b32 s36, s4, 2
	v_lshl_add_u64 v[84:85], v[84:85], 0, s[36:37]
	global_store_dword v[84:85], v86, off sc1
.LBB0_196:
	s_or_b64 exec, exec, s[44:45]
	s_waitcnt vmcnt(3)
	v_lshlrev_b32_e32 v84, 16, v78
	s_waitcnt lgkmcnt(0)
	v_and_b32_e32 v85, 0xffff0000, v78
	v_lshlrev_b32_e32 v78, 16, v79
	v_and_b32_e32 v79, 0xffff0000, v79
	v_pk_add_f32 v[32:33], v[32:33], v[78:79]
	v_pk_add_f32 v[30:31], v[30:31], v[84:85]
	v_lshlrev_b32_e32 v86, 16, v80
	v_and_b32_e32 v87, 0xffff0000, v80
	v_lshlrev_b32_e32 v80, 16, v81
	v_and_b32_e32 v81, 0xffff0000, v81
	s_waitcnt vmcnt(2)
	v_lshlrev_b32_e32 v88, 16, v74
	v_and_b32_e32 v89, 0xffff0000, v74
	v_lshlrev_b32_e32 v74, 16, v75
	v_and_b32_e32 v75, 0xffff0000, v75
	v_mul_f32_e32 v78, v31, v31
	v_mul_f32_e32 v79, v33, v33
	v_fmac_f32_e32 v78, v30, v30
	v_fmac_f32_e32 v79, v32, v32
	v_pk_add_f32 v[28:29], v[28:29], v[80:81]
	v_pk_add_f32 v[26:27], v[26:27], v[86:87]
	v_pk_add_f32 v[24:25], v[24:25], v[74:75]
	v_pk_add_f32 v[22:23], v[22:23], v[88:89]
	v_lshlrev_b32_e32 v186, 16, v76
	v_and_b32_e32 v187, 0xffff0000, v76
	v_lshlrev_b32_e32 v76, 16, v77
	v_and_b32_e32 v77, 0xffff0000, v77
	v_add_f32_e32 v78, v78, v79
	v_mul_f32_e32 v79, v27, v27
	v_mul_f32_e32 v80, v29, v29
	v_mul_f32_e32 v74, v23, v23
	v_mul_f32_e32 v75, v25, v25
	v_fmac_f32_e32 v79, v26, v26
	v_fmac_f32_e32 v80, v28, v28
	v_fmac_f32_e32 v74, v22, v22
	v_fmac_f32_e32 v75, v24, v24
	v_pk_add_f32 v[20:21], v[20:21], v[76:77]
	v_pk_add_f32 v[18:19], v[18:19], v[186:187]
	v_add_f32_e32 v79, v79, v80
	v_add_f32_e32 v74, v74, v75
	v_mul_f32_e32 v75, v19, v19
	v_mul_f32_e32 v76, v21, v21
	v_add_f32_e32 v78, v78, v79
	v_fmac_f32_e32 v75, v18, v18
	v_fmac_f32_e32 v76, v20, v20
	v_add_f32_e32 v74, v78, v74
	v_add_f32_e32 v75, v75, v76
	v_add_f32_e32 v74, v75, v74
	v_mov_b32_e32 v75, v74
	s_nop 1
	v_permlane16_swap_b32_e32 v74, v75
	v_readlane_b32 s10, v255, 40
	v_lshlrev_b64 v[76:77], 6, v[92:93]
	v_readlane_b32 s11, v255, 41
	s_waitcnt lgkmcnt(0)
	v_add_f32_e32 v74, v74, v75
	v_mov_b32_e32 v75, v74
	s_nop 1
	v_permlane32_swap_b32_e32 v74, v75
	v_lshl_add_u64 v[84:85], s[10:11], 0, v[76:77]
	s_and_saveexec_b64 s[44:45], vcc
	s_cbranch_execz .LBB0_198
	s_waitcnt lgkmcnt(0)
	v_add_f32_e32 v76, v74, v75
	v_lshl_add_u64 v[74:75], s[42:43], 2, v[84:85]
	s_lshl_b32 s36, s4, 2
	v_lshl_add_u64 v[74:75], v[74:75], 0, s[36:37]
	global_store_dword v[74:75], v76, off sc1
.LBB0_198:
	s_or_b64 exec, exec, s[44:45]
	s_waitcnt vmcnt(1)
	v_lshlrev_b32_e32 v74, 16, v70
	s_waitcnt lgkmcnt(0)
	v_and_b32_e32 v75, 0xffff0000, v70
	v_lshlrev_b32_e32 v70, 16, v71
	v_and_b32_e32 v71, 0xffff0000, v71
	v_lshlrev_b32_e32 v76, 16, v72
	v_and_b32_e32 v77, 0xffff0000, v72
	v_lshlrev_b32_e32 v72, 16, v73
	v_and_b32_e32 v73, 0xffff0000, v73
	s_waitcnt vmcnt(0)
	v_lshlrev_b32_e32 v78, 16, v66
	v_and_b32_e32 v79, 0xffff0000, v66
	v_lshlrev_b32_e32 v80, 16, v67
	v_and_b32_e32 v81, 0xffff0000, v67
	v_lshlrev_b32_e32 v86, 16, v68
	v_and_b32_e32 v87, 0xffff0000, v68
	v_lshlrev_b32_e32 v88, 16, v69
	v_and_b32_e32 v89, 0xffff0000, v69
	v_pk_add_f32 v[66:67], v[16:17], v[70:71]
	v_pk_add_f32 v[68:69], v[14:15], v[74:75]
	v_pk_add_f32 v[70:71], v[12:13], v[72:73]
	v_pk_add_f32 v[74:75], v[10:11], v[76:77]
	v_mul_f32_e32 v14, v69, v69
	v_mul_f32_e32 v15, v67, v67
	v_mul_f32_e32 v10, v75, v75
	v_mul_f32_e32 v11, v71, v71
	v_pk_add_f32 v[72:73], v[8:9], v[80:81]
	v_pk_add_f32 v[78:79], v[6:7], v[78:79]
	v_fmac_f32_e32 v14, v68, v68
	v_fmac_f32_e32 v15, v66, v66
	v_fmac_f32_e32 v10, v74, v74
	v_fmac_f32_e32 v11, v70, v70
	v_mul_f32_e32 v6, v79, v79
	v_mul_f32_e32 v7, v73, v73
	v_pk_add_f32 v[76:77], v[4:5], v[88:89]
	v_pk_add_f32 v[80:81], v[2:3], v[86:87]
	v_add_f32_e32 v14, v14, v15
	v_add_f32_e32 v10, v10, v11
	v_fmac_f32_e32 v6, v78, v78
	v_fmac_f32_e32 v7, v72, v72
	v_mul_f32_e32 v2, v81, v81
	v_mul_f32_e32 v3, v77, v77
	v_add_f32_e32 v10, v14, v10
	v_add_f32_e32 v6, v6, v7
	v_fmac_f32_e32 v2, v80, v80
	v_fmac_f32_e32 v3, v76, v76
	v_add_f32_e32 v6, v10, v6
	v_add_f32_e32 v2, v2, v3
	v_add_f32_e32 v2, v2, v6
	v_mov_b32_e32 v3, v2
	s_nop 1
	v_permlane16_swap_b32_e32 v2, v3
	v_readlane_b32 s10, v255, 40
	v_lshlrev_b64 v[4:5], 6, v[90:91]
	v_readlane_b32 s11, v255, 41
	s_waitcnt lgkmcnt(0)
	v_add_f32_e32 v2, v2, v3
	v_mov_b32_e32 v3, v2
	s_nop 1
	v_permlane32_swap_b32_e32 v2, v3
	v_lshl_add_u64 v[86:87], s[10:11], 0, v[4:5]
	s_and_saveexec_b64 s[44:45], vcc
	s_cbranch_execz .LBB0_200
	s_waitcnt lgkmcnt(0)
	v_add_f32_e32 v4, v2, v3
	v_lshl_add_u64 v[2:3], s[42:43], 2, v[86:87]
	s_lshl_b32 s36, s4, 2
	v_lshl_add_u64 v[2:3], v[2:3], 0, s[36:37]
	global_store_dword v[2:3], v4, off sc1

.LBB0_207:
	v_readlane_b32 s4, v255, 34
	v_readlane_b32 s5, v255, 35
	s_load_dwordx2 s[4:5], s[4:5], 0x18
	v_lshlrev_b64 v[88:89], 2, v[162:163]
	v_lshlrev_b32_e32 v0, 4, v0
	v_lshl_add_u64 v[162:163], v[172:173], 0, v[0:1]
	v_lshlrev_b64 v[158:159], 12, v[158:159]
	s_waitcnt lgkmcnt(0)
	v_lshl_add_u64 v[10:11], s[4:5], 0, v[88:89]
	global_load_dwordx4 v[6:9], v[10:11], off offset:16
	global_load_dwordx4 v[14:17], v[10:11], off
	global_load_dwordx4 v[2:5], v[10:11], off offset:528
	s_nop 0
	global_load_dwordx4 v[10:13], v[10:11], off offset:512
	s_nop 0
	global_load_dword v172, v[162:163], off sc1
	global_load_dword v184, v[162:163], off offset:4 sc1
	global_load_dword v173, v[162:163], off offset:8 sc1
	global_load_dword v185, v[162:163], off offset:12 sc1
	v_lshl_add_u64 v[158:159], s[30:31], 0, v[158:159]
	v_lshl_add_u64 v[158:159], v[158:159], 0, v[88:89]
	v_lshl_add_u64 v[82:83], v[82:83], 0, v[0:1]
	s_waitcnt vmcnt(0)
	v_pk_add_f32 v[162:163], v[172:173], v[184:185]
	s_nop 0
	v_add_f32_e32 v162, v162, v163
	v_mov_b32_e32 v163, v162
	s_nop 1
	v_permlane16_swap_b32_e32 v162, v163
	v_lshl_add_u64 v[172:173], v[174:175], 0, v[0:1]
	s_waitcnt lgkmcnt(0)
	v_add_f32_e32 v162, v162, v163
	v_mov_b32_e32 v163, v162
	s_nop 1
	v_permlane32_swap_b32_e32 v162, v163
	s_waitcnt lgkmcnt(0)
	v_add_f32_e32 v162, v162, v163
	v_fmamk_f32 v162, v162, 0x3a800000, v249
	v_mul_f32_e32 v163, 0x4b800000, v162
	v_cmp_gt_f32_e32 vcc, s9, v162
	s_nop 1
	v_cndmask_b32_e32 v162, v162, v163, vcc
	v_rsq_f32_e32 v162, v162
	s_nop 0
	v_mul_f32_e32 v163, 0x45800000, v162
	v_cndmask_b32_e32 v162, v162, v163, vcc
	v_pk_mul_f32 v[126:127], v[126:127], v[162:163] op_sel_hi:[1,0]
	v_pk_mul_f32 v[128:129], v[128:129], v[162:163] op_sel_hi:[1,0]
	v_pk_mul_f32 v[174:175], v[122:123], v[162:163] op_sel_hi:[1,0]
	v_pk_mul_f32 v[124:125], v[124:125], v[162:163] op_sel_hi:[1,0]
	v_pk_mul_f32 v[184:185], v[164:165], v[162:163] op_sel_hi:[1,0]
	v_pk_mul_f32 v[164:165], v[120:121], v[162:163] op_sel_hi:[1,0]
	v_pk_mul_f32 v[186:187], v[168:169], v[162:163] op_sel_hi:[1,0]
	v_pk_mul_f32 v[166:167], v[166:167], v[162:163] op_sel_hi:[1,0]
	v_pk_mul_f32 v[122:123], v[16:17], v[128:129]
	v_pk_mul_f32 v[120:121], v[14:15], v[126:127]
	v_pk_mul_f32 v[126:127], v[8:9], v[124:125]
	v_pk_mul_f32 v[124:125], v[6:7], v[174:175]
	v_pk_mul_f32 v[164:165], v[12:13], v[164:165]
	v_pk_mul_f32 v[162:163], v[10:11], v[184:185]
	v_pk_mul_f32 v[168:169], v[4:5], v[166:167]
	v_pk_mul_f32 v[166:167], v[2:3], v[186:187]
	global_store_dwordx4 v[158:159], v[120:123], off
	global_store_dwordx4 v[158:159], v[124:127], off offset:16
	global_store_dwordx4 v[158:159], v[162:165], off offset:512
	global_store_dwordx4 v[158:159], v[166:169], off offset:528
	global_load_dword v120, v[172:173], off sc1
	s_nop 0
	global_load_dword v122, v[172:173], off offset:4 sc1
	global_load_dword v121, v[172:173], off offset:8 sc1
	global_load_dword v123, v[172:173], off offset:12 sc1
	v_lshl_add_u64 v[126:127], v[176:177], 0, v[0:1]
	s_waitcnt vmcnt(0)
	v_pk_add_f32 v[120:121], v[120:121], v[122:123]
	s_nop 0
	v_add_f32_e32 v120, v120, v121
	v_mov_b32_e32 v121, v120
	s_nop 1
	v_permlane16_swap_b32_e32 v120, v121
	s_waitcnt lgkmcnt(0)
	v_add_f32_e32 v122, v120, v121
	v_mov_b32_e32 v123, v122
	s_nop 1
	v_permlane32_swap_b32_e32 v122, v123
	v_lshlrev_b64 v[120:121], 12, v[160:161]
	v_lshl_add_u64 v[120:121], s[30:31], 0, v[120:121]
	v_lshl_add_u64 v[128:129], v[120:121], 0, v[88:89]
	s_waitcnt lgkmcnt(0)
	v_add_f32_e32 v122, v122, v123
	v_fmamk_f32 v122, v122, 0x3a800000, v249
	v_mul_f32_e32 v123, 0x4b800000, v122
	v_cmp_gt_f32_e32 vcc, s9, v122
	s_nop 1
	v_cndmask_b32_e32 v122, v122, v123, vcc
	v_rsq_f32_e32 v122, v122
	s_nop 0
	v_mul_f32_e32 v120, 0x45800000, v122
	v_cndmask_b32_e32 v120, v122, v120, vcc
	v_pk_mul_f32 v[110:111], v[110:111], v[120:121] op_sel_hi:[1,0]
	v_pk_mul_f32 v[112:113], v[112:113], v[120:121] op_sel_hi:[1,0]
	v_pk_mul_f32 v[122:123], v[106:107], v[120:121] op_sel_hi:[1,0]
	v_pk_mul_f32 v[124:125], v[108:109], v[120:121] op_sel_hi:[1,0]
	v_pk_mul_f32 v[146:147], v[146:147], v[120:121] op_sel_hi:[1,0]
	v_pk_mul_f32 v[118:119], v[118:119], v[120:121] op_sel_hi:[1,0]
	v_pk_mul_f32 v[150:151], v[150:151], v[120:121] op_sel_hi:[1,0]
	v_pk_mul_f32 v[148:149], v[148:149], v[120:121] op_sel_hi:[1,0]
	v_pk_mul_f32 v[108:109], v[16:17], v[112:113]
	v_pk_mul_f32 v[106:107], v[14:15], v[110:111]
	v_pk_mul_f32 v[112:113], v[8:9], v[124:125]
	v_pk_mul_f32 v[110:111], v[6:7], v[122:123]
	v_pk_mul_f32 v[120:121], v[12:13], v[118:119]
	v_pk_mul_f32 v[118:119], v[10:11], v[146:147]
	v_pk_mul_f32 v[124:125], v[4:5], v[148:149]
	v_pk_mul_f32 v[122:123], v[2:3], v[150:151]
	global_store_dwordx4 v[128:129], v[106:109], off
	global_store_dwordx4 v[128:129], v[110:113], off offset:16
	global_store_dwordx4 v[128:129], v[118:121], off offset:512
	global_store_dwordx4 v[128:129], v[122:125], off offset:528
	global_load_dword v106, v[126:127], off sc1
	s_nop 0
	global_load_dword v108, v[126:127], off offset:4 sc1
	global_load_dword v107, v[126:127], off offset:8 sc1
	global_load_dword v109, v[126:127], off offset:12 sc1
	v_lshl_add_u64 v[122:123], v[178:179], 0, v[0:1]
	s_waitcnt vmcnt(0)
	v_pk_add_f32 v[106:107], v[106:107], v[108:109]
	s_nop 0
	v_add_f32_e32 v106, v106, v107
	v_mov_b32_e32 v107, v106
	s_nop 1
	v_permlane16_swap_b32_e32 v106, v107
	s_waitcnt lgkmcnt(0)
	v_add_f32_e32 v108, v106, v107
	v_mov_b32_e32 v109, v108
	s_nop 1
	v_permlane32_swap_b32_e32 v108, v109
	v_lshlrev_b64 v[106:107], 12, v[156:157]
	v_lshl_add_u64 v[106:107], s[30:31], 0, v[106:107]
	v_lshl_add_u64 v[124:125], v[106:107], 0, v[88:89]
	s_waitcnt lgkmcnt(0)
	v_add_f32_e32 v108, v108, v109
	v_fmamk_f32 v108, v108, 0x3a800000, v249
	v_mul_f32_e32 v109, 0x4b800000, v108
	v_cmp_gt_f32_e32 vcc, s9, v108
	s_nop 1
	v_cndmask_b32_e32 v108, v108, v109, vcc
	v_rsq_f32_e32 v108, v108
	s_nop 0
	v_mul_f32_e32 v106, 0x45800000, v108
	v_cndmask_b32_e32 v106, v108, v106, vcc
	v_pk_mul_f32 v[108:109], v[98:99], v[106:107] op_sel_hi:[1,0]
	v_pk_mul_f32 v[96:97], v[96:97], v[106:107] op_sel_hi:[1,0]
	v_pk_mul_f32 v[110:111], v[114:115], v[106:107] op_sel_hi:[1,0]
	v_pk_mul_f32 v[102:103], v[102:103], v[106:107] op_sel_hi:[1,0]
	v_pk_mul_f32 v[114:115], v[140:141], v[106:107] op_sel_hi:[1,0]
	v_pk_mul_f32 v[112:113], v[138:139], v[106:107] op_sel_hi:[1,0]
	v_pk_mul_f32 v[118:119], v[152:153], v[106:107] op_sel_hi:[1,0]
	v_pk_mul_f32 v[120:121], v[142:143], v[106:107] op_sel_hi:[1,0]
	v_pk_mul_f32 v[98:99], v[16:17], v[96:97]
	v_pk_mul_f32 v[96:97], v[14:15], v[108:109]
	v_pk_mul_f32 v[108:109], v[8:9], v[102:103]
	v_pk_mul_f32 v[106:107], v[6:7], v[110:111]
	v_pk_mul_f32 v[112:113], v[12:13], v[112:113]
	v_pk_mul_f32 v[110:111], v[10:11], v[114:115]
	v_pk_mul_f32 v[120:121], v[4:5], v[120:121]
	v_pk_mul_f32 v[118:119], v[2:3], v[118:119]
	global_store_dwordx4 v[124:125], v[96:99], off
	global_store_dwordx4 v[124:125], v[106:109], off offset:16
	global_store_dwordx4 v[124:125], v[110:113], off offset:512
	global_store_dwordx4 v[124:125], v[118:121], off offset:528
	global_load_dword v96, v[122:123], off sc1
	s_nop 0
	global_load_dword v98, v[122:123], off offset:4 sc1
	global_load_dword v97, v[122:123], off offset:8 sc1
	global_load_dword v99, v[122:123], off offset:12 sc1
	v_lshl_add_u64 v[110:111], v[180:181], 0, v[0:1]
	s_waitcnt vmcnt(0)
	v_pk_add_f32 v[96:97], v[96:97], v[98:99]
	s_nop 0
	v_add_f32_e32 v96, v96, v97
	v_mov_b32_e32 v97, v96
	s_nop 1
	v_permlane16_swap_b32_e32 v96, v97
	s_waitcnt lgkmcnt(0)
	v_add_f32_e32 v98, v96, v97
	v_mov_b32_e32 v99, v98
	s_nop 1
	v_permlane32_swap_b32_e32 v98, v99
	v_lshlrev_b64 v[96:97], 12, v[154:155]
	v_lshl_add_u64 v[96:97], s[30:31], 0, v[96:97]
	v_lshl_add_u64 v[112:113], v[96:97], 0, v[88:89]
	s_waitcnt lgkmcnt(0)
	v_add_f32_e32 v98, v98, v99
	v_fmamk_f32 v98, v98, 0x3a800000, v249
	v_mul_f32_e32 v99, 0x4b800000, v98
	v_cmp_gt_f32_e32 vcc, s9, v98
	s_nop 1
	v_cndmask_b32_e32 v98, v98, v99, vcc
	v_rsq_f32_e32 v98, v98
	s_nop 0
	v_mul_f32_e32 v96, 0x45800000, v98
	v_cndmask_b32_e32 v96, v98, v96, vcc
	v_pk_mul_f32 v[98:99], v[100:101], v[96:97] op_sel_hi:[1,0]
	v_pk_mul_f32 v[94:95], v[94:95], v[96:97] op_sel_hi:[1,0]
	v_pk_mul_f32 v[102:103], v[116:117], v[96:97] op_sel_hi:[1,0]
	v_pk_mul_f32 v[100:101], v[104:105], v[96:97] op_sel_hi:[1,0]
	v_pk_mul_f32 v[106:107], v[134:135], v[96:97] op_sel_hi:[1,0]
	v_pk_mul_f32 v[104:105], v[130:131], v[96:97] op_sel_hi:[1,0]
	v_pk_mul_f32 v[114:115], v[170:171], v[96:97] op_sel_hi:[1,0]
	v_pk_mul_f32 v[108:109], v[144:145], v[96:97] op_sel_hi:[1,0]
	v_pk_mul_f32 v[96:97], v[16:17], v[94:95]
	v_pk_mul_f32 v[94:95], v[14:15], v[98:99]
	v_pk_mul_f32 v[100:101], v[8:9], v[100:101]
	v_pk_mul_f32 v[98:99], v[6:7], v[102:103]
	v_pk_mul_f32 v[104:105], v[12:13], v[104:105]
	v_pk_mul_f32 v[102:103], v[10:11], v[106:107]
	v_pk_mul_f32 v[108:109], v[4:5], v[108:109]
	v_pk_mul_f32 v[106:107], v[2:3], v[114:115]
	global_store_dwordx4 v[112:113], v[94:97], off
	global_store_dwordx4 v[112:113], v[98:101], off offset:16
	global_store_dwordx4 v[112:113], v[102:105], off offset:512
	global_store_dwordx4 v[112:113], v[106:109], off offset:528
	global_load_dword v94, v[110:111], off sc1
	s_nop 0
	global_load_dword v96, v[110:111], off offset:4 sc1
	global_load_dword v95, v[110:111], off offset:8 sc1
	global_load_dword v97, v[110:111], off offset:12 sc1
	s_waitcnt vmcnt(0)
	v_pk_add_f32 v[94:95], v[94:95], v[96:97]
	s_nop 0
	v_add_f32_e32 v94, v94, v95
	v_mov_b32_e32 v95, v94
	s_nop 1
	v_permlane16_swap_b32_e32 v94, v95
	s_waitcnt lgkmcnt(0)
	v_add_f32_e32 v96, v94, v95
	v_mov_b32_e32 v97, v96
	s_nop 1
	v_permlane32_swap_b32_e32 v96, v97
	v_lshlrev_b64 v[94:95], 12, v[136:137]
	v_lshl_add_u64 v[94:95], s[30:31], 0, v[94:95]
	v_lshl_add_u64 v[94:95], v[94:95], 0, v[88:89]
	s_waitcnt lgkmcnt(0)
	v_add_f32_e32 v96, v96, v97
	v_fmamk_f32 v96, v96, 0x3a800000, v249
	v_mul_f32_e32 v97, 0x4b800000, v96
	v_cmp_gt_f32_e32 vcc, s9, v96
	s_nop 1
	v_cndmask_b32_e32 v96, v96, v97, vcc
	v_rsq_f32_e32 v96, v96
	s_nop 0
	v_mul_f32_e32 v97, 0x45800000, v96
	v_cndmask_b32_e32 v96, v96, v97, vcc
	v_pk_mul_f32 v[62:63], v[62:63], v[96:97] op_sel_hi:[1,0]
	v_pk_mul_f32 v[64:65], v[64:65], v[96:97] op_sel_hi:[1,0]
	v_pk_mul_f32 v[58:59], v[58:59], v[96:97] op_sel_hi:[1,0]
	v_pk_mul_f32 v[60:61], v[60:61], v[96:97] op_sel_hi:[1,0]
	v_pk_mul_f32 v[98:99], v[54:55], v[96:97] op_sel_hi:[1,0]
	v_pk_mul_f32 v[100:101], v[56:57], v[96:97] op_sel_hi:[1,0]
	v_pk_mul_f32 v[102:103], v[50:51], v[96:97] op_sel_hi:[1,0]
	v_pk_mul_f32 v[96:97], v[52:53], v[96:97] op_sel_hi:[1,0]
	v_pk_mul_f32 v[52:53], v[16:17], v[64:65]
	v_pk_mul_f32 v[50:51], v[14:15], v[62:63]
	v_pk_mul_f32 v[56:57], v[8:9], v[60:61]
	v_pk_mul_f32 v[54:55], v[6:7], v[58:59]
	v_pk_mul_f32 v[60:61], v[12:13], v[100:101]
	v_pk_mul_f32 v[58:59], v[10:11], v[98:99]
	v_pk_mul_f32 v[64:65], v[4:5], v[96:97]
	v_pk_mul_f32 v[62:63], v[2:3], v[102:103]
	global_store_dwordx4 v[94:95], v[50:53], off
	global_store_dwordx4 v[94:95], v[54:57], off offset:16
	global_store_dwordx4 v[94:95], v[58:61], off offset:512
	global_store_dwordx4 v[94:95], v[62:65], off offset:528
	global_load_dword v50, v[82:83], off sc1
	s_nop 0
	global_load_dword v52, v[82:83], off offset:4 sc1
	global_load_dword v51, v[82:83], off offset:8 sc1
	global_load_dword v53, v[82:83], off offset:12 sc1
	s_waitcnt vmcnt(0)
	v_pk_add_f32 v[50:51], v[50:51], v[52:53]
	s_nop 0
	v_add_f32_e32 v50, v50, v51
	v_mov_b32_e32 v51, v50
	s_nop 1
	v_permlane16_swap_b32_e32 v50, v51
	s_waitcnt lgkmcnt(0)
	v_add_f32_e32 v52, v50, v51
	v_mov_b32_e32 v53, v52
	s_nop 1
	v_permlane32_swap_b32_e32 v52, v53
	v_lshlrev_b64 v[50:51], 12, v[132:133]
	v_lshl_add_u64 v[50:51], s[30:31], 0, v[50:51]
	v_lshl_add_u64 v[50:51], v[50:51], 0, v[88:89]
	s_waitcnt lgkmcnt(0)
	v_add_f32_e32 v52, v52, v53
	v_fmamk_f32 v52, v52, 0x3a800000, v249
	v_mul_f32_e32 v53, 0x4b800000, v52
	v_cmp_gt_f32_e32 vcc, s9, v52
	s_nop 1
	v_cndmask_b32_e32 v52, v52, v53, vcc
	v_rsq_f32_e32 v54, v52
	v_lshl_add_u64 v[52:53], v[84:85], 0, v[0:1]
	v_mul_f32_e32 v55, 0x45800000, v54
	v_cndmask_b32_e32 v54, v54, v55, vcc
	v_pk_mul_f32 v[46:47], v[46:47], v[54:55] op_sel_hi:[1,0]
	v_pk_mul_f32 v[48:49], v[48:49], v[54:55] op_sel_hi:[1,0]
	v_pk_mul_f32 v[42:43], v[42:43], v[54:55] op_sel_hi:[1,0]
	v_pk_mul_f32 v[44:45], v[44:45], v[54:55] op_sel_hi:[1,0]
	v_pk_mul_f32 v[56:57], v[38:39], v[54:55] op_sel_hi:[1,0]
	v_pk_mul_f32 v[58:59], v[40:41], v[54:55] op_sel_hi:[1,0]
	v_pk_mul_f32 v[60:61], v[34:35], v[54:55] op_sel_hi:[1,0]
	v_pk_mul_f32 v[54:55], v[36:37], v[54:55] op_sel_hi:[1,0]
	v_pk_mul_f32 v[36:37], v[16:17], v[48:49]
	v_pk_mul_f32 v[34:35], v[14:15], v[46:47]
	v_pk_mul_f32 v[40:41], v[8:9], v[44:45]
	v_pk_mul_f32 v[38:39], v[6:7], v[42:43]
	v_pk_mul_f32 v[44:45], v[12:13], v[58:59]
	v_pk_mul_f32 v[42:43], v[10:11], v[56:57]
	v_pk_mul_f32 v[48:49], v[4:5], v[54:55]
	v_pk_mul_f32 v[46:47], v[2:3], v[60:61]
	global_store_dwordx4 v[50:51], v[34:37], off
	global_store_dwordx4 v[50:51], v[38:41], off offset:16
	global_store_dwordx4 v[50:51], v[42:45], off offset:512
	global_store_dwordx4 v[50:51], v[46:49], off offset:528
	global_load_dword v34, v[52:53], off sc1
	s_nop 0
	global_load_dword v36, v[52:53], off offset:4 sc1
	global_load_dword v35, v[52:53], off offset:8 sc1
	global_load_dword v37, v[52:53], off offset:12 sc1
	s_waitcnt vmcnt(0)
	v_pk_add_f32 v[34:35], v[34:35], v[36:37]
	s_nop 0
	v_add_f32_e32 v34, v34, v35
	v_mov_b32_e32 v35, v34
	s_nop 1
	v_permlane16_swap_b32_e32 v34, v35
	s_waitcnt lgkmcnt(0)
	v_add_f32_e32 v36, v34, v35
	v_mov_b32_e32 v37, v36
	s_nop 1
	v_permlane32_swap_b32_e32 v36, v37
	v_lshlrev_b64 v[34:35], 12, v[92:93]
	v_lshl_add_u64 v[34:35], s[30:31], 0, v[34:35]
	v_lshl_add_u64 v[34:35], v[34:35], 0, v[88:89]
	s_waitcnt lgkmcnt(0)
	v_add_f32_e32 v36, v36, v37
	v_fmamk_f32 v36, v36, 0x3a800000, v249
	v_mul_f32_e32 v37, 0x4b800000, v36
	v_cmp_gt_f32_e32 vcc, s9, v36
	s_nop 1
	v_cndmask_b32_e32 v36, v36, v37, vcc
	v_rsq_f32_e32 v38, v36
	v_lshl_add_u64 v[36:37], v[86:87], 0, v[0:1]
	v_mul_f32_e32 v0, 0x45800000, v38
	v_cndmask_b32_e32 v0, v38, v0, vcc
	v_pk_mul_f32 v[30:31], v[30:31], v[0:1] op_sel_hi:[1,0]
	v_pk_mul_f32 v[32:33], v[32:33], v[0:1] op_sel_hi:[1,0]
	v_pk_mul_f32 v[26:27], v[26:27], v[0:1] op_sel_hi:[1,0]
	v_pk_mul_f32 v[28:29], v[28:29], v[0:1] op_sel_hi:[1,0]
	v_pk_mul_f32 v[38:39], v[22:23], v[0:1] op_sel_hi:[1,0]
	v_pk_mul_f32 v[40:41], v[24:25], v[0:1] op_sel_hi:[1,0]
	v_pk_mul_f32 v[42:43], v[18:19], v[0:1] op_sel_hi:[1,0]
	v_pk_mul_f32 v[44:45], v[20:21], v[0:1] op_sel_hi:[1,0]
	v_pk_mul_f32 v[20:21], v[16:17], v[32:33]
	v_pk_mul_f32 v[18:19], v[14:15], v[30:31]
	v_pk_mul_f32 v[24:25], v[8:9], v[28:29]
	v_pk_mul_f32 v[22:23], v[6:7], v[26:27]
	v_pk_mul_f32 v[28:29], v[12:13], v[40:41]
	v_pk_mul_f32 v[26:27], v[10:11], v[38:39]
	v_pk_mul_f32 v[32:33], v[4:5], v[44:45]
	v_pk_mul_f32 v[30:31], v[2:3], v[42:43]
	global_store_dwordx4 v[34:35], v[18:21], off
	global_store_dwordx4 v[34:35], v[22:25], off offset:16
	global_store_dwordx4 v[34:35], v[26:29], off offset:512
	global_store_dwordx4 v[34:35], v[30:33], off offset:528
	global_load_dword v18, v[36:37], off sc1
	s_nop 0
	global_load_dword v20, v[36:37], off offset:4 sc1
	global_load_dword v19, v[36:37], off offset:8 sc1
	global_load_dword v21, v[36:37], off offset:12 sc1
	s_waitcnt vmcnt(0)
	v_pk_add_f32 v[18:19], v[18:19], v[20:21]
	s_nop 0
	v_add_f32_e32 v0, v18, v19
	v_mov_b32_e32 v18, v0
	s_nop 1
	v_permlane16_swap_b32_e32 v0, v18
	s_waitcnt lgkmcnt(0)
	v_add_f32_e32 v0, v0, v18
	v_mov_b32_e32 v18, v0
	s_nop 1
	v_permlane32_swap_b32_e32 v0, v18
	s_waitcnt lgkmcnt(0)
	v_add_f32_e32 v0, v0, v18
	v_fmamk_f32 v0, v0, 0x3a800000, v249
	v_mul_f32_e32 v18, 0x4b800000, v0
	v_cmp_gt_f32_e32 vcc, s9, v0
	s_nop 1
	v_cndmask_b32_e32 v0, v0, v18, vcc
	v_rsq_f32_e32 v0, v0
	v_lshlrev_b64 v[18:19], 12, v[90:91]
	v_lshl_add_u64 v[18:19], s[30:31], 0, v[18:19]
	v_lshl_add_u64 v[18:19], v[18:19], 0, v[88:89]
	v_mul_f32_e32 v20, 0x45800000, v0
	v_cndmask_b32_e32 v0, v0, v20, vcc
	v_pk_mul_f32 v[20:21], v[68:69], v[0:1] op_sel_hi:[1,0]
	v_pk_mul_f32 v[22:23], v[66:67], v[0:1] op_sel_hi:[1,0]
	v_pk_mul_f32 v[24:25], v[74:75], v[0:1] op_sel_hi:[1,0]
	v_pk_mul_f32 v[26:27], v[70:71], v[0:1] op_sel_hi:[1,0]
	v_pk_mul_f32 v[28:29], v[78:79], v[0:1] op_sel_hi:[1,0]
	v_pk_mul_f32 v[30:31], v[72:73], v[0:1] op_sel_hi:[1,0]
	v_pk_mul_f32 v[32:33], v[80:81], v[0:1] op_sel_hi:[1,0]
	v_pk_mul_f32 v[34:35], v[76:77], v[0:1] op_sel_hi:[1,0]
	v_pk_mul_f32 v[16:17], v[16:17], v[22:23]
	v_pk_mul_f32 v[14:15], v[14:15], v[20:21]
	v_pk_mul_f32 v[8:9], v[8:9], v[26:27]
	v_pk_mul_f32 v[6:7], v[6:7], v[24:25]
	v_pk_mul_f32 v[12:13], v[12:13], v[30:31]
	v_pk_mul_f32 v[10:11], v[10:11], v[28:29]
	v_pk_mul_f32 v[4:5], v[4:5], v[34:35]
	v_pk_mul_f32 v[2:3], v[2:3], v[32:33]
	global_store_dwordx4 v[18:19], v[14:17], off
	global_store_dwordx4 v[18:19], v[6:9], off offset:16
	global_store_dwordx4 v[18:19], v[10:13], off offset:512
	global_store_dwordx4 v[18:19], v[2:5], off offset:528

.LBB0_514:
	s_lshl_b32 s10, s16, 8
	v_add_u32_e32 v130, s10, v228
	v_ashrrev_i32_e32 v131, 31, v130
	v_readlane_b32 s16, v255, 40
	v_lshlrev_b64 v[132:133], 6, v[130:131]
	v_readlane_b32 s17, v255, 41
	v_mov_b32_e32 v137, v1
	s_barrier
	v_lshl_add_u64 v[132:133], s[16:17], 0, v[132:133]
	v_lshl_add_u64 v[132:133], v[132:133], 0, v[136:137]
	global_load_dwordx4 v[132:135], v[132:133], off
	v_cmp_lt_i32_e32 vcc, v218, v213
	s_mov_b32 s53, 0x800000
	s_mov_b32 s11, 0xff800000
	v_cndmask_b32_e32 v0, v211, v218, vcc
	v_lshlrev_b32_e32 v236, 2, v0
	v_cmp_lt_i32_e32 vcc, v219, v213
	s_lshl_b32 s5, s4, 2
	s_add_i32 s5, s5, 0
	s_waitcnt vmcnt(0)
	v_mov_b32_e32 v136, v133
	v_mov_b32_e32 v137, v134
	v_mov_b32_e32 v133, v135
	v_pk_add_f32 v[132:133], v[136:137], v[132:133]
	s_nop 0
	v_add_f32_e32 v0, v132, v133
	v_mov_b32_e32 v132, v0
	s_nop 1
	v_permlane16_swap_b32_e32 v0, v132
	v_cndmask_b32_e32 v133, v211, v219, vcc
	v_lshlrev_b32_e32 v237, 2, v133
	s_waitcnt lgkmcnt(0)
	v_add_f32_e32 v0, v0, v132
	v_mov_b32_e32 v132, v0
	s_nop 1
	v_permlane32_swap_b32_e32 v0, v132
	s_waitcnt lgkmcnt(0)
	v_add_f32_e32 v0, v0, v132
	v_fmamk_f32 v0, v0, 0x3a800000, v249
	v_mul_f32_e32 v132, 0x4b800000, v0
	v_cmp_gt_f32_e32 vcc, s53, v0
	s_nop 1
	v_cndmask_b32_e32 v0, v0, v132, vcc
	v_rsq_f32_e32 v0, v0
	s_nop 0
	v_mul_f32_e32 v132, 0x45800000, v0
	v_cndmask_b32_e32 v0, v0, v132, vcc
	v_mul_f32_e32 v0, 0x3db8aa3b, v0
	v_pk_mul_f32 v[128:129], v[128:129], v[0:1] op_sel_hi:[1,0]
	v_pk_mul_f32 v[124:125], v[124:125], v[0:1] op_sel_hi:[1,0]
	v_pk_mul_f32 v[132:133], v[126:127], v[0:1] op_sel_hi:[1,0]
	v_pk_mul_f32 v[126:127], v[122:123], v[0:1] op_sel_hi:[1,0]
	v_pk_mul_f32 v[120:121], v[120:121], v[0:1] op_sel_hi:[1,0]
	v_pk_mul_f32 v[122:123], v[118:119], v[0:1] op_sel_hi:[1,0]
	v_pk_mul_f32 v[116:117], v[116:117], v[0:1] op_sel_hi:[1,0]
	v_pk_mul_f32 v[118:119], v[114:115], v[0:1] op_sel_hi:[1,0]
	v_max_f32_e32 v0, v128, v129
	v_max_f32_e32 v114, v124, v125
	v_max_f32_e32 v115, v120, v121
	v_max_f32_e32 v134, v116, v117
	v_max3_f32 v0, v132, v133, v0
	v_max3_f32 v114, v126, v127, v114
	v_max3_f32 v115, v122, v123, v115
	v_max3_f32 v0, v0, s11, v114
	v_max3_f32 v114, v118, v119, v134
	v_max3_f32 v0, v0, v115, v114
	v_mov_b32_e32 v114, v0
	s_nop 1
	v_permlane16_swap_b32_e32 v0, v114
	v_cmp_eq_u32_e32 vcc, 0, v195
	s_waitcnt lgkmcnt(0)
	v_max_f32_e32 v114, v114, v114
	v_max_f32_e32 v0, v0, v114
	v_mov_b32_e32 v114, v0
	s_nop 1
	v_permlane32_swap_b32_e32 v0, v114
	s_and_saveexec_b64 s[16:17], vcc
	s_cbranch_execz .LBB0_516
	s_waitcnt lgkmcnt(0)
	v_max_f32_e32 v114, v114, v114
	v_max_f32_e32 v0, v0, v0
	v_lshl_add_u32 v115, v228, 4, s5
	v_max_f32_e32 v0, v0, v114
	ds_write_b32 v115, v0
.LBB0_516:
	s_or_b64 exec, exec, s[16:17]
	v_or_b32_e32 v235, 16, v228
	s_waitcnt lgkmcnt(0)
	v_add_u32_e32 v114, s10, v235
	v_ashrrev_i32_e32 v115, 31, v114
	v_readlane_b32 s16, v255, 40
	v_lshlrev_b32_e32 v0, 2, v195
	v_lshlrev_b64 v[134:135], 6, v[114:115]
	v_readlane_b32 s17, v255, 41
	v_lshlrev_b32_e32 v0, 2, v0
	s_nop 0
	v_lshl_add_u64 v[134:135], s[16:17], 0, v[134:135]
	v_lshl_add_u64 v[134:135], v[134:135], 0, v[0:1]
	global_load_dwordx4 v[134:137], v[134:135], off
	s_waitcnt vmcnt(0)
	v_mov_b32_e32 v138, v135
	v_mov_b32_e32 v139, v136
	v_mov_b32_e32 v135, v137
	v_pk_add_f32 v[134:135], v[138:139], v[134:135]
	s_nop 0
	v_add_f32_e32 v134, v134, v135
	v_mov_b32_e32 v135, v134
	s_nop 1
	v_permlane16_swap_b32_e32 v134, v135
	s_waitcnt lgkmcnt(0)
	v_add_f32_e32 v134, v134, v135
	v_mov_b32_e32 v135, v134
	s_nop 1
	v_permlane32_swap_b32_e32 v134, v135
	s_waitcnt lgkmcnt(0)
	v_add_f32_e32 v134, v134, v135
	v_fmamk_f32 v134, v134, 0x3a800000, v249
	v_mul_f32_e32 v135, 0x4b800000, v134
	v_cmp_gt_f32_e64 s[42:43], s53, v134
	s_nop 1
	v_cndmask_b32_e64 v134, v134, v135, s[42:43]
	v_rsq_f32_e32 v134, v134
	s_nop 0
	v_mul_f32_e32 v135, 0x45800000, v134
	v_cndmask_b32_e64 v134, v134, v135, s[42:43]
	v_mul_f32_e32 v140, 0x3db8aa3b, v134
	v_pk_mul_f32 v[136:137], v[112:113], v[140:141] op_sel_hi:[1,0]
	v_pk_mul_f32 v[108:109], v[108:109], v[140:141] op_sel_hi:[1,0]
	v_pk_mul_f32 v[138:139], v[110:111], v[140:141] op_sel_hi:[1,0]
	v_pk_mul_f32 v[134:135], v[106:107], v[140:141] op_sel_hi:[1,0]
	v_pk_mul_f32 v[104:105], v[104:105], v[140:141] op_sel_hi:[1,0]
	v_pk_mul_f32 v[110:111], v[100:101], v[140:141] op_sel_hi:[1,0]
	v_pk_mul_f32 v[112:113], v[98:99], v[140:141] op_sel_hi:[1,0]
	v_max_f32_e32 v98, v136, v137
	v_max_f32_e32 v99, v108, v109
	v_pk_mul_f32 v[106:107], v[102:103], v[140:141] op_sel_hi:[1,0]
	v_max_f32_e32 v100, v104, v105
	v_max_f32_e32 v101, v110, v111
	v_max3_f32 v98, v138, v139, v98
	v_max3_f32 v99, v134, v135, v99
	v_max3_f32 v100, v106, v107, v100
	v_max3_f32 v98, v98, s11, v99
	v_max3_f32 v99, v112, v113, v101
	v_max3_f32 v98, v98, v100, v99
	v_mov_b32_e32 v99, v98
	s_nop 1
	v_permlane16_swap_b32_e32 v98, v99
	s_waitcnt lgkmcnt(0)
	v_max_f32_e32 v99, v99, v99
	v_max_f32_e32 v98, v98, v99
	v_mov_b32_e32 v99, v98
	s_nop 1
	v_permlane32_swap_b32_e32 v98, v99
	s_and_saveexec_b64 s[16:17], vcc
	s_cbranch_execz .LBB0_518
	s_waitcnt lgkmcnt(0)
	v_max_f32_e32 v99, v99, v99
	v_max_f32_e32 v98, v98, v98
	v_lshl_add_u32 v100, v235, 4, s5
	v_max_f32_e32 v98, v98, v99
	ds_write_b32 v100, v98
.LBB0_518:
	s_or_b64 exec, exec, s[16:17]
	v_or_b32_e32 v234, 32, v228
	v_add_u32_e32 v98, s10, v234
	s_waitcnt lgkmcnt(0)
	v_ashrrev_i32_e32 v99, 31, v98
	v_readlane_b32 s16, v255, 40
	v_lshlrev_b64 v[100:101], 6, v[98:99]
	v_readlane_b32 s17, v255, 41
	s_nop 1
	v_lshl_add_u64 v[100:101], s[16:17], 0, v[100:101]
	v_lshl_add_u64 v[100:101], v[100:101], 0, v[0:1]
	global_load_dwordx4 v[100:103], v[100:101], off
	s_waitcnt vmcnt(0)
	v_mov_b32_e32 v140, v101
	v_mov_b32_e32 v141, v102
	v_mov_b32_e32 v101, v103
	v_pk_add_f32 v[100:101], v[140:141], v[100:101]
	s_nop 0
	v_add_f32_e32 v100, v100, v101
	v_mov_b32_e32 v101, v100
	s_nop 1
	v_permlane16_swap_b32_e32 v100, v101
	s_waitcnt lgkmcnt(0)
	v_add_f32_e32 v100, v100, v101
	v_mov_b32_e32 v101, v100
	s_nop 1
	v_permlane32_swap_b32_e32 v100, v101
	s_waitcnt lgkmcnt(0)
	v_add_f32_e32 v100, v100, v101
	v_fmamk_f32 v100, v100, 0x3a800000, v249
	v_mul_f32_e32 v101, 0x4b800000, v100
	v_cmp_gt_f32_e64 s[42:43], s53, v100
	s_nop 1
	v_cndmask_b32_e64 v100, v100, v101, s[42:43]
	v_rsq_f32_e32 v100, v100
	s_nop 0
	v_mul_f32_e32 v101, 0x45800000, v100
	v_cndmask_b32_e64 v100, v100, v101, s[42:43]
	v_mul_f32_e32 v100, 0x3db8aa3b, v100
	v_pk_mul_f32 v[142:143], v[96:97], v[100:101] op_sel_hi:[1,0]
	v_pk_mul_f32 v[92:93], v[92:93], v[100:101] op_sel_hi:[1,0]
	v_pk_mul_f32 v[144:145], v[94:95], v[100:101] op_sel_hi:[1,0]
	v_pk_mul_f32 v[140:141], v[90:91], v[100:101] op_sel_hi:[1,0]
	v_pk_mul_f32 v[88:89], v[88:89], v[100:101] op_sel_hi:[1,0]
	v_pk_mul_f32 v[90:91], v[86:87], v[100:101] op_sel_hi:[1,0]
	v_pk_mul_f32 v[84:85], v[84:85], v[100:101] op_sel_hi:[1,0]
	v_pk_mul_f32 v[86:87], v[82:83], v[100:101] op_sel_hi:[1,0]
	v_max_f32_e32 v82, v142, v143
	v_max_f32_e32 v83, v92, v93
	v_max_f32_e32 v94, v88, v89
	v_max_f32_e32 v95, v84, v85
	v_max3_f32 v82, v144, v145, v82
	v_max3_f32 v83, v140, v141, v83
	v_max3_f32 v94, v90, v91, v94
	v_max3_f32 v82, v82, s11, v83
	v_max3_f32 v83, v86, v87, v95
	v_max3_f32 v82, v82, v94, v83
	v_mov_b32_e32 v83, v82
	s_nop 1
	v_permlane16_swap_b32_e32 v82, v83
	s_waitcnt lgkmcnt(0)
	v_max_f32_e32 v83, v83, v83
	v_max_f32_e32 v82, v82, v83
	v_mov_b32_e32 v83, v82
	s_nop 1
	v_permlane32_swap_b32_e32 v82, v83
	s_and_saveexec_b64 s[16:17], vcc
	s_cbranch_execz .LBB0_520
	s_waitcnt lgkmcnt(0)
	v_max_f32_e32 v83, v83, v83
	v_max_f32_e32 v82, v82, v82
	v_lshl_add_u32 v94, v234, 4, s5
	v_max_f32_e32 v82, v82, v83
	ds_write_b32 v94, v82
.LBB0_520:
	s_or_b64 exec, exec, s[16:17]
	v_or_b32_e32 v233, 48, v228
	v_add_u32_e32 v82, s10, v233
	s_waitcnt lgkmcnt(0)
	v_ashrrev_i32_e32 v83, 31, v82
	v_readlane_b32 s16, v255, 40
	v_lshlrev_b64 v[94:95], 6, v[82:83]
	v_readlane_b32 s17, v255, 41
	s_nop 1
	v_lshl_add_u64 v[94:95], s[16:17], 0, v[94:95]
	v_lshl_add_u64 v[94:95], v[94:95], 0, v[0:1]
	global_load_dwordx4 v[94:97], v[94:95], off
	s_waitcnt vmcnt(0)
	v_mov_b32_e32 v100, v95
	v_mov_b32_e32 v101, v96
	v_mov_b32_e32 v95, v97
	v_pk_add_f32 v[94:95], v[100:101], v[94:95]
	s_nop 0
	v_add_f32_e32 v94, v94, v95
	v_mov_b32_e32 v95, v94
	s_nop 1
	v_permlane16_swap_b32_e32 v94, v95
	s_waitcnt lgkmcnt(0)
	v_add_f32_e32 v94, v94, v95
	v_mov_b32_e32 v95, v94
	s_nop 1
	v_permlane32_swap_b32_e32 v94, v95
	s_waitcnt lgkmcnt(0)
	v_add_f32_e32 v94, v94, v95
	v_fmamk_f32 v94, v94, 0x3a800000, v249
	v_mul_f32_e32 v95, 0x4b800000, v94
	v_cmp_gt_f32_e64 s[42:43], s53, v94
	s_nop 1
	v_cndmask_b32_e64 v94, v94, v95, s[42:43]
	v_rsq_f32_e32 v94, v94
	s_nop 0
	v_mul_f32_e32 v95, 0x45800000, v94
	v_cndmask_b32_e64 v94, v94, v95, s[42:43]
	v_mul_f32_e32 v94, 0x3db8aa3b, v94
	v_pk_mul_f32 v[146:147], v[80:81], v[94:95] op_sel_hi:[1,0]
	v_pk_mul_f32 v[152:153], v[78:79], v[94:95] op_sel_hi:[1,0]
	v_pk_mul_f32 v[78:79], v[76:77], v[94:95] op_sel_hi:[1,0]
	v_pk_mul_f32 v[80:81], v[74:75], v[94:95] op_sel_hi:[1,0]
	v_pk_mul_f32 v[76:77], v[72:73], v[94:95] op_sel_hi:[1,0]
	v_pk_mul_f32 v[74:75], v[68:69], v[94:95] op_sel_hi:[1,0]
	v_pk_mul_f32 v[68:69], v[66:67], v[94:95] op_sel_hi:[1,0]
	v_max_f32_e32 v66, v146, v147
	v_max_f32_e32 v67, v78, v79
	v_pk_mul_f32 v[70:71], v[70:71], v[94:95] op_sel_hi:[1,0]
	v_max_f32_e32 v72, v76, v77
	v_max_f32_e32 v73, v74, v75
	v_max3_f32 v66, v152, v153, v66
	v_max3_f32 v67, v80, v81, v67
	v_max3_f32 v72, v70, v71, v72
	v_max3_f32 v66, v66, s11, v67
	v_max3_f32 v67, v68, v69, v73
	v_max3_f32 v66, v66, v72, v67
	v_mov_b32_e32 v67, v66
	s_nop 1
	v_permlane16_swap_b32_e32 v66, v67
	s_waitcnt lgkmcnt(0)
	v_max_f32_e32 v67, v67, v67
	v_max_f32_e32 v66, v66, v67
	v_mov_b32_e32 v67, v66
	s_nop 1
	v_permlane32_swap_b32_e32 v66, v67
	s_and_saveexec_b64 s[16:17], vcc
	s_cbranch_execz .LBB0_522
	s_waitcnt lgkmcnt(0)
	v_max_f32_e32 v67, v67, v67
	v_max_f32_e32 v66, v66, v66
	v_lshl_add_u32 v72, v233, 4, s5
	v_max_f32_e32 v66, v66, v67
	ds_write_b32 v72, v66
.LBB0_522:
	s_or_b64 exec, exec, s[16:17]
	v_add_u32_e32 v232, 0x80, v228
	v_add_u32_e32 v66, s10, v232
	s_waitcnt lgkmcnt(0)
	v_ashrrev_i32_e32 v67, 31, v66
	v_readlane_b32 s16, v255, 40
	v_lshlrev_b64 v[72:73], 6, v[66:67]
	v_readlane_b32 s17, v255, 41
	s_nop 1
	v_lshl_add_u64 v[72:73], s[16:17], 0, v[72:73]
	v_lshl_add_u64 v[72:73], v[72:73], 0, v[0:1]
	global_load_dwordx4 v[94:97], v[72:73], off
	s_waitcnt vmcnt(0)
	v_mov_b32_e32 v72, v95
	v_mov_b32_e32 v73, v96
	v_mov_b32_e32 v95, v97
	v_pk_add_f32 v[72:73], v[72:73], v[94:95]
	s_nop 0
	v_add_f32_e32 v72, v72, v73
	v_mov_b32_e32 v73, v72
	s_nop 1
	v_permlane16_swap_b32_e32 v72, v73
	s_waitcnt lgkmcnt(0)
	v_add_f32_e32 v72, v72, v73
	v_mov_b32_e32 v73, v72
	s_nop 1
	v_permlane32_swap_b32_e32 v72, v73
	s_waitcnt lgkmcnt(0)
	v_add_f32_e32 v72, v72, v73
	v_fmamk_f32 v72, v72, 0x3a800000, v249
	v_mul_f32_e32 v73, 0x4b800000, v72
	v_cmp_gt_f32_e64 s[42:43], s53, v72
	s_nop 1
	v_cndmask_b32_e64 v72, v72, v73, s[42:43]
	v_rsq_f32_e32 v72, v72
	s_nop 0
	v_mul_f32_e32 v73, 0x45800000, v72
	v_cndmask_b32_e64 v72, v72, v73, s[42:43]
	v_mul_f32_e32 v72, 0x3db8aa3b, v72
	v_pk_mul_f32 v[158:159], v[64:65], v[72:73] op_sel_hi:[1,0]
	v_pk_mul_f32 v[148:149], v[60:61], v[72:73] op_sel_hi:[1,0]
	v_pk_mul_f32 v[166:167], v[62:63], v[72:73] op_sel_hi:[1,0]
	v_pk_mul_f32 v[154:155], v[58:59], v[72:73] op_sel_hi:[1,0]
	v_pk_mul_f32 v[56:57], v[56:57], v[72:73] op_sel_hi:[1,0]
	v_pk_mul_f32 v[150:151], v[54:55], v[72:73] op_sel_hi:[1,0]
	v_pk_mul_f32 v[52:53], v[52:53], v[72:73] op_sel_hi:[1,0]
	v_pk_mul_f32 v[54:55], v[50:51], v[72:73] op_sel_hi:[1,0]
	v_max_f32_e32 v50, v158, v159
	v_max_f32_e32 v51, v148, v149
	v_max_f32_e32 v58, v56, v57
	v_max_f32_e32 v59, v52, v53
	v_max3_f32 v50, v166, v167, v50
	v_max3_f32 v51, v154, v155, v51
	v_max3_f32 v58, v150, v151, v58
	v_max3_f32 v50, v50, s11, v51
	v_max3_f32 v51, v54, v55, v59
	v_max3_f32 v50, v50, v58, v51
	v_mov_b32_e32 v51, v50
	s_nop 1
	v_permlane16_swap_b32_e32 v50, v51
	s_waitcnt lgkmcnt(0)
	v_max_f32_e32 v51, v51, v51
	v_max_f32_e32 v50, v50, v51
	v_mov_b32_e32 v51, v50
	s_nop 1
	v_permlane32_swap_b32_e32 v50, v51
	s_and_saveexec_b64 s[16:17], vcc
	s_cbranch_execz .LBB0_524
	s_waitcnt lgkmcnt(0)
	v_max_f32_e32 v51, v51, v51
	v_max_f32_e32 v50, v50, v50
	v_lshl_add_u32 v58, v232, 4, s5
	v_max_f32_e32 v50, v50, v51
	ds_write_b32 v58, v50
.LBB0_524:
	s_or_b64 exec, exec, s[16:17]
	v_add_u32_e32 v231, 0x90, v228
	v_add_u32_e32 v50, s10, v231
	s_waitcnt lgkmcnt(0)
	v_ashrrev_i32_e32 v51, 31, v50
	v_readlane_b32 s16, v255, 40
	v_lshlrev_b64 v[58:59], 6, v[50:51]
	v_readlane_b32 s17, v255, 41
	s_nop 1
	v_lshl_add_u64 v[58:59], s[16:17], 0, v[58:59]
	v_lshl_add_u64 v[58:59], v[58:59], 0, v[0:1]
	global_load_dwordx4 v[58:61], v[58:59], off
	s_waitcnt vmcnt(0)
	v_mov_b32_e32 v62, v59
	v_mov_b32_e32 v63, v60
	v_mov_b32_e32 v59, v61
	v_pk_add_f32 v[58:59], v[62:63], v[58:59]
	s_nop 0
	v_add_f32_e32 v58, v58, v59
	v_mov_b32_e32 v59, v58
	s_nop 1
	v_permlane16_swap_b32_e32 v58, v59
	s_waitcnt lgkmcnt(0)
	v_add_f32_e32 v58, v58, v59
	v_mov_b32_e32 v59, v58
	s_nop 1
	v_permlane32_swap_b32_e32 v58, v59
	s_waitcnt lgkmcnt(0)
	v_add_f32_e32 v58, v58, v59
	v_fmamk_f32 v58, v58, 0x3a800000, v249
	v_mul_f32_e32 v59, 0x4b800000, v58
	v_cmp_gt_f32_e64 s[42:43], s53, v58
	s_nop 1
	v_cndmask_b32_e64 v58, v58, v59, s[42:43]
	v_rsq_f32_e32 v58, v58
	s_nop 0
	v_mul_f32_e32 v59, 0x45800000, v58
	v_cndmask_b32_e64 v58, v58, v59, s[42:43]
	v_mul_f32_e32 v58, 0x3db8aa3b, v58
	v_pk_mul_f32 v[168:169], v[48:49], v[58:59] op_sel_hi:[1,0]
	v_pk_mul_f32 v[44:45], v[44:45], v[58:59] op_sel_hi:[1,0]
	v_pk_mul_f32 v[182:183], v[46:47], v[58:59] op_sel_hi:[1,0]
	v_pk_mul_f32 v[48:49], v[42:43], v[58:59] op_sel_hi:[1,0]
	v_pk_mul_f32 v[40:41], v[40:41], v[58:59] op_sel_hi:[1,0]
	v_pk_mul_f32 v[46:47], v[38:39], v[58:59] op_sel_hi:[1,0]
	v_pk_mul_f32 v[38:39], v[36:37], v[58:59] op_sel_hi:[1,0]
	v_pk_mul_f32 v[42:43], v[34:35], v[58:59] op_sel_hi:[1,0]
	v_max_f32_e32 v34, v168, v169
	v_max_f32_e32 v35, v44, v45
	v_max_f32_e32 v36, v40, v41
	v_max_f32_e32 v37, v38, v39
	v_max3_f32 v34, v182, v183, v34
	v_max3_f32 v35, v48, v49, v35
	v_max3_f32 v36, v46, v47, v36
	v_max3_f32 v34, v34, s11, v35
	v_max3_f32 v35, v42, v43, v37
	v_max3_f32 v34, v34, v36, v35
	v_mov_b32_e32 v35, v34
	s_nop 1
	v_permlane16_swap_b32_e32 v34, v35
	s_waitcnt lgkmcnt(0)
	v_max_f32_e32 v35, v35, v35
	v_max_f32_e32 v34, v34, v35
	v_mov_b32_e32 v35, v34
	s_nop 1
	v_permlane32_swap_b32_e32 v34, v35
	s_and_saveexec_b64 s[16:17], vcc
	s_cbranch_execz .LBB0_526
	s_waitcnt lgkmcnt(0)
	v_max_f32_e32 v35, v35, v35
	v_max_f32_e32 v34, v34, v34
	v_lshl_add_u32 v36, v231, 4, s5
	v_max_f32_e32 v34, v34, v35
	ds_write_b32 v36, v34
.LBB0_526:
	s_or_b64 exec, exec, s[16:17]
	v_add_u32_e32 v230, 0xa0, v228
	v_add_u32_e32 v34, s10, v230
	s_waitcnt lgkmcnt(0)
	v_ashrrev_i32_e32 v35, 31, v34
	v_readlane_b32 s16, v255, 40
	v_lshlrev_b64 v[36:37], 6, v[34:35]
	v_readlane_b32 s17, v255, 41
	s_nop 1
	v_lshl_add_u64 v[36:37], s[16:17], 0, v[36:37]
	v_lshl_add_u64 v[36:37], v[36:37], 0, v[0:1]
	global_load_dwordx4 v[58:61], v[36:37], off
	s_waitcnt vmcnt(0)
	v_mov_b32_e32 v36, v59
	v_mov_b32_e32 v37, v60
	v_mov_b32_e32 v59, v61
	v_pk_add_f32 v[36:37], v[36:37], v[58:59]
	s_nop 0
	v_add_f32_e32 v36, v36, v37
	v_mov_b32_e32 v37, v36
	s_nop 1
	v_permlane16_swap_b32_e32 v36, v37
	s_waitcnt lgkmcnt(0)
	v_add_f32_e32 v36, v36, v37
	v_mov_b32_e32 v37, v36
	s_nop 1
	v_permlane32_swap_b32_e32 v36, v37
	s_waitcnt lgkmcnt(0)
	v_add_f32_e32 v36, v36, v37
	v_fmamk_f32 v36, v36, 0x3a800000, v249
	v_mul_f32_e32 v37, 0x4b800000, v36
	v_cmp_gt_f32_e64 s[42:43], s53, v36
	s_nop 1
	v_cndmask_b32_e64 v36, v36, v37, s[42:43]
	v_rsq_f32_e32 v36, v36
	s_nop 0
	v_mul_f32_e32 v37, 0x45800000, v36
	v_cndmask_b32_e64 v36, v36, v37, s[42:43]
	v_mul_f32_e32 v36, 0x3db8aa3b, v36
	v_pk_mul_f32 v[186:187], v[32:33], v[36:37] op_sel_hi:[1,0]
	v_pk_mul_f32 v[170:171], v[28:29], v[36:37] op_sel_hi:[1,0]
	v_pk_mul_f32 v[198:199], v[30:31], v[36:37] op_sel_hi:[1,0]
	v_pk_mul_f32 v[184:185], v[26:27], v[36:37] op_sel_hi:[1,0]
	v_pk_mul_f32 v[162:163], v[24:25], v[36:37] op_sel_hi:[1,0]
	v_pk_mul_f32 v[20:21], v[20:21], v[36:37] op_sel_hi:[1,0]
	v_pk_mul_f32 v[164:165], v[18:19], v[36:37] op_sel_hi:[1,0]
	v_max_f32_e32 v18, v186, v187
	v_max_f32_e32 v19, v170, v171
	v_pk_mul_f32 v[176:177], v[22:23], v[36:37] op_sel_hi:[1,0]
	v_max_f32_e32 v22, v162, v163
	v_max_f32_e32 v23, v20, v21
	v_max3_f32 v18, v198, v199, v18
	v_max3_f32 v19, v184, v185, v19
	v_max3_f32 v22, v176, v177, v22
	v_max3_f32 v18, v18, s11, v19
	v_max3_f32 v19, v164, v165, v23
	v_max3_f32 v18, v18, v22, v19
	v_mov_b32_e32 v19, v18
	s_nop 1
	v_permlane16_swap_b32_e32 v18, v19
	s_waitcnt lgkmcnt(0)
	v_max_f32_e32 v19, v19, v19
	v_max_f32_e32 v18, v18, v19
	v_mov_b32_e32 v19, v18
	s_nop 1
	v_permlane32_swap_b32_e32 v18, v19
	s_and_saveexec_b64 s[16:17], vcc
	s_cbranch_execz .LBB0_528
	s_waitcnt lgkmcnt(0)
	v_max_f32_e32 v19, v19, v19
	v_max_f32_e32 v18, v18, v18
	v_lshl_add_u32 v22, v230, 4, s5
	v_max_f32_e32 v18, v18, v19
	ds_write_b32 v22, v18
.LBB0_528:
	s_or_b64 exec, exec, s[16:17]
	v_add_u32_e32 v229, 0xb0, v228
	v_add_u32_e32 v18, s10, v229
	s_waitcnt lgkmcnt(0)
	v_ashrrev_i32_e32 v19, 31, v18
	v_readlane_b32 s16, v255, 40
	v_lshlrev_b64 v[22:23], 6, v[18:19]
	v_readlane_b32 s17, v255, 41
	s_nop 1
	v_lshl_add_u64 v[22:23], s[16:17], 0, v[22:23]
	v_lshl_add_u64 v[22:23], v[22:23], 0, v[0:1]
	global_load_dwordx4 v[22:25], v[22:23], off
	s_waitcnt vmcnt(0)
	v_mov_b32_e32 v26, v23
	v_mov_b32_e32 v27, v24
	v_mov_b32_e32 v23, v25
	v_pk_add_f32 v[22:23], v[26:27], v[22:23]
	s_nop 0
	v_add_f32_e32 v0, v22, v23
	v_mov_b32_e32 v22, v0
	s_nop 1
	v_permlane16_swap_b32_e32 v0, v22
	s_waitcnt lgkmcnt(0)
	v_add_f32_e32 v0, v0, v22
	v_mov_b32_e32 v22, v0
	s_nop 1
	v_permlane32_swap_b32_e32 v0, v22
	s_waitcnt lgkmcnt(0)
	v_add_f32_e32 v0, v0, v22
	v_fmamk_f32 v0, v0, 0x3a800000, v249
	v_mul_f32_e32 v22, 0x4b800000, v0
	v_cmp_gt_f32_e64 s[42:43], s53, v0
	s_nop 1
	v_cndmask_b32_e64 v0, v0, v22, s[42:43]
	v_rsq_f32_e32 v0, v0
	s_nop 0
	v_mul_f32_e32 v22, 0x45800000, v0
	v_cndmask_b32_e64 v0, v0, v22, s[42:43]
	v_mul_f32_e32 v0, 0x3db8aa3b, v0
	v_pk_mul_f32 v[200:201], v[16:17], v[0:1] op_sel_hi:[1,0]
	v_pk_mul_f32 v[12:13], v[12:13], v[0:1] op_sel_hi:[1,0]
	v_pk_mul_f32 v[204:205], v[14:15], v[0:1] op_sel_hi:[1,0]
	v_pk_mul_f32 v[14:15], v[10:11], v[0:1] op_sel_hi:[1,0]
	v_pk_mul_f32 v[10:11], v[8:9], v[0:1] op_sel_hi:[1,0]
	v_pk_mul_f32 v[188:189], v[6:7], v[0:1] op_sel_hi:[1,0]
	v_pk_mul_f32 v[16:17], v[4:5], v[0:1] op_sel_hi:[1,0]
	v_pk_mul_f32 v[178:179], v[2:3], v[0:1] op_sel_hi:[1,0]
	v_max_f32_e32 v0, v200, v201
	v_max_f32_e32 v2, v12, v13
	v_max_f32_e32 v3, v10, v11
	v_max_f32_e32 v4, v16, v17
	v_max3_f32 v0, v204, v205, v0
	v_max3_f32 v2, v14, v15, v2
	v_max3_f32 v3, v188, v189, v3
	v_max3_f32 v0, v0, s11, v2
	v_max3_f32 v2, v178, v179, v4
	v_max3_f32 v0, v0, v3, v2
	v_mov_b32_e32 v2, v0
	s_nop 1
	v_permlane16_swap_b32_e32 v0, v2
	s_waitcnt lgkmcnt(0)
	v_max_f32_e32 v2, v2, v2
	v_max_f32_e32 v0, v0, v2
	v_mov_b32_e32 v2, v0
	s_nop 1
	v_permlane32_swap_b32_e32 v0, v2
	s_and_saveexec_b64 s[16:17], vcc
	s_cbranch_execz .LBB0_530
	s_waitcnt lgkmcnt(0)
	v_max_f32_e32 v2, v2, v2
	v_max_f32_e32 v0, v0, v0
	v_lshl_add_u32 v3, v229, 4, s5
	v_max_f32_e32 v0, v0, v2
	ds_write_b32 v3, v0
.LBB0_530:
	s_or_b64 exec, exec, s[16:17]
	s_waitcnt lgkmcnt(0)
	s_barrier
	v_lshl_add_u32 v0, v228, 4, 0
	s_waitcnt lgkmcnt(0)
	ds_read_b128 v[2:5], v0
	s_waitcnt lgkmcnt(0)
	v_max_f32_e32 v5, v5, v5
	v_max_f32_e32 v4, v4, v4
	v_max_f32_e32 v4, v4, v5
	v_max3_f32 v2, v2, v3, v4
	v_sub_f32_e32 v3, v132, v2
	v_exp_f32_e32 v132, v3
	v_sub_f32_e32 v3, v133, v2
	v_exp_f32_e32 v133, v3
	v_sub_f32_e32 v3, v128, v2
	v_exp_f32_e32 v156, v3
	v_sub_f32_e32 v3, v129, v2
	v_exp_f32_e32 v157, v3
	v_sub_f32_e32 v4, v126, v2
	v_add_f32_e32 v3, 0, v132
	v_exp_f32_e32 v160, v4
	v_sub_f32_e32 v4, v127, v2
	v_add_f32_e32 v3, v133, v3
	v_exp_f32_e32 v161, v4
	v_sub_f32_e32 v4, v124, v2
	v_add_f32_e32 v3, v156, v3
	v_exp_f32_e32 v172, v4
	v_sub_f32_e32 v4, v125, v2
	v_add_f32_e32 v3, v157, v3
	v_exp_f32_e32 v173, v4
	v_sub_f32_e32 v4, v122, v2
	v_add_f32_e32 v3, v160, v3
	v_exp_f32_e32 v174, v4
	v_sub_f32_e32 v4, v123, v2
	v_add_f32_e32 v3, v161, v3
	v_exp_f32_e32 v175, v4
	v_sub_f32_e32 v4, v120, v2
	v_add_f32_e32 v3, v172, v3
	v_exp_f32_e32 v180, v4
	v_sub_f32_e32 v4, v121, v2
	v_add_f32_e32 v3, v173, v3
	v_exp_f32_e32 v181, v4
	v_sub_f32_e32 v4, v118, v2
	v_add_f32_e32 v3, v174, v3
	v_exp_f32_e32 v196, v4
	v_sub_f32_e32 v4, v119, v2
	v_add_f32_e32 v3, v175, v3
	v_exp_f32_e32 v197, v4
	v_sub_f32_e32 v4, v116, v2
	v_add_f32_e32 v3, v180, v3
	v_exp_f32_e32 v202, v4
	v_sub_f32_e32 v2, v117, v2
	v_add_f32_e32 v3, v181, v3
	v_exp_f32_e32 v203, v2
	v_add_f32_e32 v2, v196, v3
	v_add_f32_e32 v2, v197, v2
	v_add_f32_e32 v2, v202, v2
	v_add_f32_e32 v2, v203, v2
	v_mov_b32_e32 v3, v2
	s_nop 1
	v_permlane16_swap_b32_e32 v2, v3
	v_lshlrev_b32_e32 v4, 2, v228
	v_lshl_add_u32 v228, v4, 2, s5
	s_waitcnt lgkmcnt(0)
	v_add_f32_e32 v2, v2, v3
	v_mov_b32_e32 v3, v2
	s_nop 1
	v_permlane32_swap_b32_e32 v2, v3
	s_and_saveexec_b64 s[16:17], vcc
	s_cbranch_execz .LBB0_532
	s_waitcnt lgkmcnt(0)
	v_add_f32_e32 v2, v2, v3
	ds_write_b32 v228, v2 offset:4096
.LBB0_532:
	s_or_b64 exec, exec, s[16:17]
	s_waitcnt lgkmcnt(0)
	ds_read_b128 v[2:5], v0 offset:256
	s_waitcnt lgkmcnt(0)
	v_max_f32_e32 v5, v5, v5
	v_max_f32_e32 v4, v4, v4
	v_max_f32_e32 v4, v4, v5
	v_max3_f32 v2, v2, v3, v4
	v_sub_f32_e32 v3, v138, v2
	v_sub_f32_e32 v4, v139, v2
	v_exp_f32_e32 v94, v3
	v_sub_f32_e32 v5, v136, v2
	v_exp_f32_e32 v95, v4
	v_sub_f32_e32 v6, v137, v2
	v_exp_f32_e32 v102, v5
	v_exp_f32_e32 v103, v6
	v_sub_f32_e32 v4, v134, v2
	v_add_f32_e32 v3, 0, v94
	v_exp_f32_e32 v100, v4
	v_sub_f32_e32 v4, v135, v2
	v_add_f32_e32 v3, v95, v3
	v_exp_f32_e32 v101, v4
	v_sub_f32_e32 v4, v108, v2
	v_add_f32_e32 v3, v102, v3
	v_exp_f32_e32 v108, v4
	v_sub_f32_e32 v4, v109, v2
	v_add_f32_e32 v3, v103, v3
	v_exp_f32_e32 v109, v4
	v_sub_f32_e32 v4, v106, v2
	v_add_f32_e32 v3, v100, v3
	v_exp_f32_e32 v96, v4
	v_sub_f32_e32 v4, v107, v2
	v_add_f32_e32 v3, v101, v3
	v_exp_f32_e32 v97, v4
	v_sub_f32_e32 v4, v104, v2
	v_add_f32_e32 v3, v108, v3
	v_exp_f32_e32 v106, v4
	v_sub_f32_e32 v4, v105, v2
	v_add_f32_e32 v3, v109, v3
	v_exp_f32_e32 v107, v4
	v_sub_f32_e32 v4, v112, v2
	v_add_f32_e32 v3, v96, v3
	v_exp_f32_e32 v104, v4
	v_sub_f32_e32 v4, v113, v2
	v_add_f32_e32 v3, v97, v3
	v_exp_f32_e32 v105, v4
	v_sub_f32_e32 v4, v110, v2
	v_add_f32_e32 v3, v106, v3
	v_exp_f32_e32 v110, v4
	v_sub_f32_e32 v2, v111, v2
	v_add_f32_e32 v3, v107, v3
	v_exp_f32_e32 v111, v2
	v_add_f32_e32 v2, v104, v3
	v_add_f32_e32 v2, v105, v2
	v_add_f32_e32 v2, v110, v2
	v_add_f32_e32 v2, v111, v2
	v_mov_b32_e32 v3, v2
	s_nop 1
	v_permlane16_swap_b32_e32 v2, v3
	s_waitcnt lgkmcnt(0)
	v_add_f32_e32 v2, v2, v3
	v_mov_b32_e32 v3, v2
	s_nop 1
	v_permlane32_swap_b32_e32 v2, v3
	s_and_saveexec_b64 s[16:17], vcc
	s_cbranch_execz .LBB0_534
	s_waitcnt lgkmcnt(0)
	v_add_f32_e32 v2, v2, v3
	ds_write_b32 v228, v2 offset:4352
.LBB0_534:
	s_or_b64 exec, exec, s[16:17]
	s_waitcnt lgkmcnt(0)
	ds_read_b128 v[2:5], v0 offset:512
	s_waitcnt lgkmcnt(0)
	v_max_f32_e32 v5, v5, v5
	v_max_f32_e32 v4, v4, v4
	v_max_f32_e32 v4, v4, v5
	v_max3_f32 v2, v2, v3, v4
	v_sub_f32_e32 v3, v144, v2
	v_sub_f32_e32 v4, v145, v2
	v_exp_f32_e32 v112, v3
	v_sub_f32_e32 v5, v142, v2
	v_exp_f32_e32 v113, v4
	v_sub_f32_e32 v6, v143, v2
	v_exp_f32_e32 v116, v5
	v_exp_f32_e32 v117, v6
	v_sub_f32_e32 v4, v140, v2
	v_add_f32_e32 v3, 0, v112
	v_exp_f32_e32 v118, v4
	v_sub_f32_e32 v4, v141, v2
	v_add_f32_e32 v3, v113, v3
	v_exp_f32_e32 v119, v4
	v_sub_f32_e32 v4, v92, v2
	v_add_f32_e32 v3, v116, v3
	v_exp_f32_e32 v120, v4
	v_sub_f32_e32 v4, v93, v2
	v_add_f32_e32 v3, v117, v3
	v_exp_f32_e32 v121, v4
	v_sub_f32_e32 v4, v90, v2
	v_add_f32_e32 v3, v118, v3
	v_exp_f32_e32 v122, v4
	v_sub_f32_e32 v4, v91, v2
	v_add_f32_e32 v3, v119, v3
	v_exp_f32_e32 v123, v4
	v_sub_f32_e32 v4, v88, v2
	v_add_f32_e32 v3, v120, v3
	v_exp_f32_e32 v124, v4
	v_sub_f32_e32 v4, v89, v2
	v_add_f32_e32 v3, v121, v3
	v_exp_f32_e32 v125, v4
	v_sub_f32_e32 v4, v86, v2
	v_add_f32_e32 v3, v122, v3
	v_exp_f32_e32 v126, v4
	v_sub_f32_e32 v4, v87, v2
	v_add_f32_e32 v3, v123, v3
	v_exp_f32_e32 v127, v4
	v_sub_f32_e32 v4, v84, v2
	v_add_f32_e32 v3, v124, v3
	v_exp_f32_e32 v128, v4
	v_sub_f32_e32 v2, v85, v2
	v_add_f32_e32 v3, v125, v3
	v_exp_f32_e32 v129, v2
	v_add_f32_e32 v2, v126, v3
	v_add_f32_e32 v2, v127, v2
	v_add_f32_e32 v2, v128, v2
	v_add_f32_e32 v2, v129, v2
	v_mov_b32_e32 v3, v2
	s_nop 1
	v_permlane16_swap_b32_e32 v2, v3
	s_waitcnt lgkmcnt(0)
	v_add_f32_e32 v2, v2, v3
	v_mov_b32_e32 v3, v2
	s_nop 1
	v_permlane32_swap_b32_e32 v2, v3
	s_and_saveexec_b64 s[16:17], vcc
	s_cbranch_execz .LBB0_536
	s_waitcnt lgkmcnt(0)
	v_add_f32_e32 v2, v2, v3
	ds_write_b32 v228, v2 offset:4608
.LBB0_536:
	s_or_b64 exec, exec, s[16:17]
	s_waitcnt lgkmcnt(0)
	ds_read_b128 v[2:5], v0 offset:768
	s_waitcnt lgkmcnt(0)
	v_max_f32_e32 v5, v5, v5
	v_max_f32_e32 v4, v4, v4
	v_max_f32_e32 v4, v4, v5
	v_max3_f32 v2, v2, v3, v4
	v_sub_f32_e32 v3, v152, v2
	v_sub_f32_e32 v4, v153, v2
	v_exp_f32_e32 v58, v3
	v_sub_f32_e32 v5, v146, v2
	v_exp_f32_e32 v59, v4
	v_sub_f32_e32 v6, v147, v2
	v_exp_f32_e32 v64, v5
	v_exp_f32_e32 v65, v6
	v_sub_f32_e32 v4, v80, v2
	v_add_f32_e32 v3, 0, v58
	v_exp_f32_e32 v62, v4
	v_sub_f32_e32 v4, v81, v2
	v_add_f32_e32 v3, v59, v3
	v_exp_f32_e32 v63, v4
	v_sub_f32_e32 v4, v78, v2
	v_add_f32_e32 v3, v64, v3
	v_exp_f32_e32 v72, v4
	v_sub_f32_e32 v4, v79, v2
	v_add_f32_e32 v3, v65, v3
	v_exp_f32_e32 v73, v4
	v_sub_f32_e32 v4, v70, v2
	v_add_f32_e32 v3, v62, v3
	v_exp_f32_e32 v60, v4
	v_sub_f32_e32 v4, v71, v2
	v_add_f32_e32 v3, v63, v3
	v_exp_f32_e32 v61, v4
	v_sub_f32_e32 v4, v76, v2
	v_add_f32_e32 v3, v72, v3
	v_exp_f32_e32 v70, v4
	v_sub_f32_e32 v4, v77, v2
	v_add_f32_e32 v3, v73, v3
	v_exp_f32_e32 v71, v4
	v_sub_f32_e32 v4, v68, v2
	v_add_f32_e32 v3, v60, v3
	v_exp_f32_e32 v68, v4
	v_sub_f32_e32 v4, v69, v2
	v_add_f32_e32 v3, v61, v3
	v_exp_f32_e32 v69, v4
	v_sub_f32_e32 v4, v74, v2
	v_add_f32_e32 v3, v70, v3
	v_exp_f32_e32 v74, v4
	v_sub_f32_e32 v2, v75, v2
	v_add_f32_e32 v3, v71, v3
	v_exp_f32_e32 v75, v2
	v_add_f32_e32 v2, v68, v3
	v_add_f32_e32 v2, v69, v2
	v_add_f32_e32 v2, v74, v2
	v_add_f32_e32 v2, v75, v2
	v_mov_b32_e32 v3, v2
	s_nop 1
	v_permlane16_swap_b32_e32 v2, v3
	s_waitcnt lgkmcnt(0)
	v_add_f32_e32 v2, v2, v3
	v_mov_b32_e32 v3, v2
	s_nop 1
	v_permlane32_swap_b32_e32 v2, v3
	s_and_saveexec_b64 s[16:17], vcc
	s_cbranch_execz .LBB0_538
	s_waitcnt lgkmcnt(0)
	v_add_f32_e32 v2, v2, v3
	ds_write_b32 v228, v2 offset:4864
.LBB0_538:
	s_or_b64 exec, exec, s[16:17]
	s_waitcnt lgkmcnt(0)
	ds_read_b128 v[2:5], v0 offset:2048
	s_waitcnt lgkmcnt(0)
	v_max_f32_e32 v5, v5, v5
	v_max_f32_e32 v4, v4, v4
	v_max_f32_e32 v4, v4, v5
	v_max3_f32 v2, v2, v3, v4
	v_sub_f32_e32 v3, v166, v2
	v_sub_f32_e32 v4, v167, v2
	v_exp_f32_e32 v76, v3
	v_sub_f32_e32 v5, v158, v2
	v_exp_f32_e32 v77, v4
	v_sub_f32_e32 v6, v159, v2
	v_exp_f32_e32 v78, v5
	v_exp_f32_e32 v79, v6
	v_sub_f32_e32 v4, v154, v2
	v_add_f32_e32 v3, 0, v76
	v_exp_f32_e32 v80, v4
	v_sub_f32_e32 v4, v155, v2
	v_add_f32_e32 v3, v77, v3
	v_exp_f32_e32 v81, v4
	v_sub_f32_e32 v4, v148, v2
	v_add_f32_e32 v3, v78, v3
	v_exp_f32_e32 v84, v4
	v_sub_f32_e32 v4, v149, v2
	v_add_f32_e32 v3, v79, v3
	v_exp_f32_e32 v85, v4
	v_sub_f32_e32 v4, v150, v2
	v_add_f32_e32 v3, v80, v3
	v_exp_f32_e32 v86, v4
	v_sub_f32_e32 v4, v151, v2
	v_add_f32_e32 v3, v81, v3
	v_exp_f32_e32 v87, v4
	v_sub_f32_e32 v4, v56, v2
	v_add_f32_e32 v3, v84, v3
	v_exp_f32_e32 v88, v4
	v_sub_f32_e32 v4, v57, v2
	v_add_f32_e32 v3, v85, v3
	v_exp_f32_e32 v89, v4
	v_sub_f32_e32 v4, v54, v2
	v_add_f32_e32 v3, v86, v3
	v_exp_f32_e32 v90, v4
	v_sub_f32_e32 v4, v55, v2
	v_add_f32_e32 v3, v87, v3
	v_exp_f32_e32 v91, v4
	v_sub_f32_e32 v4, v52, v2
	v_add_f32_e32 v3, v88, v3
	v_exp_f32_e32 v92, v4
	v_sub_f32_e32 v2, v53, v2
	v_add_f32_e32 v3, v89, v3
	v_exp_f32_e32 v93, v2
	v_add_f32_e32 v2, v90, v3
	v_add_f32_e32 v2, v91, v2
	v_add_f32_e32 v2, v92, v2
	v_add_f32_e32 v2, v93, v2
	v_mov_b32_e32 v3, v2
	s_nop 1
	v_permlane16_swap_b32_e32 v2, v3
	s_waitcnt lgkmcnt(0)
	v_add_f32_e32 v2, v2, v3
	v_mov_b32_e32 v3, v2
	s_nop 1
	v_permlane32_swap_b32_e32 v2, v3
	s_and_saveexec_b64 s[16:17], vcc
	s_cbranch_execz .LBB0_540
	s_waitcnt lgkmcnt(0)
	v_add_f32_e32 v2, v2, v3
	ds_write_b32 v228, v2 offset:6144
.LBB0_540:
	s_or_b64 exec, exec, s[16:17]
	s_waitcnt lgkmcnt(0)
	ds_read_b128 v[2:5], v0 offset:2304
	s_waitcnt lgkmcnt(0)
	v_max_f32_e32 v5, v5, v5
	v_max_f32_e32 v4, v4, v4
	v_max_f32_e32 v4, v4, v5
	v_max3_f32 v2, v2, v3, v4
	v_sub_f32_e32 v3, v182, v2
	v_sub_f32_e32 v4, v183, v2
	v_exp_f32_e32 v22, v3
	v_sub_f32_e32 v5, v168, v2
	v_exp_f32_e32 v23, v4
	v_sub_f32_e32 v6, v169, v2
	v_exp_f32_e32 v28, v5
	v_exp_f32_e32 v29, v6
	v_sub_f32_e32 v4, v48, v2
	v_add_f32_e32 v3, 0, v22
	v_exp_f32_e32 v26, v4
	v_sub_f32_e32 v4, v49, v2
	v_add_f32_e32 v3, v23, v3
	v_exp_f32_e32 v27, v4
	v_sub_f32_e32 v4, v44, v2
	v_add_f32_e32 v3, v28, v3
	v_exp_f32_e32 v36, v4
	v_sub_f32_e32 v4, v45, v2
	v_add_f32_e32 v3, v29, v3
	v_exp_f32_e32 v37, v4
	v_sub_f32_e32 v4, v46, v2
	v_add_f32_e32 v3, v26, v3
	v_exp_f32_e32 v24, v4
	v_sub_f32_e32 v4, v47, v2
	v_add_f32_e32 v3, v27, v3
	v_exp_f32_e32 v25, v4
	v_sub_f32_e32 v4, v40, v2
	v_add_f32_e32 v3, v36, v3
	v_exp_f32_e32 v32, v4
	v_sub_f32_e32 v4, v41, v2
	v_add_f32_e32 v3, v37, v3
	v_exp_f32_e32 v33, v4
	v_sub_f32_e32 v4, v42, v2
	v_add_f32_e32 v3, v24, v3
	v_exp_f32_e32 v30, v4
	v_sub_f32_e32 v4, v43, v2
	v_add_f32_e32 v3, v25, v3
	v_exp_f32_e32 v31, v4
	v_sub_f32_e32 v4, v38, v2
	v_add_f32_e32 v3, v32, v3
	v_exp_f32_e32 v38, v4
	v_sub_f32_e32 v2, v39, v2
	v_add_f32_e32 v3, v33, v3
	v_exp_f32_e32 v39, v2
	v_add_f32_e32 v2, v30, v3
	v_add_f32_e32 v2, v31, v2
	v_add_f32_e32 v2, v38, v2
	v_add_f32_e32 v2, v39, v2
	v_mov_b32_e32 v3, v2
	s_nop 1
	v_permlane16_swap_b32_e32 v2, v3
	s_waitcnt lgkmcnt(0)
	v_add_f32_e32 v2, v2, v3
	v_mov_b32_e32 v3, v2
	s_nop 1
	v_permlane32_swap_b32_e32 v2, v3
	s_and_saveexec_b64 s[16:17], vcc
	s_cbranch_execz .LBB0_542
	s_waitcnt lgkmcnt(0)
	v_add_f32_e32 v2, v2, v3
	ds_write_b32 v228, v2 offset:6400
.LBB0_542:
	s_or_b64 exec, exec, s[16:17]
	s_waitcnt lgkmcnt(0)
	ds_read_b128 v[2:5], v0 offset:2560
	s_waitcnt lgkmcnt(0)
	v_max_f32_e32 v5, v5, v5
	v_max_f32_e32 v4, v4, v4
	v_max_f32_e32 v4, v4, v5
	v_max3_f32 v2, v2, v3, v4
	v_sub_f32_e32 v3, v198, v2
	v_sub_f32_e32 v4, v199, v2
	v_exp_f32_e32 v40, v3
	v_sub_f32_e32 v5, v186, v2
	v_exp_f32_e32 v41, v4
	v_sub_f32_e32 v6, v187, v2
	v_exp_f32_e32 v42, v5
	v_exp_f32_e32 v43, v6
	v_sub_f32_e32 v4, v184, v2
	v_add_f32_e32 v3, 0, v40
	v_exp_f32_e32 v44, v4
	v_sub_f32_e32 v4, v185, v2
	v_add_f32_e32 v3, v41, v3
	v_exp_f32_e32 v45, v4
	v_sub_f32_e32 v4, v170, v2
	v_add_f32_e32 v3, v42, v3
	v_exp_f32_e32 v46, v4
	v_sub_f32_e32 v4, v171, v2
	v_add_f32_e32 v3, v43, v3
	v_exp_f32_e32 v47, v4
	v_sub_f32_e32 v4, v176, v2
	v_add_f32_e32 v3, v44, v3
	v_exp_f32_e32 v48, v4
	v_sub_f32_e32 v4, v177, v2
	v_add_f32_e32 v3, v45, v3
	v_exp_f32_e32 v49, v4
	v_sub_f32_e32 v4, v162, v2
	v_add_f32_e32 v3, v46, v3
	v_exp_f32_e32 v52, v4
	v_sub_f32_e32 v4, v163, v2
	v_add_f32_e32 v3, v47, v3
	v_exp_f32_e32 v53, v4
	v_sub_f32_e32 v4, v164, v2
	v_add_f32_e32 v3, v48, v3
	v_exp_f32_e32 v54, v4
	v_sub_f32_e32 v4, v165, v2
	v_add_f32_e32 v3, v49, v3
	v_exp_f32_e32 v55, v4
	v_sub_f32_e32 v4, v20, v2
	v_add_f32_e32 v3, v52, v3
	v_exp_f32_e32 v56, v4
	v_sub_f32_e32 v2, v21, v2
	v_add_f32_e32 v3, v53, v3
	v_exp_f32_e32 v57, v2
	v_add_f32_e32 v2, v54, v3
	v_add_f32_e32 v2, v55, v2
	v_add_f32_e32 v2, v56, v2
	v_add_f32_e32 v2, v57, v2
	v_mov_b32_e32 v3, v2
	s_nop 1
	v_permlane16_swap_b32_e32 v2, v3
	s_waitcnt lgkmcnt(0)
	v_add_f32_e32 v2, v2, v3
	v_mov_b32_e32 v3, v2
	s_nop 1
	v_permlane32_swap_b32_e32 v2, v3
	s_and_saveexec_b64 s[16:17], vcc
	s_cbranch_execz .LBB0_544
	s_waitcnt lgkmcnt(0)
	v_add_f32_e32 v2, v2, v3
	ds_write_b32 v228, v2 offset:6656
.LBB0_544:
	s_or_b64 exec, exec, s[16:17]
	s_waitcnt lgkmcnt(0)
	ds_read_b128 v[2:5], v0 offset:2816
	s_waitcnt lgkmcnt(0)
	v_max_f32_e32 v5, v5, v5
	v_max_f32_e32 v4, v4, v4
	v_max_f32_e32 v4, v4, v5
	v_max3_f32 v20, v2, v3, v4
	v_sub_f32_e32 v2, v204, v20
	v_sub_f32_e32 v3, v205, v20
	v_exp_f32_e32 v2, v2
	v_sub_f32_e32 v4, v200, v20
	v_exp_f32_e32 v3, v3
	v_sub_f32_e32 v5, v201, v20
	v_exp_f32_e32 v8, v4
	v_exp_f32_e32 v9, v5
	v_sub_f32_e32 v5, v14, v20
	v_add_f32_e32 v4, 0, v2
	v_exp_f32_e32 v6, v5
	v_sub_f32_e32 v5, v15, v20
	v_add_f32_e32 v4, v3, v4
	v_exp_f32_e32 v7, v5
	v_sub_f32_e32 v5, v12, v20
	v_add_f32_e32 v4, v8, v4
	v_exp_f32_e32 v14, v5
	v_sub_f32_e32 v5, v13, v20
	v_add_f32_e32 v4, v9, v4
	v_exp_f32_e32 v15, v5
	v_add_f32_e32 v4, v6, v4
	v_add_f32_e32 v4, v7, v4
	v_add_f32_e32 v4, v14, v4
	v_add_f32_e32 v21, v15, v4
	v_sub_f32_e32 v4, v188, v20
	v_exp_f32_e32 v4, v4
	v_sub_f32_e32 v5, v189, v20
	v_exp_f32_e32 v5, v5
	v_sub_f32_e32 v10, v10, v20
	v_exp_f32_e32 v12, v10
	v_sub_f32_e32 v10, v11, v20
	v_exp_f32_e32 v13, v10
	v_add_f32_e32 v10, v4, v21
	v_add_f32_e32 v10, v5, v10
	v_add_f32_e32 v10, v12, v10
	v_add_f32_e32 v21, v13, v10
	v_sub_f32_e32 v10, v178, v20
	v_exp_f32_e32 v10, v10
	v_sub_f32_e32 v11, v179, v20
	v_exp_f32_e32 v11, v11
	v_sub_f32_e32 v16, v16, v20
	v_exp_f32_e32 v16, v16
	v_sub_f32_e32 v17, v17, v20
	v_exp_f32_e32 v17, v17
	v_add_f32_e32 v20, v10, v21
	v_add_f32_e32 v20, v11, v20
	v_add_f32_e32 v20, v16, v20
	v_add_f32_e32 v20, v17, v20
	v_mov_b32_e32 v21, v20
	s_nop 1
	v_permlane16_swap_b32_e32 v20, v21
	s_waitcnt lgkmcnt(0)
	v_add_f32_e32 v20, v20, v21
	v_mov_b32_e32 v21, v20
	s_nop 1
	v_permlane32_swap_b32_e32 v20, v21
	s_and_saveexec_b64 s[16:17], vcc
	s_cbranch_execz .LBB0_546
	s_waitcnt lgkmcnt(0)
	v_add_f32_e32 v20, v20, v21
	ds_write_b32 v228, v20 offset:6912
